# LayerNorm rows rebalanced: waves 0-3 take 3 prompt rows + the sample row, waves 4-7 take 5 prompt rows
# baseline (speedup 1.0000x reference)
.LBB0_1083:
	s_or_b64 exec, exec, s[2:3]
	v_readlane_b32 s2, v241, 9
	v_readlane_b32 s3, v241, 10
	v_readlane_b32 s3, v241, 0
	s_waitcnt lgkmcnt(0)
	s_barrier
	v_mov_b32_e32 v0, v178
	v_readlane_b32 s2, v239, 2
	v_ashrrev_i32_e32 v1, 6, v0
	s_nop 0
	v_add_u32_e32 v32, s2, v1
	s_movk_i32 s2, 0x2400
	v_cmp_gt_i32_e32 vcc, s2, v32
	s_and_saveexec_b64 s[2:3], vcc
	s_cbranch_execz .LBB0_1118
	v_readlane_b32 s30, v241, 9
	s_cmpk_lg_i32 s30, 0x100
	s_cbranch_scc1 .Lln1_old
	v_readlane_b32 s38, v241, 0
	v_readlane_b32 s12, v239, 42
	v_readlane_b32 s13, v239, 43
	v_readlane_b32 s30, v239, 37
	s_add_u32 s4, s12, 0xc700000
	s_addc_u32 s5, s13, 0
	s_add_u32 s6, s12, 0x1d080000
	s_addc_u32 s7, s13, 0
	s_add_u32 s8, s12, 0x33ac0000
	s_addc_u32 s9, s13, 0
	s_lshl_b32 s30, s30, 13
	v_readlane_b32 s40, v241, 33
	v_readlane_b32 s41, v241, 34
	v_readlane_b32 s42, v241, 35
	v_readlane_b32 s43, v241, 36
	s_add_u32 s40, s40, s30
	s_addc_u32 s41, s41, 0
	s_add_u32 s42, s42, s30
	s_addc_u32 s43, s43, 0
	v_lshlrev_b32_e32 v252, 4, v178
	global_load_dwordx4 v[0:3], v252, s[40:41]
	global_load_dwordx4 v[4:7], v252, s[42:43]
	v_lshrrev_b32_e32 v253, 7, v178
	v_lshlrev_b32_e32 v253, 11, v253
	v_and_b32_e32 v254, 1, v178
	v_lshl_or_b32 v253, v254, 10, v253
	v_bfe_u32 v254, v178, 1, 6
	v_lshl_or_b32 v253, v254, 3, v253
	v_readfirstlane_b32 s36, v178
	v_and_b32_e32 v168, 63, v178
	s_lshr_b32 s36, s36, 6
	s_lshl_b32 s30, s38, 3
	s_add_i32 s30, s30, s36
	s_lshl_b32 s30, s30, 12
	v_lshl_add_u32 v90, v168, 4, s30
	v_lshlrev_b32_e32 v168, 3, v168
	s_waitcnt vmcnt(0)
	ds_write_b64 v253, v[0:1]
	ds_write_b64 v253, v[2:3] offset:512
	ds_write_b64 v253, v[4:5] offset:8192
	ds_write_b64 v253, v[6:7] offset:8704
	s_waitcnt lgkmcnt(0)
	s_barrier
	s_cmp_lt_u32 s36, 4
	s_cbranch_scc0 .Lln1_hi_1
	global_load_dwordx4 v[0:3], v90, s[4:5]
	global_load_dwordx4 v[4:7], v90, s[4:5] offset:1024
	global_load_dwordx4 v[8:11], v90, s[4:5] offset:2048
	global_load_dwordx4 v[12:15], v90, s[4:5] offset:3072
	global_load_dwordx4 v[16:19], v90, s[6:7]
	global_load_dwordx4 v[20:23], v90, s[6:7] offset:1024
	global_load_dwordx4 v[24:27], v90, s[6:7] offset:2048
	global_load_dwordx4 v[28:31], v90, s[6:7] offset:3072
	s_add_u32 s12, s4, 0x800000
	s_addc_u32 s13, s5, 0
	global_load_dwordx4 v[32:35], v90, s[12:13]
	global_load_dwordx4 v[36:39], v90, s[12:13] offset:1024
	global_load_dwordx4 v[40:43], v90, s[12:13] offset:2048
	global_load_dwordx4 v[44:47], v90, s[12:13] offset:3072
	s_add_u32 s12, s6, 0x800000
	s_addc_u32 s13, s7, 0
	global_load_dwordx4 v[48:51], v90, s[12:13]
	global_load_dwordx4 v[52:55], v90, s[12:13] offset:1024
	global_load_dwordx4 v[56:59], v90, s[12:13] offset:2048
	global_load_dwordx4 v[60:63], v90, s[12:13] offset:3072
	s_waitcnt vmcnt(8)
	v_lshlrev_b32_e32 v64, 16, v16
	v_and_b32_e32 v65, 0xffff0000, v16
	v_and_b32_e32 v252, 0xffff0000, v0
	v_lshlrev_b32_e32 v0, 16, v0
	v_fmac_f32_e32 v64, 0x3fb504f3, v0
	v_fmac_f32_e32 v65, 0x3fb504f3, v252
	v_lshlrev_b32_e32 v66, 16, v17
	v_and_b32_e32 v67, 0xffff0000, v17
	v_and_b32_e32 v252, 0xffff0000, v1
	v_lshlrev_b32_e32 v1, 16, v1
	v_fmac_f32_e32 v66, 0x3fb504f3, v1
	v_fmac_f32_e32 v67, 0x3fb504f3, v252
	v_add_f32_e32 v252, v64, v65
	v_add_f32_e32 v253, v66, v67
	v_add_f32_e32 v254, v252, v253
	v_lshlrev_b32_e32 v68, 16, v18
	v_and_b32_e32 v69, 0xffff0000, v18
	v_and_b32_e32 v252, 0xffff0000, v2
	v_lshlrev_b32_e32 v2, 16, v2
	v_fmac_f32_e32 v68, 0x3fb504f3, v2
	v_fmac_f32_e32 v69, 0x3fb504f3, v252
	v_lshlrev_b32_e32 v70, 16, v19
	v_and_b32_e32 v71, 0xffff0000, v19
	v_and_b32_e32 v252, 0xffff0000, v3
	v_lshlrev_b32_e32 v3, 16, v3
	v_fmac_f32_e32 v70, 0x3fb504f3, v3
	v_fmac_f32_e32 v71, 0x3fb504f3, v252
	v_add_f32_e32 v252, v68, v69
	v_add_f32_e32 v253, v70, v71
	v_add_f32_e32 v252, v252, v253
	v_add_f32_e32 v254, v254, v252
	v_lshlrev_b32_e32 v72, 16, v20
	v_and_b32_e32 v73, 0xffff0000, v20
	v_and_b32_e32 v252, 0xffff0000, v4
	v_lshlrev_b32_e32 v4, 16, v4
	v_fmac_f32_e32 v72, 0x3fb504f3, v4
	v_fmac_f32_e32 v73, 0x3fb504f3, v252
	v_lshlrev_b32_e32 v74, 16, v21
	v_and_b32_e32 v75, 0xffff0000, v21
	v_and_b32_e32 v252, 0xffff0000, v5
	v_lshlrev_b32_e32 v5, 16, v5
	v_fmac_f32_e32 v74, 0x3fb504f3, v5
	v_fmac_f32_e32 v75, 0x3fb504f3, v252
	v_add_f32_e32 v252, v72, v73
	v_add_f32_e32 v253, v74, v75
	v_add_f32_e32 v252, v252, v253
	v_add_f32_e32 v254, v254, v252
	v_lshlrev_b32_e32 v76, 16, v22
	v_and_b32_e32 v77, 0xffff0000, v22
	v_and_b32_e32 v252, 0xffff0000, v6
	v_lshlrev_b32_e32 v6, 16, v6
	v_fmac_f32_e32 v76, 0x3fb504f3, v6
	v_fmac_f32_e32 v77, 0x3fb504f3, v252
	v_lshlrev_b32_e32 v78, 16, v23
	v_and_b32_e32 v79, 0xffff0000, v23
	v_and_b32_e32 v252, 0xffff0000, v7
	v_lshlrev_b32_e32 v7, 16, v7
	v_fmac_f32_e32 v78, 0x3fb504f3, v7
	v_fmac_f32_e32 v79, 0x3fb504f3, v252
	v_add_f32_e32 v252, v76, v77
	v_add_f32_e32 v253, v78, v79
	v_add_f32_e32 v252, v252, v253
	v_add_f32_e32 v254, v254, v252
	v_lshlrev_b32_e32 v80, 16, v24
	v_and_b32_e32 v81, 0xffff0000, v24
	v_and_b32_e32 v252, 0xffff0000, v8
	v_lshlrev_b32_e32 v8, 16, v8
	v_fmac_f32_e32 v80, 0x3fb504f3, v8
	v_fmac_f32_e32 v81, 0x3fb504f3, v252
	v_lshlrev_b32_e32 v82, 16, v25
	v_and_b32_e32 v83, 0xffff0000, v25
	v_and_b32_e32 v252, 0xffff0000, v9
	v_lshlrev_b32_e32 v9, 16, v9
	v_fmac_f32_e32 v82, 0x3fb504f3, v9
	v_fmac_f32_e32 v83, 0x3fb504f3, v252
	v_add_f32_e32 v252, v80, v81
	v_add_f32_e32 v253, v82, v83
	v_add_f32_e32 v252, v252, v253
	v_add_f32_e32 v254, v254, v252
	v_lshlrev_b32_e32 v84, 16, v26
	v_and_b32_e32 v85, 0xffff0000, v26
	v_and_b32_e32 v252, 0xffff0000, v10
	v_lshlrev_b32_e32 v10, 16, v10
	v_fmac_f32_e32 v84, 0x3fb504f3, v10
	v_fmac_f32_e32 v85, 0x3fb504f3, v252
	v_lshlrev_b32_e32 v86, 16, v27
	v_and_b32_e32 v87, 0xffff0000, v27
	v_and_b32_e32 v252, 0xffff0000, v11
	v_lshlrev_b32_e32 v11, 16, v11
	v_fmac_f32_e32 v86, 0x3fb504f3, v11
	v_fmac_f32_e32 v87, 0x3fb504f3, v252
	v_add_f32_e32 v252, v84, v85
	v_add_f32_e32 v253, v86, v87
	v_add_f32_e32 v252, v252, v253
	v_add_f32_e32 v254, v254, v252
	v_lshlrev_b32_e32 v244, 16, v28
	v_and_b32_e32 v245, 0xffff0000, v28
	v_and_b32_e32 v252, 0xffff0000, v12
	v_lshlrev_b32_e32 v12, 16, v12
	v_fmac_f32_e32 v244, 0x3fb504f3, v12
	v_fmac_f32_e32 v245, 0x3fb504f3, v252
	v_lshlrev_b32_e32 v246, 16, v29
	v_and_b32_e32 v247, 0xffff0000, v29
	v_and_b32_e32 v252, 0xffff0000, v13
	v_lshlrev_b32_e32 v13, 16, v13
	v_fmac_f32_e32 v246, 0x3fb504f3, v13
	v_fmac_f32_e32 v247, 0x3fb504f3, v252
	v_add_f32_e32 v252, v244, v245
	v_add_f32_e32 v253, v246, v247
	v_add_f32_e32 v252, v252, v253
	v_add_f32_e32 v254, v254, v252
	v_lshlrev_b32_e32 v248, 16, v30
	v_and_b32_e32 v249, 0xffff0000, v30
	v_and_b32_e32 v252, 0xffff0000, v14
	v_lshlrev_b32_e32 v14, 16, v14
	v_fmac_f32_e32 v248, 0x3fb504f3, v14
	v_fmac_f32_e32 v249, 0x3fb504f3, v252
	v_lshlrev_b32_e32 v250, 16, v31
	v_and_b32_e32 v251, 0xffff0000, v31
	v_and_b32_e32 v252, 0xffff0000, v15
	v_lshlrev_b32_e32 v15, 16, v15
	v_fmac_f32_e32 v250, 0x3fb504f3, v15
	v_fmac_f32_e32 v251, 0x3fb504f3, v252
	v_add_f32_e32 v252, v248, v249
	v_add_f32_e32 v253, v250, v251
	v_add_f32_e32 v252, v252, v253
	v_add_f32_e32 v254, v254, v252
	s_add_u32 s12, s4, 0x1000000
	s_addc_u32 s13, s5, 0
	global_load_dwordx4 v[0:3], v90, s[12:13]
	global_load_dwordx4 v[4:7], v90, s[12:13] offset:1024
	global_load_dwordx4 v[8:11], v90, s[12:13] offset:2048
	global_load_dwordx4 v[12:15], v90, s[12:13] offset:3072
	s_add_u32 s12, s6, 0x1000000
	s_addc_u32 s13, s7, 0
	global_load_dwordx4 v[16:19], v90, s[12:13]
	global_load_dwordx4 v[20:23], v90, s[12:13] offset:1024
	global_load_dwordx4 v[24:27], v90, s[12:13] offset:2048
	global_load_dwordx4 v[28:31], v90, s[12:13] offset:3072
	s_nop 1
	v_add_f32_dpp v252, v254, v254 quad_perm:[1,0,3,2] row_mask:0xf bank_mask:0xf
	s_nop 1
	v_add_f32_dpp v252, v252, v252 quad_perm:[2,3,0,1] row_mask:0xf bank_mask:0xf
	s_nop 1
	v_add_f32_dpp v252, v252, v252 row_half_mirror row_mask:0xf bank_mask:0xf
	s_nop 1
	v_add_f32_dpp v252, v252, v252 row_mirror row_mask:0xf bank_mask:0xf
	s_nop 1
	v_readlane_b32 s40, v252, 0
	v_readlane_b32 s41, v252, 16
	v_readlane_b32 s42, v252, 32
	v_readlane_b32 s43, v252, 48
	s_nop 1
	v_mov_b32_e32 v253, s40
	v_add_f32_e32 v253, s41, v253
	v_add_f32_e32 v253, s42, v253
	v_add_f32_e32 v253, s43, v253
	v_mul_f32_e32 v253, 0x3a000000, v253
	s_nop 0
	v_readfirstlane_b32 s37, v253
	s_nop 1
	v_subrev_f32_e32 v64, s37, v64
	v_subrev_f32_e32 v65, s37, v65
	v_subrev_f32_e32 v66, s37, v66
	v_subrev_f32_e32 v67, s37, v67
	v_subrev_f32_e32 v68, s37, v68
	v_subrev_f32_e32 v69, s37, v69
	v_subrev_f32_e32 v70, s37, v70
	v_subrev_f32_e32 v71, s37, v71
	v_mul_f32_e32 v252, v64, v64
	v_fmac_f32_e32 v252, v65, v65
	v_mul_f32_e32 v253, v66, v66
	v_fmac_f32_e32 v253, v67, v67
	v_add_f32_e32 v254, v252, v253
	v_mul_f32_e32 v252, v68, v68
	v_fmac_f32_e32 v252, v69, v69
	v_mul_f32_e32 v253, v70, v70
	v_fmac_f32_e32 v253, v71, v71
	v_add_f32_e32 v252, v252, v253
	v_add_f32_e32 v254, v254, v252
	v_subrev_f32_e32 v72, s37, v72
	v_subrev_f32_e32 v73, s37, v73
	v_subrev_f32_e32 v74, s37, v74
	v_subrev_f32_e32 v75, s37, v75
	v_subrev_f32_e32 v76, s37, v76
	v_subrev_f32_e32 v77, s37, v77
	v_subrev_f32_e32 v78, s37, v78
	v_subrev_f32_e32 v79, s37, v79
	v_mul_f32_e32 v252, v72, v72
	v_fmac_f32_e32 v252, v73, v73
	v_mul_f32_e32 v253, v74, v74
	v_fmac_f32_e32 v253, v75, v75
	v_add_f32_e32 v252, v252, v253
	v_add_f32_e32 v254, v254, v252
	v_mul_f32_e32 v252, v76, v76
	v_fmac_f32_e32 v252, v77, v77
	v_mul_f32_e32 v253, v78, v78
	v_fmac_f32_e32 v253, v79, v79
	v_add_f32_e32 v252, v252, v253
	v_add_f32_e32 v254, v254, v252
	v_subrev_f32_e32 v80, s37, v80
	v_subrev_f32_e32 v81, s37, v81
	v_subrev_f32_e32 v82, s37, v82
	v_subrev_f32_e32 v83, s37, v83
	v_subrev_f32_e32 v84, s37, v84
	v_subrev_f32_e32 v85, s37, v85
	v_subrev_f32_e32 v86, s37, v86
	v_subrev_f32_e32 v87, s37, v87
	v_mul_f32_e32 v252, v80, v80
	v_fmac_f32_e32 v252, v81, v81
	v_mul_f32_e32 v253, v82, v82
	v_fmac_f32_e32 v253, v83, v83
	v_add_f32_e32 v252, v252, v253
	v_add_f32_e32 v254, v254, v252
	v_mul_f32_e32 v252, v84, v84
	v_fmac_f32_e32 v252, v85, v85
	v_mul_f32_e32 v253, v86, v86
	v_fmac_f32_e32 v253, v87, v87
	v_add_f32_e32 v252, v252, v253
	v_add_f32_e32 v254, v254, v252
	v_subrev_f32_e32 v244, s37, v244
	v_subrev_f32_e32 v245, s37, v245
	v_subrev_f32_e32 v246, s37, v246
	v_subrev_f32_e32 v247, s37, v247
	v_subrev_f32_e32 v248, s37, v248
	v_subrev_f32_e32 v249, s37, v249
	v_subrev_f32_e32 v250, s37, v250
	v_subrev_f32_e32 v251, s37, v251
	v_mul_f32_e32 v252, v244, v244
	v_fmac_f32_e32 v252, v245, v245
	v_mul_f32_e32 v253, v246, v246
	v_fmac_f32_e32 v253, v247, v247
	v_add_f32_e32 v252, v252, v253
	v_add_f32_e32 v254, v254, v252
	v_mul_f32_e32 v252, v248, v248
	v_fmac_f32_e32 v252, v249, v249
	v_mul_f32_e32 v253, v250, v250
	v_fmac_f32_e32 v253, v251, v251
	v_add_f32_e32 v252, v252, v253
	v_add_f32_e32 v254, v254, v252
	s_nop 1
	v_add_f32_dpp v252, v254, v254 quad_perm:[1,0,3,2] row_mask:0xf bank_mask:0xf
	s_nop 1
	v_add_f32_dpp v252, v252, v252 quad_perm:[2,3,0,1] row_mask:0xf bank_mask:0xf
	s_nop 1
	v_add_f32_dpp v252, v252, v252 row_half_mirror row_mask:0xf bank_mask:0xf
	s_nop 1
	v_add_f32_dpp v252, v252, v252 row_mirror row_mask:0xf bank_mask:0xf
	s_nop 1
	v_readlane_b32 s40, v252, 0
	v_readlane_b32 s41, v252, 16
	v_readlane_b32 s42, v252, 32
	v_readlane_b32 s43, v252, 48
	s_nop 1
	v_mov_b32_e32 v253, s40
	v_add_f32_e32 v253, s41, v253
	v_add_f32_e32 v253, s42, v253
	v_add_f32_e32 v253, s43, v253
	v_mov_b32_e32 v252, 0x3a000000
	v_fmaak_f32 v253, v253, v252, 0x3727c5ac
	v_rsq_f32_e32 v253, v253
	s_nop 1
	v_readfirstlane_b32 s37, v253
	s_mov_b32 s12, s4
	s_mov_b32 s13, s5
	ds_read_b64 v[252:253], v168
	ds_read_b64 v[254:255], v168 offset:8192
	ds_read_b64 v[88:89], v168 offset:512
	ds_read_b64 v[242:243], v168 offset:8704
	s_waitcnt lgkmcnt(2)
	v_mul_f32_e32 v64, s37, v64
	v_mul_f32_e32 v65, s37, v65
	v_fma_f32 v64, v64, v252, v254
	v_fma_f32 v65, v65, v253, v255
	ds_read_b64 v[252:253], v168 offset:1024
	ds_read_b64 v[254:255], v168 offset:9216
	s_waitcnt lgkmcnt(2)
	v_mul_f32_e32 v66, s37, v66
	v_mul_f32_e32 v67, s37, v67
	v_fma_f32 v66, v66, v88, v242
	v_fma_f32 v67, v67, v89, v243
	ds_read_b64 v[88:89], v168 offset:1536
	ds_read_b64 v[242:243], v168 offset:9728
	s_waitcnt lgkmcnt(2)
	v_mul_f32_e32 v68, s37, v68
	v_mul_f32_e32 v69, s37, v69
	v_fma_f32 v68, v68, v252, v254
	v_fma_f32 v69, v69, v253, v255
	ds_read_b64 v[252:253], v168 offset:2048
	ds_read_b64 v[254:255], v168 offset:10240
	s_waitcnt lgkmcnt(2)
	v_mul_f32_e32 v70, s37, v70
	v_mul_f32_e32 v71, s37, v71
	v_fma_f32 v70, v70, v88, v242
	v_fma_f32 v71, v71, v89, v243
	v_cvt_pk_bf16_f32 v64, v64, v65
	v_cvt_pk_bf16_f32 v65, v66, v67
	v_cvt_pk_bf16_f32 v66, v68, v69
	v_cvt_pk_bf16_f32 v67, v70, v71
	global_store_dwordx4 v90, v[64:67], s[12:13]
	ds_read_b64 v[88:89], v168 offset:2560
	ds_read_b64 v[242:243], v168 offset:10752
	s_waitcnt lgkmcnt(2)
	v_mul_f32_e32 v72, s37, v72
	v_mul_f32_e32 v73, s37, v73
	v_fma_f32 v72, v72, v252, v254
	v_fma_f32 v73, v73, v253, v255
	ds_read_b64 v[252:253], v168 offset:3072
	ds_read_b64 v[254:255], v168 offset:11264
	s_waitcnt lgkmcnt(2)
	v_mul_f32_e32 v74, s37, v74
	v_mul_f32_e32 v75, s37, v75
	v_fma_f32 v74, v74, v88, v242
	v_fma_f32 v75, v75, v89, v243
	ds_read_b64 v[88:89], v168 offset:3584
	ds_read_b64 v[242:243], v168 offset:11776
	s_waitcnt lgkmcnt(2)
	v_mul_f32_e32 v76, s37, v76
	v_mul_f32_e32 v77, s37, v77
	v_fma_f32 v76, v76, v252, v254
	v_fma_f32 v77, v77, v253, v255
	ds_read_b64 v[252:253], v168 offset:4096
	ds_read_b64 v[254:255], v168 offset:12288
	s_waitcnt lgkmcnt(2)
	v_mul_f32_e32 v78, s37, v78
	v_mul_f32_e32 v79, s37, v79
	v_fma_f32 v78, v78, v88, v242
	v_fma_f32 v79, v79, v89, v243
	v_cvt_pk_bf16_f32 v72, v72, v73
	v_cvt_pk_bf16_f32 v73, v74, v75
	v_cvt_pk_bf16_f32 v74, v76, v77
	v_cvt_pk_bf16_f32 v75, v78, v79
	global_store_dwordx4 v90, v[72:75], s[12:13] offset:1024
	ds_read_b64 v[88:89], v168 offset:4608
	ds_read_b64 v[242:243], v168 offset:12800
	s_waitcnt lgkmcnt(2)
	v_mul_f32_e32 v80, s37, v80
	v_mul_f32_e32 v81, s37, v81
	v_fma_f32 v80, v80, v252, v254
	v_fma_f32 v81, v81, v253, v255
	ds_read_b64 v[252:253], v168 offset:5120
	ds_read_b64 v[254:255], v168 offset:13312
	s_waitcnt lgkmcnt(2)
	v_mul_f32_e32 v82, s37, v82
	v_mul_f32_e32 v83, s37, v83
	v_fma_f32 v82, v82, v88, v242
	v_fma_f32 v83, v83, v89, v243
	ds_read_b64 v[88:89], v168 offset:5632
	ds_read_b64 v[242:243], v168 offset:13824
	s_waitcnt lgkmcnt(2)
	v_mul_f32_e32 v84, s37, v84
	v_mul_f32_e32 v85, s37, v85
	v_fma_f32 v84, v84, v252, v254
	v_fma_f32 v85, v85, v253, v255
	ds_read_b64 v[252:253], v168 offset:6144
	ds_read_b64 v[254:255], v168 offset:14336
	s_waitcnt lgkmcnt(2)
	v_mul_f32_e32 v86, s37, v86
	v_mul_f32_e32 v87, s37, v87
	v_fma_f32 v86, v86, v88, v242
	v_fma_f32 v87, v87, v89, v243
	v_cvt_pk_bf16_f32 v80, v80, v81
	v_cvt_pk_bf16_f32 v81, v82, v83
	v_cvt_pk_bf16_f32 v82, v84, v85
	v_cvt_pk_bf16_f32 v83, v86, v87
	global_store_dwordx4 v90, v[80:83], s[12:13] offset:2048
	ds_read_b64 v[88:89], v168 offset:6656
	ds_read_b64 v[242:243], v168 offset:14848
	s_waitcnt lgkmcnt(2)
	v_mul_f32_e32 v244, s37, v244
	v_mul_f32_e32 v245, s37, v245
	v_fma_f32 v244, v244, v252, v254
	v_fma_f32 v245, v245, v253, v255
	ds_read_b64 v[252:253], v168 offset:7168
	ds_read_b64 v[254:255], v168 offset:15360
	s_waitcnt lgkmcnt(2)
	v_mul_f32_e32 v246, s37, v246
	v_mul_f32_e32 v247, s37, v247
	v_fma_f32 v246, v246, v88, v242
	v_fma_f32 v247, v247, v89, v243
	ds_read_b64 v[88:89], v168 offset:7680
	ds_read_b64 v[242:243], v168 offset:15872
	s_waitcnt lgkmcnt(2)
	v_mul_f32_e32 v248, s37, v248
	v_mul_f32_e32 v249, s37, v249
	v_fma_f32 v248, v248, v252, v254
	v_fma_f32 v249, v249, v253, v255
	s_waitcnt lgkmcnt(0)
	v_mul_f32_e32 v250, s37, v250
	v_mul_f32_e32 v251, s37, v251
	v_fma_f32 v250, v250, v88, v242
	v_fma_f32 v251, v251, v89, v243
	v_cvt_pk_bf16_f32 v244, v244, v245
	v_cvt_pk_bf16_f32 v245, v246, v247
	v_cvt_pk_bf16_f32 v246, v248, v249
	v_cvt_pk_bf16_f32 v247, v250, v251
	global_store_dwordx4 v90, v[244:247], s[12:13] offset:3072
	s_waitcnt vmcnt(12)
	v_lshlrev_b32_e32 v64, 16, v48
	v_and_b32_e32 v65, 0xffff0000, v48
	v_and_b32_e32 v252, 0xffff0000, v32
	v_lshlrev_b32_e32 v32, 16, v32
	v_fmac_f32_e32 v64, 0x3fb504f3, v32
	v_fmac_f32_e32 v65, 0x3fb504f3, v252
	v_lshlrev_b32_e32 v66, 16, v49
	v_and_b32_e32 v67, 0xffff0000, v49
	v_and_b32_e32 v252, 0xffff0000, v33
	v_lshlrev_b32_e32 v33, 16, v33
	v_fmac_f32_e32 v66, 0x3fb504f3, v33
	v_fmac_f32_e32 v67, 0x3fb504f3, v252
	v_add_f32_e32 v252, v64, v65
	v_add_f32_e32 v253, v66, v67
	v_add_f32_e32 v254, v252, v253
	v_lshlrev_b32_e32 v68, 16, v50
	v_and_b32_e32 v69, 0xffff0000, v50
	v_and_b32_e32 v252, 0xffff0000, v34
	v_lshlrev_b32_e32 v34, 16, v34
	v_fmac_f32_e32 v68, 0x3fb504f3, v34
	v_fmac_f32_e32 v69, 0x3fb504f3, v252
	v_lshlrev_b32_e32 v70, 16, v51
	v_and_b32_e32 v71, 0xffff0000, v51
	v_and_b32_e32 v252, 0xffff0000, v35
	v_lshlrev_b32_e32 v35, 16, v35
	v_fmac_f32_e32 v70, 0x3fb504f3, v35
	v_fmac_f32_e32 v71, 0x3fb504f3, v252
	v_add_f32_e32 v252, v68, v69
	v_add_f32_e32 v253, v70, v71
	v_add_f32_e32 v252, v252, v253
	v_add_f32_e32 v254, v254, v252
	v_lshlrev_b32_e32 v72, 16, v52
	v_and_b32_e32 v73, 0xffff0000, v52
	v_and_b32_e32 v252, 0xffff0000, v36
	v_lshlrev_b32_e32 v36, 16, v36
	v_fmac_f32_e32 v72, 0x3fb504f3, v36
	v_fmac_f32_e32 v73, 0x3fb504f3, v252
	v_lshlrev_b32_e32 v74, 16, v53
	v_and_b32_e32 v75, 0xffff0000, v53
	v_and_b32_e32 v252, 0xffff0000, v37
	v_lshlrev_b32_e32 v37, 16, v37
	v_fmac_f32_e32 v74, 0x3fb504f3, v37
	v_fmac_f32_e32 v75, 0x3fb504f3, v252
	v_add_f32_e32 v252, v72, v73
	v_add_f32_e32 v253, v74, v75
	v_add_f32_e32 v252, v252, v253
	v_add_f32_e32 v254, v254, v252
	v_lshlrev_b32_e32 v76, 16, v54
	v_and_b32_e32 v77, 0xffff0000, v54
	v_and_b32_e32 v252, 0xffff0000, v38
	v_lshlrev_b32_e32 v38, 16, v38
	v_fmac_f32_e32 v76, 0x3fb504f3, v38
	v_fmac_f32_e32 v77, 0x3fb504f3, v252
	v_lshlrev_b32_e32 v78, 16, v55
	v_and_b32_e32 v79, 0xffff0000, v55
	v_and_b32_e32 v252, 0xffff0000, v39
	v_lshlrev_b32_e32 v39, 16, v39
	v_fmac_f32_e32 v78, 0x3fb504f3, v39
	v_fmac_f32_e32 v79, 0x3fb504f3, v252
	v_add_f32_e32 v252, v76, v77
	v_add_f32_e32 v253, v78, v79
	v_add_f32_e32 v252, v252, v253
	v_add_f32_e32 v254, v254, v252
	v_lshlrev_b32_e32 v80, 16, v56
	v_and_b32_e32 v81, 0xffff0000, v56
	v_and_b32_e32 v252, 0xffff0000, v40
	v_lshlrev_b32_e32 v40, 16, v40
	v_fmac_f32_e32 v80, 0x3fb504f3, v40
	v_fmac_f32_e32 v81, 0x3fb504f3, v252
	v_lshlrev_b32_e32 v82, 16, v57
	v_and_b32_e32 v83, 0xffff0000, v57
	v_and_b32_e32 v252, 0xffff0000, v41
	v_lshlrev_b32_e32 v41, 16, v41
	v_fmac_f32_e32 v82, 0x3fb504f3, v41
	v_fmac_f32_e32 v83, 0x3fb504f3, v252
	v_add_f32_e32 v252, v80, v81
	v_add_f32_e32 v253, v82, v83
	v_add_f32_e32 v252, v252, v253
	v_add_f32_e32 v254, v254, v252
	v_lshlrev_b32_e32 v84, 16, v58
	v_and_b32_e32 v85, 0xffff0000, v58
	v_and_b32_e32 v252, 0xffff0000, v42
	v_lshlrev_b32_e32 v42, 16, v42
	v_fmac_f32_e32 v84, 0x3fb504f3, v42
	v_fmac_f32_e32 v85, 0x3fb504f3, v252
	v_lshlrev_b32_e32 v86, 16, v59
	v_and_b32_e32 v87, 0xffff0000, v59
	v_and_b32_e32 v252, 0xffff0000, v43
	v_lshlrev_b32_e32 v43, 16, v43
	v_fmac_f32_e32 v86, 0x3fb504f3, v43
	v_fmac_f32_e32 v87, 0x3fb504f3, v252
	v_add_f32_e32 v252, v84, v85
	v_add_f32_e32 v253, v86, v87
	v_add_f32_e32 v252, v252, v253
	v_add_f32_e32 v254, v254, v252
	v_lshlrev_b32_e32 v244, 16, v60
	v_and_b32_e32 v245, 0xffff0000, v60
	v_and_b32_e32 v252, 0xffff0000, v44
	v_lshlrev_b32_e32 v44, 16, v44
	v_fmac_f32_e32 v244, 0x3fb504f3, v44
	v_fmac_f32_e32 v245, 0x3fb504f3, v252
	v_lshlrev_b32_e32 v246, 16, v61
	v_and_b32_e32 v247, 0xffff0000, v61
	v_and_b32_e32 v252, 0xffff0000, v45
	v_lshlrev_b32_e32 v45, 16, v45
	v_fmac_f32_e32 v246, 0x3fb504f3, v45
	v_fmac_f32_e32 v247, 0x3fb504f3, v252
	v_add_f32_e32 v252, v244, v245
	v_add_f32_e32 v253, v246, v247
	v_add_f32_e32 v252, v252, v253
	v_add_f32_e32 v254, v254, v252
	v_lshlrev_b32_e32 v248, 16, v62
	v_and_b32_e32 v249, 0xffff0000, v62
	v_and_b32_e32 v252, 0xffff0000, v46
	v_lshlrev_b32_e32 v46, 16, v46
	v_fmac_f32_e32 v248, 0x3fb504f3, v46
	v_fmac_f32_e32 v249, 0x3fb504f3, v252
	v_lshlrev_b32_e32 v250, 16, v63
	v_and_b32_e32 v251, 0xffff0000, v63
	v_and_b32_e32 v252, 0xffff0000, v47
	v_lshlrev_b32_e32 v47, 16, v47
	v_fmac_f32_e32 v250, 0x3fb504f3, v47
	v_fmac_f32_e32 v251, 0x3fb504f3, v252
	v_add_f32_e32 v252, v248, v249
	v_add_f32_e32 v253, v250, v251
	v_add_f32_e32 v252, v252, v253
	v_add_f32_e32 v254, v254, v252
	v_readlane_b32 s38, v241, 0
	s_lshl_b32 s30, s38, 14
	v_subrev_u32_e32 v88, s30, v90
	s_add_u32 s12, s8, 0x400000
	s_addc_u32 s13, s9, 0
	global_load_dwordx4 v[32:35], v88, s[12:13]
	global_load_dwordx4 v[36:39], v88, s[12:13] offset:1024
	global_load_dwordx4 v[40:43], v88, s[12:13] offset:2048
	global_load_dwordx4 v[44:47], v88, s[12:13] offset:3072
	s_add_u32 s12, s8, 0x800000
	s_addc_u32 s13, s9, 0
	global_load_dwordx4 v[48:51], v88, s[12:13]
	global_load_dwordx4 v[52:55], v88, s[12:13] offset:1024
	global_load_dwordx4 v[56:59], v88, s[12:13] offset:2048
	global_load_dwordx4 v[60:63], v88, s[12:13] offset:3072
	s_nop 1
	v_add_f32_dpp v252, v254, v254 quad_perm:[1,0,3,2] row_mask:0xf bank_mask:0xf
	s_nop 1
	v_add_f32_dpp v252, v252, v252 quad_perm:[2,3,0,1] row_mask:0xf bank_mask:0xf
	s_nop 1
	v_add_f32_dpp v252, v252, v252 row_half_mirror row_mask:0xf bank_mask:0xf
	s_nop 1
	v_add_f32_dpp v252, v252, v252 row_mirror row_mask:0xf bank_mask:0xf
	s_nop 1
	v_readlane_b32 s40, v252, 0
	v_readlane_b32 s41, v252, 16
	v_readlane_b32 s42, v252, 32
	v_readlane_b32 s43, v252, 48
	s_nop 1
	v_mov_b32_e32 v253, s40
	v_add_f32_e32 v253, s41, v253
	v_add_f32_e32 v253, s42, v253
	v_add_f32_e32 v253, s43, v253
	v_mul_f32_e32 v253, 0x3a000000, v253
	s_nop 0
	v_readfirstlane_b32 s37, v253
	s_nop 1
	v_subrev_f32_e32 v64, s37, v64
	v_subrev_f32_e32 v65, s37, v65
	v_subrev_f32_e32 v66, s37, v66
	v_subrev_f32_e32 v67, s37, v67
	v_subrev_f32_e32 v68, s37, v68
	v_subrev_f32_e32 v69, s37, v69
	v_subrev_f32_e32 v70, s37, v70
	v_subrev_f32_e32 v71, s37, v71
	v_mul_f32_e32 v252, v64, v64
	v_fmac_f32_e32 v252, v65, v65
	v_mul_f32_e32 v253, v66, v66
	v_fmac_f32_e32 v253, v67, v67
	v_add_f32_e32 v254, v252, v253
	v_mul_f32_e32 v252, v68, v68
	v_fmac_f32_e32 v252, v69, v69
	v_mul_f32_e32 v253, v70, v70
	v_fmac_f32_e32 v253, v71, v71
	v_add_f32_e32 v252, v252, v253
	v_add_f32_e32 v254, v254, v252
	v_subrev_f32_e32 v72, s37, v72
	v_subrev_f32_e32 v73, s37, v73
	v_subrev_f32_e32 v74, s37, v74
	v_subrev_f32_e32 v75, s37, v75
	v_subrev_f32_e32 v76, s37, v76
	v_subrev_f32_e32 v77, s37, v77
	v_subrev_f32_e32 v78, s37, v78
	v_subrev_f32_e32 v79, s37, v79
	v_mul_f32_e32 v252, v72, v72
	v_fmac_f32_e32 v252, v73, v73
	v_mul_f32_e32 v253, v74, v74
	v_fmac_f32_e32 v253, v75, v75
	v_add_f32_e32 v252, v252, v253
	v_add_f32_e32 v254, v254, v252
	v_mul_f32_e32 v252, v76, v76
	v_fmac_f32_e32 v252, v77, v77
	v_mul_f32_e32 v253, v78, v78
	v_fmac_f32_e32 v253, v79, v79
	v_add_f32_e32 v252, v252, v253
	v_add_f32_e32 v254, v254, v252
	v_subrev_f32_e32 v80, s37, v80
	v_subrev_f32_e32 v81, s37, v81
	v_subrev_f32_e32 v82, s37, v82
	v_subrev_f32_e32 v83, s37, v83
	v_subrev_f32_e32 v84, s37, v84
	v_subrev_f32_e32 v85, s37, v85
	v_subrev_f32_e32 v86, s37, v86
	v_subrev_f32_e32 v87, s37, v87
	v_mul_f32_e32 v252, v80, v80
	v_fmac_f32_e32 v252, v81, v81
	v_mul_f32_e32 v253, v82, v82
	v_fmac_f32_e32 v253, v83, v83
	v_add_f32_e32 v252, v252, v253
	v_add_f32_e32 v254, v254, v252
	v_mul_f32_e32 v252, v84, v84
	v_fmac_f32_e32 v252, v85, v85
	v_mul_f32_e32 v253, v86, v86
	v_fmac_f32_e32 v253, v87, v87
	v_add_f32_e32 v252, v252, v253
	v_add_f32_e32 v254, v254, v252
	v_subrev_f32_e32 v244, s37, v244
	v_subrev_f32_e32 v245, s37, v245
	v_subrev_f32_e32 v246, s37, v246
	v_subrev_f32_e32 v247, s37, v247
	v_subrev_f32_e32 v248, s37, v248
	v_subrev_f32_e32 v249, s37, v249
	v_subrev_f32_e32 v250, s37, v250
	v_subrev_f32_e32 v251, s37, v251
	v_mul_f32_e32 v252, v244, v244
	v_fmac_f32_e32 v252, v245, v245
	v_mul_f32_e32 v253, v246, v246
	v_fmac_f32_e32 v253, v247, v247
	v_add_f32_e32 v252, v252, v253
	v_add_f32_e32 v254, v254, v252
	v_mul_f32_e32 v252, v248, v248
	v_fmac_f32_e32 v252, v249, v249
	v_mul_f32_e32 v253, v250, v250
	v_fmac_f32_e32 v253, v251, v251
	v_add_f32_e32 v252, v252, v253
	v_add_f32_e32 v254, v254, v252
	s_nop 1
	v_add_f32_dpp v252, v254, v254 quad_perm:[1,0,3,2] row_mask:0xf bank_mask:0xf
	s_nop 1
	v_add_f32_dpp v252, v252, v252 quad_perm:[2,3,0,1] row_mask:0xf bank_mask:0xf
	s_nop 1
	v_add_f32_dpp v252, v252, v252 row_half_mirror row_mask:0xf bank_mask:0xf
	s_nop 1
	v_add_f32_dpp v252, v252, v252 row_mirror row_mask:0xf bank_mask:0xf
	s_nop 1
	v_readlane_b32 s40, v252, 0
	v_readlane_b32 s41, v252, 16
	v_readlane_b32 s42, v252, 32
	v_readlane_b32 s43, v252, 48
	s_nop 1
	v_mov_b32_e32 v253, s40
	v_add_f32_e32 v253, s41, v253
	v_add_f32_e32 v253, s42, v253
	v_add_f32_e32 v253, s43, v253
	v_mov_b32_e32 v252, 0x3a000000
	v_fmaak_f32 v253, v253, v252, 0x3727c5ac
	v_rsq_f32_e32 v253, v253
	s_nop 1
	v_readfirstlane_b32 s37, v253
	s_add_u32 s12, s4, 0x800000
	s_addc_u32 s13, s5, 0
	ds_read_b64 v[252:253], v168
	ds_read_b64 v[254:255], v168 offset:8192
	ds_read_b64 v[88:89], v168 offset:512
	ds_read_b64 v[242:243], v168 offset:8704
	s_waitcnt lgkmcnt(2)
	v_mul_f32_e32 v64, s37, v64
	v_mul_f32_e32 v65, s37, v65
	v_fma_f32 v64, v64, v252, v254
	v_fma_f32 v65, v65, v253, v255
	ds_read_b64 v[252:253], v168 offset:1024
	ds_read_b64 v[254:255], v168 offset:9216
	s_waitcnt lgkmcnt(2)
	v_mul_f32_e32 v66, s37, v66
	v_mul_f32_e32 v67, s37, v67
	v_fma_f32 v66, v66, v88, v242
	v_fma_f32 v67, v67, v89, v243
	ds_read_b64 v[88:89], v168 offset:1536
	ds_read_b64 v[242:243], v168 offset:9728
	s_waitcnt lgkmcnt(2)
	v_mul_f32_e32 v68, s37, v68
	v_mul_f32_e32 v69, s37, v69
	v_fma_f32 v68, v68, v252, v254
	v_fma_f32 v69, v69, v253, v255
	ds_read_b64 v[252:253], v168 offset:2048
	ds_read_b64 v[254:255], v168 offset:10240
	s_waitcnt lgkmcnt(2)
	v_mul_f32_e32 v70, s37, v70
	v_mul_f32_e32 v71, s37, v71
	v_fma_f32 v70, v70, v88, v242
	v_fma_f32 v71, v71, v89, v243
	v_cvt_pk_bf16_f32 v64, v64, v65
	v_cvt_pk_bf16_f32 v65, v66, v67
	v_cvt_pk_bf16_f32 v66, v68, v69
	v_cvt_pk_bf16_f32 v67, v70, v71
	global_store_dwordx4 v90, v[64:67], s[12:13]
	ds_read_b64 v[88:89], v168 offset:2560
	ds_read_b64 v[242:243], v168 offset:10752
	s_waitcnt lgkmcnt(2)
	v_mul_f32_e32 v72, s37, v72
	v_mul_f32_e32 v73, s37, v73
	v_fma_f32 v72, v72, v252, v254
	v_fma_f32 v73, v73, v253, v255
	ds_read_b64 v[252:253], v168 offset:3072
	ds_read_b64 v[254:255], v168 offset:11264
	s_waitcnt lgkmcnt(2)
	v_mul_f32_e32 v74, s37, v74
	v_mul_f32_e32 v75, s37, v75
	v_fma_f32 v74, v74, v88, v242
	v_fma_f32 v75, v75, v89, v243
	ds_read_b64 v[88:89], v168 offset:3584
	ds_read_b64 v[242:243], v168 offset:11776
	s_waitcnt lgkmcnt(2)
	v_mul_f32_e32 v76, s37, v76
	v_mul_f32_e32 v77, s37, v77
	v_fma_f32 v76, v76, v252, v254
	v_fma_f32 v77, v77, v253, v255
	ds_read_b64 v[252:253], v168 offset:4096
	ds_read_b64 v[254:255], v168 offset:12288
	s_waitcnt lgkmcnt(2)
	v_mul_f32_e32 v78, s37, v78
	v_mul_f32_e32 v79, s37, v79
	v_fma_f32 v78, v78, v88, v242
	v_fma_f32 v79, v79, v89, v243
	v_cvt_pk_bf16_f32 v72, v72, v73
	v_cvt_pk_bf16_f32 v73, v74, v75
	v_cvt_pk_bf16_f32 v74, v76, v77
	v_cvt_pk_bf16_f32 v75, v78, v79
	global_store_dwordx4 v90, v[72:75], s[12:13] offset:1024
	ds_read_b64 v[88:89], v168 offset:4608
	ds_read_b64 v[242:243], v168 offset:12800
	s_waitcnt lgkmcnt(2)
	v_mul_f32_e32 v80, s37, v80
	v_mul_f32_e32 v81, s37, v81
	v_fma_f32 v80, v80, v252, v254
	v_fma_f32 v81, v81, v253, v255
	ds_read_b64 v[252:253], v168 offset:5120
	ds_read_b64 v[254:255], v168 offset:13312
	s_waitcnt lgkmcnt(2)
	v_mul_f32_e32 v82, s37, v82
	v_mul_f32_e32 v83, s37, v83
	v_fma_f32 v82, v82, v88, v242
	v_fma_f32 v83, v83, v89, v243
	ds_read_b64 v[88:89], v168 offset:5632
	ds_read_b64 v[242:243], v168 offset:13824
	s_waitcnt lgkmcnt(2)
	v_mul_f32_e32 v84, s37, v84
	v_mul_f32_e32 v85, s37, v85
	v_fma_f32 v84, v84, v252, v254
	v_fma_f32 v85, v85, v253, v255
	ds_read_b64 v[252:253], v168 offset:6144
	ds_read_b64 v[254:255], v168 offset:14336
	s_waitcnt lgkmcnt(2)
	v_mul_f32_e32 v86, s37, v86
	v_mul_f32_e32 v87, s37, v87
	v_fma_f32 v86, v86, v88, v242
	v_fma_f32 v87, v87, v89, v243
	v_cvt_pk_bf16_f32 v80, v80, v81
	v_cvt_pk_bf16_f32 v81, v82, v83
	v_cvt_pk_bf16_f32 v82, v84, v85
	v_cvt_pk_bf16_f32 v83, v86, v87
	global_store_dwordx4 v90, v[80:83], s[12:13] offset:2048
	ds_read_b64 v[88:89], v168 offset:6656
	ds_read_b64 v[242:243], v168 offset:14848
	s_waitcnt lgkmcnt(2)
	v_mul_f32_e32 v244, s37, v244
	v_mul_f32_e32 v245, s37, v245
	v_fma_f32 v244, v244, v252, v254
	v_fma_f32 v245, v245, v253, v255
	ds_read_b64 v[252:253], v168 offset:7168
	ds_read_b64 v[254:255], v168 offset:15360
	s_waitcnt lgkmcnt(2)
	v_mul_f32_e32 v246, s37, v246
	v_mul_f32_e32 v247, s37, v247
	v_fma_f32 v246, v246, v88, v242
	v_fma_f32 v247, v247, v89, v243
	ds_read_b64 v[88:89], v168 offset:7680
	ds_read_b64 v[242:243], v168 offset:15872
	s_waitcnt lgkmcnt(2)
	v_mul_f32_e32 v248, s37, v248
	v_mul_f32_e32 v249, s37, v249
	v_fma_f32 v248, v248, v252, v254
	v_fma_f32 v249, v249, v253, v255
	s_waitcnt lgkmcnt(0)
	v_mul_f32_e32 v250, s37, v250
	v_mul_f32_e32 v251, s37, v251
	v_fma_f32 v250, v250, v88, v242
	v_fma_f32 v251, v251, v89, v243
	v_cvt_pk_bf16_f32 v244, v244, v245
	v_cvt_pk_bf16_f32 v245, v246, v247
	v_cvt_pk_bf16_f32 v246, v248, v249
	v_cvt_pk_bf16_f32 v247, v250, v251
	global_store_dwordx4 v90, v[244:247], s[12:13] offset:3072
	s_waitcnt vmcnt(16)
	v_lshlrev_b32_e32 v64, 16, v16
	v_and_b32_e32 v65, 0xffff0000, v16
	v_and_b32_e32 v252, 0xffff0000, v0
	v_lshlrev_b32_e32 v0, 16, v0
	v_fmac_f32_e32 v64, 0x3fb504f3, v0
	v_fmac_f32_e32 v65, 0x3fb504f3, v252
	v_lshlrev_b32_e32 v66, 16, v17
	v_and_b32_e32 v67, 0xffff0000, v17
	v_and_b32_e32 v252, 0xffff0000, v1
	v_lshlrev_b32_e32 v1, 16, v1
	v_fmac_f32_e32 v66, 0x3fb504f3, v1
	v_fmac_f32_e32 v67, 0x3fb504f3, v252
	v_add_f32_e32 v252, v64, v65
	v_add_f32_e32 v253, v66, v67
	v_add_f32_e32 v254, v252, v253
	v_lshlrev_b32_e32 v68, 16, v18
	v_and_b32_e32 v69, 0xffff0000, v18
	v_and_b32_e32 v252, 0xffff0000, v2
	v_lshlrev_b32_e32 v2, 16, v2
	v_fmac_f32_e32 v68, 0x3fb504f3, v2
	v_fmac_f32_e32 v69, 0x3fb504f3, v252
	v_lshlrev_b32_e32 v70, 16, v19
	v_and_b32_e32 v71, 0xffff0000, v19
	v_and_b32_e32 v252, 0xffff0000, v3
	v_lshlrev_b32_e32 v3, 16, v3
	v_fmac_f32_e32 v70, 0x3fb504f3, v3
	v_fmac_f32_e32 v71, 0x3fb504f3, v252
	v_add_f32_e32 v252, v68, v69
	v_add_f32_e32 v253, v70, v71
	v_add_f32_e32 v252, v252, v253
	v_add_f32_e32 v254, v254, v252
	v_lshlrev_b32_e32 v72, 16, v20
	v_and_b32_e32 v73, 0xffff0000, v20
	v_and_b32_e32 v252, 0xffff0000, v4
	v_lshlrev_b32_e32 v4, 16, v4
	v_fmac_f32_e32 v72, 0x3fb504f3, v4
	v_fmac_f32_e32 v73, 0x3fb504f3, v252
	v_lshlrev_b32_e32 v74, 16, v21
	v_and_b32_e32 v75, 0xffff0000, v21
	v_and_b32_e32 v252, 0xffff0000, v5
	v_lshlrev_b32_e32 v5, 16, v5
	v_fmac_f32_e32 v74, 0x3fb504f3, v5
	v_fmac_f32_e32 v75, 0x3fb504f3, v252
	v_add_f32_e32 v252, v72, v73
	v_add_f32_e32 v253, v74, v75
	v_add_f32_e32 v252, v252, v253
	v_add_f32_e32 v254, v254, v252
	v_lshlrev_b32_e32 v76, 16, v22
	v_and_b32_e32 v77, 0xffff0000, v22
	v_and_b32_e32 v252, 0xffff0000, v6
	v_lshlrev_b32_e32 v6, 16, v6
	v_fmac_f32_e32 v76, 0x3fb504f3, v6
	v_fmac_f32_e32 v77, 0x3fb504f3, v252
	v_lshlrev_b32_e32 v78, 16, v23
	v_and_b32_e32 v79, 0xffff0000, v23
	v_and_b32_e32 v252, 0xffff0000, v7
	v_lshlrev_b32_e32 v7, 16, v7
	v_fmac_f32_e32 v78, 0x3fb504f3, v7
	v_fmac_f32_e32 v79, 0x3fb504f3, v252
	v_add_f32_e32 v252, v76, v77
	v_add_f32_e32 v253, v78, v79
	v_add_f32_e32 v252, v252, v253
	v_add_f32_e32 v254, v254, v252
	v_lshlrev_b32_e32 v80, 16, v24
	v_and_b32_e32 v81, 0xffff0000, v24
	v_and_b32_e32 v252, 0xffff0000, v8
	v_lshlrev_b32_e32 v8, 16, v8
	v_fmac_f32_e32 v80, 0x3fb504f3, v8
	v_fmac_f32_e32 v81, 0x3fb504f3, v252
	v_lshlrev_b32_e32 v82, 16, v25
	v_and_b32_e32 v83, 0xffff0000, v25
	v_and_b32_e32 v252, 0xffff0000, v9
	v_lshlrev_b32_e32 v9, 16, v9
	v_fmac_f32_e32 v82, 0x3fb504f3, v9
	v_fmac_f32_e32 v83, 0x3fb504f3, v252
	v_add_f32_e32 v252, v80, v81
	v_add_f32_e32 v253, v82, v83
	v_add_f32_e32 v252, v252, v253
	v_add_f32_e32 v254, v254, v252
	v_lshlrev_b32_e32 v84, 16, v26
	v_and_b32_e32 v85, 0xffff0000, v26
	v_and_b32_e32 v252, 0xffff0000, v10
	v_lshlrev_b32_e32 v10, 16, v10
	v_fmac_f32_e32 v84, 0x3fb504f3, v10
	v_fmac_f32_e32 v85, 0x3fb504f3, v252
	v_lshlrev_b32_e32 v86, 16, v27
	v_and_b32_e32 v87, 0xffff0000, v27
	v_and_b32_e32 v252, 0xffff0000, v11
	v_lshlrev_b32_e32 v11, 16, v11
	v_fmac_f32_e32 v86, 0x3fb504f3, v11
	v_fmac_f32_e32 v87, 0x3fb504f3, v252
	v_add_f32_e32 v252, v84, v85
	v_add_f32_e32 v253, v86, v87
	v_add_f32_e32 v252, v252, v253
	v_add_f32_e32 v254, v254, v252
	v_lshlrev_b32_e32 v244, 16, v28
	v_and_b32_e32 v245, 0xffff0000, v28
	v_and_b32_e32 v252, 0xffff0000, v12
	v_lshlrev_b32_e32 v12, 16, v12
	v_fmac_f32_e32 v244, 0x3fb504f3, v12
	v_fmac_f32_e32 v245, 0x3fb504f3, v252
	v_lshlrev_b32_e32 v246, 16, v29
	v_and_b32_e32 v247, 0xffff0000, v29
	v_and_b32_e32 v252, 0xffff0000, v13
	v_lshlrev_b32_e32 v13, 16, v13
	v_fmac_f32_e32 v246, 0x3fb504f3, v13
	v_fmac_f32_e32 v247, 0x3fb504f3, v252
	v_add_f32_e32 v252, v244, v245
	v_add_f32_e32 v253, v246, v247
	v_add_f32_e32 v252, v252, v253
	v_add_f32_e32 v254, v254, v252
	v_lshlrev_b32_e32 v248, 16, v30
	v_and_b32_e32 v249, 0xffff0000, v30
	v_and_b32_e32 v252, 0xffff0000, v14
	v_lshlrev_b32_e32 v14, 16, v14
	v_fmac_f32_e32 v248, 0x3fb504f3, v14
	v_fmac_f32_e32 v249, 0x3fb504f3, v252
	v_lshlrev_b32_e32 v250, 16, v31
	v_and_b32_e32 v251, 0xffff0000, v31
	v_and_b32_e32 v252, 0xffff0000, v15
	v_lshlrev_b32_e32 v15, 16, v15
	v_fmac_f32_e32 v250, 0x3fb504f3, v15
	v_fmac_f32_e32 v251, 0x3fb504f3, v252
	v_add_f32_e32 v252, v248, v249
	v_add_f32_e32 v253, v250, v251
	v_add_f32_e32 v252, v252, v253
	v_add_f32_e32 v254, v254, v252
	v_readlane_b32 s38, v241, 0
	s_lshl_b32 s30, s38, 14
	v_subrev_u32_e32 v88, s30, v90
	s_add_u32 s12, s4, 0x2000000
	s_addc_u32 s13, s5, 0
	global_load_dwordx4 v[0:3], v88, s[12:13]
	global_load_dwordx4 v[4:7], v88, s[12:13] offset:1024
	global_load_dwordx4 v[8:11], v88, s[12:13] offset:2048
	global_load_dwordx4 v[12:15], v88, s[12:13] offset:3072
	global_load_dwordx4 v[16:19], v88, s[8:9]
	global_load_dwordx4 v[20:23], v88, s[8:9] offset:1024
	global_load_dwordx4 v[24:27], v88, s[8:9] offset:2048
	global_load_dwordx4 v[28:31], v88, s[8:9] offset:3072
	s_nop 1
	v_add_f32_dpp v252, v254, v254 quad_perm:[1,0,3,2] row_mask:0xf bank_mask:0xf
	s_nop 1
	v_add_f32_dpp v252, v252, v252 quad_perm:[2,3,0,1] row_mask:0xf bank_mask:0xf
	s_nop 1
	v_add_f32_dpp v252, v252, v252 row_half_mirror row_mask:0xf bank_mask:0xf
	s_nop 1
	v_add_f32_dpp v252, v252, v252 row_mirror row_mask:0xf bank_mask:0xf
	s_nop 1
	v_readlane_b32 s40, v252, 0
	v_readlane_b32 s41, v252, 16
	v_readlane_b32 s42, v252, 32
	v_readlane_b32 s43, v252, 48
	s_nop 1
	v_mov_b32_e32 v253, s40
	v_add_f32_e32 v253, s41, v253
	v_add_f32_e32 v253, s42, v253
	v_add_f32_e32 v253, s43, v253
	v_mul_f32_e32 v253, 0x3a000000, v253
	s_nop 0
	v_readfirstlane_b32 s37, v253
	s_nop 1
	v_subrev_f32_e32 v64, s37, v64
	v_subrev_f32_e32 v65, s37, v65
	v_subrev_f32_e32 v66, s37, v66
	v_subrev_f32_e32 v67, s37, v67
	v_subrev_f32_e32 v68, s37, v68
	v_subrev_f32_e32 v69, s37, v69
	v_subrev_f32_e32 v70, s37, v70
	v_subrev_f32_e32 v71, s37, v71
	v_mul_f32_e32 v252, v64, v64
	v_fmac_f32_e32 v252, v65, v65
	v_mul_f32_e32 v253, v66, v66
	v_fmac_f32_e32 v253, v67, v67
	v_add_f32_e32 v254, v252, v253
	v_mul_f32_e32 v252, v68, v68
	v_fmac_f32_e32 v252, v69, v69
	v_mul_f32_e32 v253, v70, v70
	v_fmac_f32_e32 v253, v71, v71
	v_add_f32_e32 v252, v252, v253
	v_add_f32_e32 v254, v254, v252
	v_subrev_f32_e32 v72, s37, v72
	v_subrev_f32_e32 v73, s37, v73
	v_subrev_f32_e32 v74, s37, v74
	v_subrev_f32_e32 v75, s37, v75
	v_subrev_f32_e32 v76, s37, v76
	v_subrev_f32_e32 v77, s37, v77
	v_subrev_f32_e32 v78, s37, v78
	v_subrev_f32_e32 v79, s37, v79
	v_mul_f32_e32 v252, v72, v72
	v_fmac_f32_e32 v252, v73, v73
	v_mul_f32_e32 v253, v74, v74
	v_fmac_f32_e32 v253, v75, v75
	v_add_f32_e32 v252, v252, v253
	v_add_f32_e32 v254, v254, v252
	v_mul_f32_e32 v252, v76, v76
	v_fmac_f32_e32 v252, v77, v77
	v_mul_f32_e32 v253, v78, v78
	v_fmac_f32_e32 v253, v79, v79
	v_add_f32_e32 v252, v252, v253
	v_add_f32_e32 v254, v254, v252
	v_subrev_f32_e32 v80, s37, v80
	v_subrev_f32_e32 v81, s37, v81
	v_subrev_f32_e32 v82, s37, v82
	v_subrev_f32_e32 v83, s37, v83
	v_subrev_f32_e32 v84, s37, v84
	v_subrev_f32_e32 v85, s37, v85
	v_subrev_f32_e32 v86, s37, v86
	v_subrev_f32_e32 v87, s37, v87
	v_mul_f32_e32 v252, v80, v80
	v_fmac_f32_e32 v252, v81, v81
	v_mul_f32_e32 v253, v82, v82
	v_fmac_f32_e32 v253, v83, v83
	v_add_f32_e32 v252, v252, v253
	v_add_f32_e32 v254, v254, v252
	v_mul_f32_e32 v252, v84, v84
	v_fmac_f32_e32 v252, v85, v85
	v_mul_f32_e32 v253, v86, v86
	v_fmac_f32_e32 v253, v87, v87
	v_add_f32_e32 v252, v252, v253
	v_add_f32_e32 v254, v254, v252
	v_subrev_f32_e32 v244, s37, v244
	v_subrev_f32_e32 v245, s37, v245
	v_subrev_f32_e32 v246, s37, v246
	v_subrev_f32_e32 v247, s37, v247
	v_subrev_f32_e32 v248, s37, v248
	v_subrev_f32_e32 v249, s37, v249
	v_subrev_f32_e32 v250, s37, v250
	v_subrev_f32_e32 v251, s37, v251
	v_mul_f32_e32 v252, v244, v244
	v_fmac_f32_e32 v252, v245, v245
	v_mul_f32_e32 v253, v246, v246
	v_fmac_f32_e32 v253, v247, v247
	v_add_f32_e32 v252, v252, v253
	v_add_f32_e32 v254, v254, v252
	v_mul_f32_e32 v252, v248, v248
	v_fmac_f32_e32 v252, v249, v249
	v_mul_f32_e32 v253, v250, v250
	v_fmac_f32_e32 v253, v251, v251
	v_add_f32_e32 v252, v252, v253
	v_add_f32_e32 v254, v254, v252
	s_nop 1
	v_add_f32_dpp v252, v254, v254 quad_perm:[1,0,3,2] row_mask:0xf bank_mask:0xf
	s_nop 1
	v_add_f32_dpp v252, v252, v252 quad_perm:[2,3,0,1] row_mask:0xf bank_mask:0xf
	s_nop 1
	v_add_f32_dpp v252, v252, v252 row_half_mirror row_mask:0xf bank_mask:0xf
	s_nop 1
	v_add_f32_dpp v252, v252, v252 row_mirror row_mask:0xf bank_mask:0xf
	s_nop 1
	v_readlane_b32 s40, v252, 0
	v_readlane_b32 s41, v252, 16
	v_readlane_b32 s42, v252, 32
	v_readlane_b32 s43, v252, 48
	s_nop 1
	v_mov_b32_e32 v253, s40
	v_add_f32_e32 v253, s41, v253
	v_add_f32_e32 v253, s42, v253
	v_add_f32_e32 v253, s43, v253
	v_mov_b32_e32 v252, 0x3a000000
	v_fmaak_f32 v253, v253, v252, 0x3727c5ac
	v_rsq_f32_e32 v253, v253
	s_nop 1
	v_readfirstlane_b32 s37, v253
	s_add_u32 s12, s4, 0x1000000
	s_addc_u32 s13, s5, 0
	ds_read_b64 v[252:253], v168
	ds_read_b64 v[254:255], v168 offset:8192
	ds_read_b64 v[88:89], v168 offset:512
	ds_read_b64 v[242:243], v168 offset:8704
	s_waitcnt lgkmcnt(2)
	v_mul_f32_e32 v64, s37, v64
	v_mul_f32_e32 v65, s37, v65
	v_fma_f32 v64, v64, v252, v254
	v_fma_f32 v65, v65, v253, v255
	ds_read_b64 v[252:253], v168 offset:1024
	ds_read_b64 v[254:255], v168 offset:9216
	s_waitcnt lgkmcnt(2)
	v_mul_f32_e32 v66, s37, v66
	v_mul_f32_e32 v67, s37, v67
	v_fma_f32 v66, v66, v88, v242
	v_fma_f32 v67, v67, v89, v243
	ds_read_b64 v[88:89], v168 offset:1536
	ds_read_b64 v[242:243], v168 offset:9728
	s_waitcnt lgkmcnt(2)
	v_mul_f32_e32 v68, s37, v68
	v_mul_f32_e32 v69, s37, v69
	v_fma_f32 v68, v68, v252, v254
	v_fma_f32 v69, v69, v253, v255
	ds_read_b64 v[252:253], v168 offset:2048
	ds_read_b64 v[254:255], v168 offset:10240
	s_waitcnt lgkmcnt(2)
	v_mul_f32_e32 v70, s37, v70
	v_mul_f32_e32 v71, s37, v71
	v_fma_f32 v70, v70, v88, v242
	v_fma_f32 v71, v71, v89, v243
	v_cvt_pk_bf16_f32 v64, v64, v65
	v_cvt_pk_bf16_f32 v65, v66, v67
	v_cvt_pk_bf16_f32 v66, v68, v69
	v_cvt_pk_bf16_f32 v67, v70, v71
	global_store_dwordx4 v90, v[64:67], s[12:13]
	ds_read_b64 v[88:89], v168 offset:2560
	ds_read_b64 v[242:243], v168 offset:10752
	s_waitcnt lgkmcnt(2)
	v_mul_f32_e32 v72, s37, v72
	v_mul_f32_e32 v73, s37, v73
	v_fma_f32 v72, v72, v252, v254
	v_fma_f32 v73, v73, v253, v255
	ds_read_b64 v[252:253], v168 offset:3072
	ds_read_b64 v[254:255], v168 offset:11264
	s_waitcnt lgkmcnt(2)
	v_mul_f32_e32 v74, s37, v74
	v_mul_f32_e32 v75, s37, v75
	v_fma_f32 v74, v74, v88, v242
	v_fma_f32 v75, v75, v89, v243
	ds_read_b64 v[88:89], v168 offset:3584
	ds_read_b64 v[242:243], v168 offset:11776
	s_waitcnt lgkmcnt(2)
	v_mul_f32_e32 v76, s37, v76
	v_mul_f32_e32 v77, s37, v77
	v_fma_f32 v76, v76, v252, v254
	v_fma_f32 v77, v77, v253, v255
	ds_read_b64 v[252:253], v168 offset:4096
	ds_read_b64 v[254:255], v168 offset:12288
	s_waitcnt lgkmcnt(2)
	v_mul_f32_e32 v78, s37, v78
	v_mul_f32_e32 v79, s37, v79
	v_fma_f32 v78, v78, v88, v242
	v_fma_f32 v79, v79, v89, v243
	v_cvt_pk_bf16_f32 v72, v72, v73
	v_cvt_pk_bf16_f32 v73, v74, v75
	v_cvt_pk_bf16_f32 v74, v76, v77
	v_cvt_pk_bf16_f32 v75, v78, v79
	global_store_dwordx4 v90, v[72:75], s[12:13] offset:1024
	ds_read_b64 v[88:89], v168 offset:4608
	ds_read_b64 v[242:243], v168 offset:12800
	s_waitcnt lgkmcnt(2)
	v_mul_f32_e32 v80, s37, v80
	v_mul_f32_e32 v81, s37, v81
	v_fma_f32 v80, v80, v252, v254
	v_fma_f32 v81, v81, v253, v255
	ds_read_b64 v[252:253], v168 offset:5120
	ds_read_b64 v[254:255], v168 offset:13312
	s_waitcnt lgkmcnt(2)
	v_mul_f32_e32 v82, s37, v82
	v_mul_f32_e32 v83, s37, v83
	v_fma_f32 v82, v82, v88, v242
	v_fma_f32 v83, v83, v89, v243
	ds_read_b64 v[88:89], v168 offset:5632
	ds_read_b64 v[242:243], v168 offset:13824
	s_waitcnt lgkmcnt(2)
	v_mul_f32_e32 v84, s37, v84
	v_mul_f32_e32 v85, s37, v85
	v_fma_f32 v84, v84, v252, v254
	v_fma_f32 v85, v85, v253, v255
	ds_read_b64 v[252:253], v168 offset:6144
	ds_read_b64 v[254:255], v168 offset:14336
	s_waitcnt lgkmcnt(2)
	v_mul_f32_e32 v86, s37, v86
	v_mul_f32_e32 v87, s37, v87
	v_fma_f32 v86, v86, v88, v242
	v_fma_f32 v87, v87, v89, v243
	v_cvt_pk_bf16_f32 v80, v80, v81
	v_cvt_pk_bf16_f32 v81, v82, v83
	v_cvt_pk_bf16_f32 v82, v84, v85
	v_cvt_pk_bf16_f32 v83, v86, v87
	global_store_dwordx4 v90, v[80:83], s[12:13] offset:2048
	ds_read_b64 v[88:89], v168 offset:6656
	ds_read_b64 v[242:243], v168 offset:14848
	s_waitcnt lgkmcnt(2)
	v_mul_f32_e32 v244, s37, v244
	v_mul_f32_e32 v245, s37, v245
	v_fma_f32 v244, v244, v252, v254
	v_fma_f32 v245, v245, v253, v255
	ds_read_b64 v[252:253], v168 offset:7168
	ds_read_b64 v[254:255], v168 offset:15360
	s_waitcnt lgkmcnt(2)
	v_mul_f32_e32 v246, s37, v246
	v_mul_f32_e32 v247, s37, v247
	v_fma_f32 v246, v246, v88, v242
	v_fma_f32 v247, v247, v89, v243
	ds_read_b64 v[88:89], v168 offset:7680
	ds_read_b64 v[242:243], v168 offset:15872
	s_waitcnt lgkmcnt(2)
	v_mul_f32_e32 v248, s37, v248
	v_mul_f32_e32 v249, s37, v249
	v_fma_f32 v248, v248, v252, v254
	v_fma_f32 v249, v249, v253, v255
	s_waitcnt lgkmcnt(0)
	v_mul_f32_e32 v250, s37, v250
	v_mul_f32_e32 v251, s37, v251
	v_fma_f32 v250, v250, v88, v242
	v_fma_f32 v251, v251, v89, v243
	v_cvt_pk_bf16_f32 v244, v244, v245
	v_cvt_pk_bf16_f32 v245, v246, v247
	v_cvt_pk_bf16_f32 v246, v248, v249
	v_cvt_pk_bf16_f32 v247, v250, v251
	global_store_dwordx4 v90, v[244:247], s[12:13] offset:3072
	v_readlane_b32 s38, v241, 0
	s_lshl_b32 s30, s38, 14
	v_subrev_u32_e32 v90, s30, v90
	s_waitcnt vmcnt(4)
	v_lshlrev_b32_e32 v64, 16, v16
	v_and_b32_e32 v65, 0xffff0000, v16
	v_lshlrev_b32_e32 v66, 16, v17
	v_and_b32_e32 v67, 0xffff0000, v17
	v_lshlrev_b32_e32 v68, 16, v18
	v_and_b32_e32 v69, 0xffff0000, v18
	v_lshlrev_b32_e32 v70, 16, v19
	v_and_b32_e32 v71, 0xffff0000, v19
	v_lshlrev_b32_e32 v72, 16, v20
	v_and_b32_e32 v73, 0xffff0000, v20
	v_lshlrev_b32_e32 v74, 16, v21
	v_and_b32_e32 v75, 0xffff0000, v21
	v_lshlrev_b32_e32 v76, 16, v22
	v_and_b32_e32 v77, 0xffff0000, v22
	v_lshlrev_b32_e32 v78, 16, v23
	v_and_b32_e32 v79, 0xffff0000, v23
	v_lshlrev_b32_e32 v80, 16, v24
	v_and_b32_e32 v81, 0xffff0000, v24
	v_lshlrev_b32_e32 v82, 16, v25
	v_and_b32_e32 v83, 0xffff0000, v25
	v_lshlrev_b32_e32 v84, 16, v26
	v_and_b32_e32 v85, 0xffff0000, v26
	v_lshlrev_b32_e32 v86, 16, v27
	v_and_b32_e32 v87, 0xffff0000, v27
	v_lshlrev_b32_e32 v244, 16, v28
	v_and_b32_e32 v245, 0xffff0000, v28
	v_lshlrev_b32_e32 v246, 16, v29
	v_and_b32_e32 v247, 0xffff0000, v29
	v_lshlrev_b32_e32 v248, 16, v30
	v_and_b32_e32 v249, 0xffff0000, v30
	v_lshlrev_b32_e32 v250, 16, v31
	v_and_b32_e32 v251, 0xffff0000, v31
	s_add_u32 s12, s8, 0xc00000
	s_addc_u32 s13, s9, 0
	global_load_dwordx4 v[16:19], v90, s[12:13]
	global_load_dwordx4 v[20:23], v90, s[12:13] offset:1024
	global_load_dwordx4 v[24:27], v90, s[12:13] offset:2048
	global_load_dwordx4 v[28:31], v90, s[12:13] offset:3072
	v_lshlrev_b32_e32 v252, 16, v32
	v_and_b32_e32 v253, 0xffff0000, v32
	v_add_f32_e32 v64, v64, v252
	v_add_f32_e32 v65, v65, v253
	v_lshlrev_b32_e32 v252, 16, v33
	v_and_b32_e32 v253, 0xffff0000, v33
	v_add_f32_e32 v66, v66, v252
	v_add_f32_e32 v67, v67, v253
	v_lshlrev_b32_e32 v252, 16, v34
	v_and_b32_e32 v253, 0xffff0000, v34
	v_add_f32_e32 v68, v68, v252
	v_add_f32_e32 v69, v69, v253
	v_lshlrev_b32_e32 v252, 16, v35
	v_and_b32_e32 v253, 0xffff0000, v35
	v_add_f32_e32 v70, v70, v252
	v_add_f32_e32 v71, v71, v253
	v_lshlrev_b32_e32 v252, 16, v36
	v_and_b32_e32 v253, 0xffff0000, v36
	v_add_f32_e32 v72, v72, v252
	v_add_f32_e32 v73, v73, v253
	v_lshlrev_b32_e32 v252, 16, v37
	v_and_b32_e32 v253, 0xffff0000, v37
	v_add_f32_e32 v74, v74, v252
	v_add_f32_e32 v75, v75, v253
	v_lshlrev_b32_e32 v252, 16, v38
	v_and_b32_e32 v253, 0xffff0000, v38
	v_add_f32_e32 v76, v76, v252
	v_add_f32_e32 v77, v77, v253
	v_lshlrev_b32_e32 v252, 16, v39
	v_and_b32_e32 v253, 0xffff0000, v39
	v_add_f32_e32 v78, v78, v252
	v_add_f32_e32 v79, v79, v253
	v_lshlrev_b32_e32 v252, 16, v40
	v_and_b32_e32 v253, 0xffff0000, v40
	v_add_f32_e32 v80, v80, v252
	v_add_f32_e32 v81, v81, v253
	v_lshlrev_b32_e32 v252, 16, v41
	v_and_b32_e32 v253, 0xffff0000, v41
	v_add_f32_e32 v82, v82, v252
	v_add_f32_e32 v83, v83, v253
	v_lshlrev_b32_e32 v252, 16, v42
	v_and_b32_e32 v253, 0xffff0000, v42
	v_add_f32_e32 v84, v84, v252
	v_add_f32_e32 v85, v85, v253
	v_lshlrev_b32_e32 v252, 16, v43
	v_and_b32_e32 v253, 0xffff0000, v43
	v_add_f32_e32 v86, v86, v252
	v_add_f32_e32 v87, v87, v253
	v_lshlrev_b32_e32 v252, 16, v44
	v_and_b32_e32 v253, 0xffff0000, v44
	v_add_f32_e32 v244, v244, v252
	v_add_f32_e32 v245, v245, v253
	v_lshlrev_b32_e32 v252, 16, v45
	v_and_b32_e32 v253, 0xffff0000, v45
	v_add_f32_e32 v246, v246, v252
	v_add_f32_e32 v247, v247, v253
	v_lshlrev_b32_e32 v252, 16, v46
	v_and_b32_e32 v253, 0xffff0000, v46
	v_add_f32_e32 v248, v248, v252
	v_add_f32_e32 v249, v249, v253
	v_lshlrev_b32_e32 v252, 16, v47
	v_and_b32_e32 v253, 0xffff0000, v47
	v_add_f32_e32 v250, v250, v252
	v_add_f32_e32 v251, v251, v253
	s_add_u32 s12, s8, 0x1000000
	s_addc_u32 s13, s9, 0
	global_load_dwordx4 v[32:35], v90, s[12:13]
	global_load_dwordx4 v[36:39], v90, s[12:13] offset:1024
	global_load_dwordx4 v[40:43], v90, s[12:13] offset:2048
	global_load_dwordx4 v[44:47], v90, s[12:13] offset:3072
	v_lshlrev_b32_e32 v252, 16, v48
	v_and_b32_e32 v253, 0xffff0000, v48
	v_add_f32_e32 v64, v64, v252
	v_add_f32_e32 v65, v65, v253
	v_lshlrev_b32_e32 v252, 16, v49
	v_and_b32_e32 v253, 0xffff0000, v49
	v_add_f32_e32 v66, v66, v252
	v_add_f32_e32 v67, v67, v253
	v_lshlrev_b32_e32 v252, 16, v50
	v_and_b32_e32 v253, 0xffff0000, v50
	v_add_f32_e32 v68, v68, v252
	v_add_f32_e32 v69, v69, v253
	v_lshlrev_b32_e32 v252, 16, v51
	v_and_b32_e32 v253, 0xffff0000, v51
	v_add_f32_e32 v70, v70, v252
	v_add_f32_e32 v71, v71, v253
	v_lshlrev_b32_e32 v252, 16, v52
	v_and_b32_e32 v253, 0xffff0000, v52
	v_add_f32_e32 v72, v72, v252
	v_add_f32_e32 v73, v73, v253
	v_lshlrev_b32_e32 v252, 16, v53
	v_and_b32_e32 v253, 0xffff0000, v53
	v_add_f32_e32 v74, v74, v252
	v_add_f32_e32 v75, v75, v253
	v_lshlrev_b32_e32 v252, 16, v54
	v_and_b32_e32 v253, 0xffff0000, v54
	v_add_f32_e32 v76, v76, v252
	v_add_f32_e32 v77, v77, v253
	v_lshlrev_b32_e32 v252, 16, v55
	v_and_b32_e32 v253, 0xffff0000, v55
	v_add_f32_e32 v78, v78, v252
	v_add_f32_e32 v79, v79, v253
	v_lshlrev_b32_e32 v252, 16, v56
	v_and_b32_e32 v253, 0xffff0000, v56
	v_add_f32_e32 v80, v80, v252
	v_add_f32_e32 v81, v81, v253
	v_lshlrev_b32_e32 v252, 16, v57
	v_and_b32_e32 v253, 0xffff0000, v57
	v_add_f32_e32 v82, v82, v252
	v_add_f32_e32 v83, v83, v253
	v_lshlrev_b32_e32 v252, 16, v58
	v_and_b32_e32 v253, 0xffff0000, v58
	v_add_f32_e32 v84, v84, v252
	v_add_f32_e32 v85, v85, v253
	v_lshlrev_b32_e32 v252, 16, v59
	v_and_b32_e32 v253, 0xffff0000, v59
	v_add_f32_e32 v86, v86, v252
	v_add_f32_e32 v87, v87, v253
	v_lshlrev_b32_e32 v252, 16, v60
	v_and_b32_e32 v253, 0xffff0000, v60
	v_add_f32_e32 v244, v244, v252
	v_add_f32_e32 v245, v245, v253
	v_lshlrev_b32_e32 v252, 16, v61
	v_and_b32_e32 v253, 0xffff0000, v61
	v_add_f32_e32 v246, v246, v252
	v_add_f32_e32 v247, v247, v253
	v_lshlrev_b32_e32 v252, 16, v62
	v_and_b32_e32 v253, 0xffff0000, v62
	v_add_f32_e32 v248, v248, v252
	v_add_f32_e32 v249, v249, v253
	v_lshlrev_b32_e32 v252, 16, v63
	v_and_b32_e32 v253, 0xffff0000, v63
	v_add_f32_e32 v250, v250, v252
	v_add_f32_e32 v251, v251, v253
	s_add_u32 s12, s8, 0x1400000
	s_addc_u32 s13, s9, 0
	global_load_dwordx4 v[48:51], v90, s[12:13]
	global_load_dwordx4 v[52:55], v90, s[12:13] offset:1024
	global_load_dwordx4 v[56:59], v90, s[12:13] offset:2048
	global_load_dwordx4 v[60:63], v90, s[12:13] offset:3072
	s_waitcnt vmcnt(8)
	v_lshlrev_b32_e32 v252, 16, v16
	v_and_b32_e32 v253, 0xffff0000, v16
	v_add_f32_e32 v64, v64, v252
	v_add_f32_e32 v65, v65, v253
	v_lshlrev_b32_e32 v252, 16, v17
	v_and_b32_e32 v253, 0xffff0000, v17
	v_add_f32_e32 v66, v66, v252
	v_add_f32_e32 v67, v67, v253
	v_lshlrev_b32_e32 v252, 16, v18
	v_and_b32_e32 v253, 0xffff0000, v18
	v_add_f32_e32 v68, v68, v252
	v_add_f32_e32 v69, v69, v253
	v_lshlrev_b32_e32 v252, 16, v19
	v_and_b32_e32 v253, 0xffff0000, v19
	v_add_f32_e32 v70, v70, v252
	v_add_f32_e32 v71, v71, v253
	v_lshlrev_b32_e32 v252, 16, v20
	v_and_b32_e32 v253, 0xffff0000, v20
	v_add_f32_e32 v72, v72, v252
	v_add_f32_e32 v73, v73, v253
	v_lshlrev_b32_e32 v252, 16, v21
	v_and_b32_e32 v253, 0xffff0000, v21
	v_add_f32_e32 v74, v74, v252
	v_add_f32_e32 v75, v75, v253
	v_lshlrev_b32_e32 v252, 16, v22
	v_and_b32_e32 v253, 0xffff0000, v22
	v_add_f32_e32 v76, v76, v252
	v_add_f32_e32 v77, v77, v253
	v_lshlrev_b32_e32 v252, 16, v23
	v_and_b32_e32 v253, 0xffff0000, v23
	v_add_f32_e32 v78, v78, v252
	v_add_f32_e32 v79, v79, v253
	v_lshlrev_b32_e32 v252, 16, v24
	v_and_b32_e32 v253, 0xffff0000, v24
	v_add_f32_e32 v80, v80, v252
	v_add_f32_e32 v81, v81, v253
	v_lshlrev_b32_e32 v252, 16, v25
	v_and_b32_e32 v253, 0xffff0000, v25
	v_add_f32_e32 v82, v82, v252
	v_add_f32_e32 v83, v83, v253
	v_lshlrev_b32_e32 v252, 16, v26
	v_and_b32_e32 v253, 0xffff0000, v26
	v_add_f32_e32 v84, v84, v252
	v_add_f32_e32 v85, v85, v253
	v_lshlrev_b32_e32 v252, 16, v27
	v_and_b32_e32 v253, 0xffff0000, v27
	v_add_f32_e32 v86, v86, v252
	v_add_f32_e32 v87, v87, v253
	v_lshlrev_b32_e32 v252, 16, v28
	v_and_b32_e32 v253, 0xffff0000, v28
	v_add_f32_e32 v244, v244, v252
	v_add_f32_e32 v245, v245, v253
	v_lshlrev_b32_e32 v252, 16, v29
	v_and_b32_e32 v253, 0xffff0000, v29
	v_add_f32_e32 v246, v246, v252
	v_add_f32_e32 v247, v247, v253
	v_lshlrev_b32_e32 v252, 16, v30
	v_and_b32_e32 v253, 0xffff0000, v30
	v_add_f32_e32 v248, v248, v252
	v_add_f32_e32 v249, v249, v253
	v_lshlrev_b32_e32 v252, 16, v31
	v_and_b32_e32 v253, 0xffff0000, v31
	v_add_f32_e32 v250, v250, v252
	v_add_f32_e32 v251, v251, v253
	s_add_u32 s12, s8, 0x1800000
	s_addc_u32 s13, s9, 0
	global_load_dwordx4 v[16:19], v90, s[12:13]
	global_load_dwordx4 v[20:23], v90, s[12:13] offset:1024
	global_load_dwordx4 v[24:27], v90, s[12:13] offset:2048
	global_load_dwordx4 v[28:31], v90, s[12:13] offset:3072
	s_waitcnt vmcnt(8)
	v_lshlrev_b32_e32 v252, 16, v32
	v_and_b32_e32 v253, 0xffff0000, v32
	v_add_f32_e32 v64, v64, v252
	v_add_f32_e32 v65, v65, v253
	v_lshlrev_b32_e32 v252, 16, v33
	v_and_b32_e32 v253, 0xffff0000, v33
	v_add_f32_e32 v66, v66, v252
	v_add_f32_e32 v67, v67, v253
	v_lshlrev_b32_e32 v252, 16, v34
	v_and_b32_e32 v253, 0xffff0000, v34
	v_add_f32_e32 v68, v68, v252
	v_add_f32_e32 v69, v69, v253
	v_lshlrev_b32_e32 v252, 16, v35
	v_and_b32_e32 v253, 0xffff0000, v35
	v_add_f32_e32 v70, v70, v252
	v_add_f32_e32 v71, v71, v253
	v_lshlrev_b32_e32 v252, 16, v36
	v_and_b32_e32 v253, 0xffff0000, v36
	v_add_f32_e32 v72, v72, v252
	v_add_f32_e32 v73, v73, v253
	v_lshlrev_b32_e32 v252, 16, v37
	v_and_b32_e32 v253, 0xffff0000, v37
	v_add_f32_e32 v74, v74, v252
	v_add_f32_e32 v75, v75, v253
	v_lshlrev_b32_e32 v252, 16, v38
	v_and_b32_e32 v253, 0xffff0000, v38
	v_add_f32_e32 v76, v76, v252
	v_add_f32_e32 v77, v77, v253
	v_lshlrev_b32_e32 v252, 16, v39
	v_and_b32_e32 v253, 0xffff0000, v39
	v_add_f32_e32 v78, v78, v252
	v_add_f32_e32 v79, v79, v253
	v_lshlrev_b32_e32 v252, 16, v40
	v_and_b32_e32 v253, 0xffff0000, v40
	v_add_f32_e32 v80, v80, v252
	v_add_f32_e32 v81, v81, v253
	v_lshlrev_b32_e32 v252, 16, v41
	v_and_b32_e32 v253, 0xffff0000, v41
	v_add_f32_e32 v82, v82, v252
	v_add_f32_e32 v83, v83, v253
	v_lshlrev_b32_e32 v252, 16, v42
	v_and_b32_e32 v253, 0xffff0000, v42
	v_add_f32_e32 v84, v84, v252
	v_add_f32_e32 v85, v85, v253
	v_lshlrev_b32_e32 v252, 16, v43
	v_and_b32_e32 v253, 0xffff0000, v43
	v_add_f32_e32 v86, v86, v252
	v_add_f32_e32 v87, v87, v253
	v_lshlrev_b32_e32 v252, 16, v44
	v_and_b32_e32 v253, 0xffff0000, v44
	v_add_f32_e32 v244, v244, v252
	v_add_f32_e32 v245, v245, v253
	v_lshlrev_b32_e32 v252, 16, v45
	v_and_b32_e32 v253, 0xffff0000, v45
	v_add_f32_e32 v246, v246, v252
	v_add_f32_e32 v247, v247, v253
	v_lshlrev_b32_e32 v252, 16, v46
	v_and_b32_e32 v253, 0xffff0000, v46
	v_add_f32_e32 v248, v248, v252
	v_add_f32_e32 v249, v249, v253
	v_lshlrev_b32_e32 v252, 16, v47
	v_and_b32_e32 v253, 0xffff0000, v47
	v_add_f32_e32 v250, v250, v252
	v_add_f32_e32 v251, v251, v253
	s_add_u32 s12, s8, 0x1c00000
	s_addc_u32 s13, s9, 0
	global_load_dwordx4 v[32:35], v90, s[12:13]
	global_load_dwordx4 v[36:39], v90, s[12:13] offset:1024
	global_load_dwordx4 v[40:43], v90, s[12:13] offset:2048
	global_load_dwordx4 v[44:47], v90, s[12:13] offset:3072
	s_waitcnt vmcnt(8)
	v_lshlrev_b32_e32 v252, 16, v48
	v_and_b32_e32 v253, 0xffff0000, v48
	v_add_f32_e32 v64, v64, v252
	v_add_f32_e32 v65, v65, v253
	v_lshlrev_b32_e32 v252, 16, v49
	v_and_b32_e32 v253, 0xffff0000, v49
	v_add_f32_e32 v66, v66, v252
	v_add_f32_e32 v67, v67, v253
	v_lshlrev_b32_e32 v252, 16, v50
	v_and_b32_e32 v253, 0xffff0000, v50
	v_add_f32_e32 v68, v68, v252
	v_add_f32_e32 v69, v69, v253
	v_lshlrev_b32_e32 v252, 16, v51
	v_and_b32_e32 v253, 0xffff0000, v51
	v_add_f32_e32 v70, v70, v252
	v_add_f32_e32 v71, v71, v253
	v_lshlrev_b32_e32 v252, 16, v52
	v_and_b32_e32 v253, 0xffff0000, v52
	v_add_f32_e32 v72, v72, v252
	v_add_f32_e32 v73, v73, v253
	v_lshlrev_b32_e32 v252, 16, v53
	v_and_b32_e32 v253, 0xffff0000, v53
	v_add_f32_e32 v74, v74, v252
	v_add_f32_e32 v75, v75, v253
	v_lshlrev_b32_e32 v252, 16, v54
	v_and_b32_e32 v253, 0xffff0000, v54
	v_add_f32_e32 v76, v76, v252
	v_add_f32_e32 v77, v77, v253
	v_lshlrev_b32_e32 v252, 16, v55
	v_and_b32_e32 v253, 0xffff0000, v55
	v_add_f32_e32 v78, v78, v252
	v_add_f32_e32 v79, v79, v253
	v_lshlrev_b32_e32 v252, 16, v56
	v_and_b32_e32 v253, 0xffff0000, v56
	v_add_f32_e32 v80, v80, v252
	v_add_f32_e32 v81, v81, v253
	v_lshlrev_b32_e32 v252, 16, v57
	v_and_b32_e32 v253, 0xffff0000, v57
	v_add_f32_e32 v82, v82, v252
	v_add_f32_e32 v83, v83, v253
	v_lshlrev_b32_e32 v252, 16, v58
	v_and_b32_e32 v253, 0xffff0000, v58
	v_add_f32_e32 v84, v84, v252
	v_add_f32_e32 v85, v85, v253
	v_lshlrev_b32_e32 v252, 16, v59
	v_and_b32_e32 v253, 0xffff0000, v59
	v_add_f32_e32 v86, v86, v252
	v_add_f32_e32 v87, v87, v253
	v_lshlrev_b32_e32 v252, 16, v60
	v_and_b32_e32 v253, 0xffff0000, v60
	v_add_f32_e32 v244, v244, v252
	v_add_f32_e32 v245, v245, v253
	v_lshlrev_b32_e32 v252, 16, v61
	v_and_b32_e32 v253, 0xffff0000, v61
	v_add_f32_e32 v246, v246, v252
	v_add_f32_e32 v247, v247, v253
	v_lshlrev_b32_e32 v252, 16, v62
	v_and_b32_e32 v253, 0xffff0000, v62
	v_add_f32_e32 v248, v248, v252
	v_add_f32_e32 v249, v249, v253
	v_lshlrev_b32_e32 v252, 16, v63
	v_and_b32_e32 v253, 0xffff0000, v63
	v_add_f32_e32 v250, v250, v252
	v_add_f32_e32 v251, v251, v253
	s_waitcnt vmcnt(4)
	v_lshlrev_b32_e32 v252, 16, v16
	v_and_b32_e32 v253, 0xffff0000, v16
	v_add_f32_e32 v64, v64, v252
	v_add_f32_e32 v65, v65, v253
	v_lshlrev_b32_e32 v252, 16, v17
	v_and_b32_e32 v253, 0xffff0000, v17
	v_add_f32_e32 v66, v66, v252
	v_add_f32_e32 v67, v67, v253
	v_lshlrev_b32_e32 v252, 16, v18
	v_and_b32_e32 v253, 0xffff0000, v18
	v_add_f32_e32 v68, v68, v252
	v_add_f32_e32 v69, v69, v253
	v_lshlrev_b32_e32 v252, 16, v19
	v_and_b32_e32 v253, 0xffff0000, v19
	v_add_f32_e32 v70, v70, v252
	v_add_f32_e32 v71, v71, v253
	v_lshlrev_b32_e32 v252, 16, v20
	v_and_b32_e32 v253, 0xffff0000, v20
	v_add_f32_e32 v72, v72, v252
	v_add_f32_e32 v73, v73, v253
	v_lshlrev_b32_e32 v252, 16, v21
	v_and_b32_e32 v253, 0xffff0000, v21
	v_add_f32_e32 v74, v74, v252
	v_add_f32_e32 v75, v75, v253
	v_lshlrev_b32_e32 v252, 16, v22
	v_and_b32_e32 v253, 0xffff0000, v22
	v_add_f32_e32 v76, v76, v252
	v_add_f32_e32 v77, v77, v253
	v_lshlrev_b32_e32 v252, 16, v23
	v_and_b32_e32 v253, 0xffff0000, v23
	v_add_f32_e32 v78, v78, v252
	v_add_f32_e32 v79, v79, v253
	v_lshlrev_b32_e32 v252, 16, v24
	v_and_b32_e32 v253, 0xffff0000, v24
	v_add_f32_e32 v80, v80, v252
	v_add_f32_e32 v81, v81, v253
	v_lshlrev_b32_e32 v252, 16, v25
	v_and_b32_e32 v253, 0xffff0000, v25
	v_add_f32_e32 v82, v82, v252
	v_add_f32_e32 v83, v83, v253
	v_lshlrev_b32_e32 v252, 16, v26
	v_and_b32_e32 v253, 0xffff0000, v26
	v_add_f32_e32 v84, v84, v252
	v_add_f32_e32 v85, v85, v253
	v_lshlrev_b32_e32 v252, 16, v27
	v_and_b32_e32 v253, 0xffff0000, v27
	v_add_f32_e32 v86, v86, v252
	v_add_f32_e32 v87, v87, v253
	v_lshlrev_b32_e32 v252, 16, v28
	v_and_b32_e32 v253, 0xffff0000, v28
	v_add_f32_e32 v244, v244, v252
	v_add_f32_e32 v245, v245, v253
	v_lshlrev_b32_e32 v252, 16, v29
	v_and_b32_e32 v253, 0xffff0000, v29
	v_add_f32_e32 v246, v246, v252
	v_add_f32_e32 v247, v247, v253
	v_lshlrev_b32_e32 v252, 16, v30
	v_and_b32_e32 v253, 0xffff0000, v30
	v_add_f32_e32 v248, v248, v252
	v_add_f32_e32 v249, v249, v253
	v_lshlrev_b32_e32 v252, 16, v31
	v_and_b32_e32 v253, 0xffff0000, v31
	v_add_f32_e32 v250, v250, v252
	v_add_f32_e32 v251, v251, v253
	s_waitcnt vmcnt(0)
	v_lshlrev_b32_e32 v252, 16, v32
	v_and_b32_e32 v253, 0xffff0000, v32
	v_add_f32_e32 v64, v64, v252
	v_add_f32_e32 v65, v65, v253
	v_lshlrev_b32_e32 v252, 16, v33
	v_and_b32_e32 v253, 0xffff0000, v33
	v_add_f32_e32 v66, v66, v252
	v_add_f32_e32 v67, v67, v253
	v_lshlrev_b32_e32 v252, 16, v34
	v_and_b32_e32 v253, 0xffff0000, v34
	v_add_f32_e32 v68, v68, v252
	v_add_f32_e32 v69, v69, v253
	v_lshlrev_b32_e32 v252, 16, v35
	v_and_b32_e32 v253, 0xffff0000, v35
	v_add_f32_e32 v70, v70, v252
	v_add_f32_e32 v71, v71, v253
	v_lshlrev_b32_e32 v252, 16, v36
	v_and_b32_e32 v253, 0xffff0000, v36
	v_add_f32_e32 v72, v72, v252
	v_add_f32_e32 v73, v73, v253
	v_lshlrev_b32_e32 v252, 16, v37
	v_and_b32_e32 v253, 0xffff0000, v37
	v_add_f32_e32 v74, v74, v252
	v_add_f32_e32 v75, v75, v253
	v_lshlrev_b32_e32 v252, 16, v38
	v_and_b32_e32 v253, 0xffff0000, v38
	v_add_f32_e32 v76, v76, v252
	v_add_f32_e32 v77, v77, v253
	v_lshlrev_b32_e32 v252, 16, v39
	v_and_b32_e32 v253, 0xffff0000, v39
	v_add_f32_e32 v78, v78, v252
	v_add_f32_e32 v79, v79, v253
	v_lshlrev_b32_e32 v252, 16, v40
	v_and_b32_e32 v253, 0xffff0000, v40
	v_add_f32_e32 v80, v80, v252
	v_add_f32_e32 v81, v81, v253
	v_lshlrev_b32_e32 v252, 16, v41
	v_and_b32_e32 v253, 0xffff0000, v41
	v_add_f32_e32 v82, v82, v252
	v_add_f32_e32 v83, v83, v253
	v_lshlrev_b32_e32 v252, 16, v42
	v_and_b32_e32 v253, 0xffff0000, v42
	v_add_f32_e32 v84, v84, v252
	v_add_f32_e32 v85, v85, v253
	v_lshlrev_b32_e32 v252, 16, v43
	v_and_b32_e32 v253, 0xffff0000, v43
	v_add_f32_e32 v86, v86, v252
	v_add_f32_e32 v87, v87, v253
	v_lshlrev_b32_e32 v252, 16, v44
	v_and_b32_e32 v253, 0xffff0000, v44
	v_add_f32_e32 v244, v244, v252
	v_add_f32_e32 v245, v245, v253
	v_lshlrev_b32_e32 v252, 16, v45
	v_and_b32_e32 v253, 0xffff0000, v45
	v_add_f32_e32 v246, v246, v252
	v_add_f32_e32 v247, v247, v253
	v_lshlrev_b32_e32 v252, 16, v46
	v_and_b32_e32 v253, 0xffff0000, v46
	v_add_f32_e32 v248, v248, v252
	v_add_f32_e32 v249, v249, v253
	v_lshlrev_b32_e32 v252, 16, v47
	v_and_b32_e32 v253, 0xffff0000, v47
	v_add_f32_e32 v250, v250, v252
	v_add_f32_e32 v251, v251, v253
	v_and_b32_e32 v252, 0xffff0000, v0
	v_lshlrev_b32_e32 v0, 16, v0
	v_fmac_f32_e32 v64, 0x3fb504f3, v0
	v_fmac_f32_e32 v65, 0x3fb504f3, v252
	v_and_b32_e32 v252, 0xffff0000, v1
	v_lshlrev_b32_e32 v1, 16, v1
	v_fmac_f32_e32 v66, 0x3fb504f3, v1
	v_fmac_f32_e32 v67, 0x3fb504f3, v252
	v_add_f32_e32 v252, v64, v65
	v_add_f32_e32 v253, v66, v67
	v_add_f32_e32 v254, v252, v253
	v_and_b32_e32 v252, 0xffff0000, v2
	v_lshlrev_b32_e32 v2, 16, v2
	v_fmac_f32_e32 v68, 0x3fb504f3, v2
	v_fmac_f32_e32 v69, 0x3fb504f3, v252
	v_and_b32_e32 v252, 0xffff0000, v3
	v_lshlrev_b32_e32 v3, 16, v3
	v_fmac_f32_e32 v70, 0x3fb504f3, v3
	v_fmac_f32_e32 v71, 0x3fb504f3, v252
	v_add_f32_e32 v252, v68, v69
	v_add_f32_e32 v253, v70, v71
	v_add_f32_e32 v252, v252, v253
	v_add_f32_e32 v254, v254, v252
	v_and_b32_e32 v252, 0xffff0000, v4
	v_lshlrev_b32_e32 v4, 16, v4
	v_fmac_f32_e32 v72, 0x3fb504f3, v4
	v_fmac_f32_e32 v73, 0x3fb504f3, v252
	v_and_b32_e32 v252, 0xffff0000, v5
	v_lshlrev_b32_e32 v5, 16, v5
	v_fmac_f32_e32 v74, 0x3fb504f3, v5
	v_fmac_f32_e32 v75, 0x3fb504f3, v252
	v_add_f32_e32 v252, v72, v73
	v_add_f32_e32 v253, v74, v75
	v_add_f32_e32 v252, v252, v253
	v_add_f32_e32 v254, v254, v252
	v_and_b32_e32 v252, 0xffff0000, v6
	v_lshlrev_b32_e32 v6, 16, v6
	v_fmac_f32_e32 v76, 0x3fb504f3, v6
	v_fmac_f32_e32 v77, 0x3fb504f3, v252
	v_and_b32_e32 v252, 0xffff0000, v7
	v_lshlrev_b32_e32 v7, 16, v7
	v_fmac_f32_e32 v78, 0x3fb504f3, v7
	v_fmac_f32_e32 v79, 0x3fb504f3, v252
	v_add_f32_e32 v252, v76, v77
	v_add_f32_e32 v253, v78, v79
	v_add_f32_e32 v252, v252, v253
	v_add_f32_e32 v254, v254, v252
	v_and_b32_e32 v252, 0xffff0000, v8
	v_lshlrev_b32_e32 v8, 16, v8
	v_fmac_f32_e32 v80, 0x3fb504f3, v8
	v_fmac_f32_e32 v81, 0x3fb504f3, v252
	v_and_b32_e32 v252, 0xffff0000, v9
	v_lshlrev_b32_e32 v9, 16, v9
	v_fmac_f32_e32 v82, 0x3fb504f3, v9
	v_fmac_f32_e32 v83, 0x3fb504f3, v252
	v_add_f32_e32 v252, v80, v81
	v_add_f32_e32 v253, v82, v83
	v_add_f32_e32 v252, v252, v253
	v_add_f32_e32 v254, v254, v252
	v_and_b32_e32 v252, 0xffff0000, v10
	v_lshlrev_b32_e32 v10, 16, v10
	v_fmac_f32_e32 v84, 0x3fb504f3, v10
	v_fmac_f32_e32 v85, 0x3fb504f3, v252
	v_and_b32_e32 v252, 0xffff0000, v11
	v_lshlrev_b32_e32 v11, 16, v11
	v_fmac_f32_e32 v86, 0x3fb504f3, v11
	v_fmac_f32_e32 v87, 0x3fb504f3, v252
	v_add_f32_e32 v252, v84, v85
	v_add_f32_e32 v253, v86, v87
	v_add_f32_e32 v252, v252, v253
	v_add_f32_e32 v254, v254, v252
	v_and_b32_e32 v252, 0xffff0000, v12
	v_lshlrev_b32_e32 v12, 16, v12
	v_fmac_f32_e32 v244, 0x3fb504f3, v12
	v_fmac_f32_e32 v245, 0x3fb504f3, v252
	v_and_b32_e32 v252, 0xffff0000, v13
	v_lshlrev_b32_e32 v13, 16, v13
	v_fmac_f32_e32 v246, 0x3fb504f3, v13
	v_fmac_f32_e32 v247, 0x3fb504f3, v252
	v_add_f32_e32 v252, v244, v245
	v_add_f32_e32 v253, v246, v247
	v_add_f32_e32 v252, v252, v253
	v_add_f32_e32 v254, v254, v252
	v_and_b32_e32 v252, 0xffff0000, v14
	v_lshlrev_b32_e32 v14, 16, v14
	v_fmac_f32_e32 v248, 0x3fb504f3, v14
	v_fmac_f32_e32 v249, 0x3fb504f3, v252
	v_and_b32_e32 v252, 0xffff0000, v15
	v_lshlrev_b32_e32 v15, 16, v15
	v_fmac_f32_e32 v250, 0x3fb504f3, v15
	v_fmac_f32_e32 v251, 0x3fb504f3, v252
	v_add_f32_e32 v252, v248, v249
	v_add_f32_e32 v253, v250, v251
	v_add_f32_e32 v252, v252, v253
	v_add_f32_e32 v254, v254, v252
	s_nop 1
	v_add_f32_dpp v252, v254, v254 quad_perm:[1,0,3,2] row_mask:0xf bank_mask:0xf
	s_nop 1
	v_add_f32_dpp v252, v252, v252 quad_perm:[2,3,0,1] row_mask:0xf bank_mask:0xf
	s_nop 1
	v_add_f32_dpp v252, v252, v252 row_half_mirror row_mask:0xf bank_mask:0xf
	s_nop 1
	v_add_f32_dpp v252, v252, v252 row_mirror row_mask:0xf bank_mask:0xf
	s_nop 1
	v_readlane_b32 s40, v252, 0
	v_readlane_b32 s41, v252, 16
	v_readlane_b32 s42, v252, 32
	v_readlane_b32 s43, v252, 48
	s_nop 1
	v_mov_b32_e32 v253, s40
	v_add_f32_e32 v253, s41, v253
	v_add_f32_e32 v253, s42, v253
	v_add_f32_e32 v253, s43, v253
	v_mul_f32_e32 v253, 0x3a000000, v253
	s_nop 0
	v_readfirstlane_b32 s37, v253
	s_nop 1
	v_subrev_f32_e32 v64, s37, v64
	v_subrev_f32_e32 v65, s37, v65
	v_subrev_f32_e32 v66, s37, v66
	v_subrev_f32_e32 v67, s37, v67
	v_subrev_f32_e32 v68, s37, v68
	v_subrev_f32_e32 v69, s37, v69
	v_subrev_f32_e32 v70, s37, v70
	v_subrev_f32_e32 v71, s37, v71
	v_mul_f32_e32 v252, v64, v64
	v_fmac_f32_e32 v252, v65, v65
	v_mul_f32_e32 v253, v66, v66
	v_fmac_f32_e32 v253, v67, v67
	v_add_f32_e32 v254, v252, v253
	v_mul_f32_e32 v252, v68, v68
	v_fmac_f32_e32 v252, v69, v69
	v_mul_f32_e32 v253, v70, v70
	v_fmac_f32_e32 v253, v71, v71
	v_add_f32_e32 v252, v252, v253
	v_add_f32_e32 v254, v254, v252
	v_subrev_f32_e32 v72, s37, v72
	v_subrev_f32_e32 v73, s37, v73
	v_subrev_f32_e32 v74, s37, v74
	v_subrev_f32_e32 v75, s37, v75
	v_subrev_f32_e32 v76, s37, v76
	v_subrev_f32_e32 v77, s37, v77
	v_subrev_f32_e32 v78, s37, v78
	v_subrev_f32_e32 v79, s37, v79
	v_mul_f32_e32 v252, v72, v72
	v_fmac_f32_e32 v252, v73, v73
	v_mul_f32_e32 v253, v74, v74
	v_fmac_f32_e32 v253, v75, v75
	v_add_f32_e32 v252, v252, v253
	v_add_f32_e32 v254, v254, v252
	v_mul_f32_e32 v252, v76, v76
	v_fmac_f32_e32 v252, v77, v77
	v_mul_f32_e32 v253, v78, v78
	v_fmac_f32_e32 v253, v79, v79
	v_add_f32_e32 v252, v252, v253
	v_add_f32_e32 v254, v254, v252
	v_subrev_f32_e32 v80, s37, v80
	v_subrev_f32_e32 v81, s37, v81
	v_subrev_f32_e32 v82, s37, v82
	v_subrev_f32_e32 v83, s37, v83
	v_subrev_f32_e32 v84, s37, v84
	v_subrev_f32_e32 v85, s37, v85
	v_subrev_f32_e32 v86, s37, v86
	v_subrev_f32_e32 v87, s37, v87
	v_mul_f32_e32 v252, v80, v80
	v_fmac_f32_e32 v252, v81, v81
	v_mul_f32_e32 v253, v82, v82
	v_fmac_f32_e32 v253, v83, v83
	v_add_f32_e32 v252, v252, v253
	v_add_f32_e32 v254, v254, v252
	v_mul_f32_e32 v252, v84, v84
	v_fmac_f32_e32 v252, v85, v85
	v_mul_f32_e32 v253, v86, v86
	v_fmac_f32_e32 v253, v87, v87
	v_add_f32_e32 v252, v252, v253
	v_add_f32_e32 v254, v254, v252
	v_subrev_f32_e32 v244, s37, v244
	v_subrev_f32_e32 v245, s37, v245
	v_subrev_f32_e32 v246, s37, v246
	v_subrev_f32_e32 v247, s37, v247
	v_subrev_f32_e32 v248, s37, v248
	v_subrev_f32_e32 v249, s37, v249
	v_subrev_f32_e32 v250, s37, v250
	v_subrev_f32_e32 v251, s37, v251
	v_mul_f32_e32 v252, v244, v244
	v_fmac_f32_e32 v252, v245, v245
	v_mul_f32_e32 v253, v246, v246
	v_fmac_f32_e32 v253, v247, v247
	v_add_f32_e32 v252, v252, v253
	v_add_f32_e32 v254, v254, v252
	v_mul_f32_e32 v252, v248, v248
	v_fmac_f32_e32 v252, v249, v249
	v_mul_f32_e32 v253, v250, v250
	v_fmac_f32_e32 v253, v251, v251
	v_add_f32_e32 v252, v252, v253
	v_add_f32_e32 v254, v254, v252
	s_nop 1
	v_add_f32_dpp v252, v254, v254 quad_perm:[1,0,3,2] row_mask:0xf bank_mask:0xf
	s_nop 1
	v_add_f32_dpp v252, v252, v252 quad_perm:[2,3,0,1] row_mask:0xf bank_mask:0xf
	s_nop 1
	v_add_f32_dpp v252, v252, v252 row_half_mirror row_mask:0xf bank_mask:0xf
	s_nop 1
	v_add_f32_dpp v252, v252, v252 row_mirror row_mask:0xf bank_mask:0xf
	s_nop 1
	v_readlane_b32 s40, v252, 0
	v_readlane_b32 s41, v252, 16
	v_readlane_b32 s42, v252, 32
	v_readlane_b32 s43, v252, 48
	s_nop 1
	v_mov_b32_e32 v253, s40
	v_add_f32_e32 v253, s41, v253
	v_add_f32_e32 v253, s42, v253
	v_add_f32_e32 v253, s43, v253
	v_mov_b32_e32 v252, 0x3a000000
	v_fmaak_f32 v253, v253, v252, 0x3727c5ac
	v_rsq_f32_e32 v253, v253
	s_nop 1
	v_readfirstlane_b32 s37, v253
	s_add_u32 s12, s4, 0x2000000
	s_addc_u32 s13, s5, 0
	ds_read_b64 v[252:253], v168
	ds_read_b64 v[254:255], v168 offset:8192
	ds_read_b64 v[88:89], v168 offset:512
	ds_read_b64 v[242:243], v168 offset:8704
	s_waitcnt lgkmcnt(2)
	v_mul_f32_e32 v64, s37, v64
	v_mul_f32_e32 v65, s37, v65
	v_fma_f32 v64, v64, v252, v254
	v_fma_f32 v65, v65, v253, v255
	ds_read_b64 v[252:253], v168 offset:1024
	ds_read_b64 v[254:255], v168 offset:9216
	s_waitcnt lgkmcnt(2)
	v_mul_f32_e32 v66, s37, v66
	v_mul_f32_e32 v67, s37, v67
	v_fma_f32 v66, v66, v88, v242
	v_fma_f32 v67, v67, v89, v243
	ds_read_b64 v[88:89], v168 offset:1536
	ds_read_b64 v[242:243], v168 offset:9728
	s_waitcnt lgkmcnt(2)
	v_mul_f32_e32 v68, s37, v68
	v_mul_f32_e32 v69, s37, v69
	v_fma_f32 v68, v68, v252, v254
	v_fma_f32 v69, v69, v253, v255
	ds_read_b64 v[252:253], v168 offset:2048
	ds_read_b64 v[254:255], v168 offset:10240
	s_waitcnt lgkmcnt(2)
	v_mul_f32_e32 v70, s37, v70
	v_mul_f32_e32 v71, s37, v71
	v_fma_f32 v70, v70, v88, v242
	v_fma_f32 v71, v71, v89, v243
	v_cvt_pk_bf16_f32 v64, v64, v65
	v_cvt_pk_bf16_f32 v65, v66, v67
	v_cvt_pk_bf16_f32 v66, v68, v69
	v_cvt_pk_bf16_f32 v67, v70, v71
	global_store_dwordx4 v90, v[64:67], s[12:13]
	ds_read_b64 v[88:89], v168 offset:2560
	ds_read_b64 v[242:243], v168 offset:10752
	s_waitcnt lgkmcnt(2)
	v_mul_f32_e32 v72, s37, v72
	v_mul_f32_e32 v73, s37, v73
	v_fma_f32 v72, v72, v252, v254
	v_fma_f32 v73, v73, v253, v255
	ds_read_b64 v[252:253], v168 offset:3072
	ds_read_b64 v[254:255], v168 offset:11264
	s_waitcnt lgkmcnt(2)
	v_mul_f32_e32 v74, s37, v74
	v_mul_f32_e32 v75, s37, v75
	v_fma_f32 v74, v74, v88, v242
	v_fma_f32 v75, v75, v89, v243
	ds_read_b64 v[88:89], v168 offset:3584
	ds_read_b64 v[242:243], v168 offset:11776
	s_waitcnt lgkmcnt(2)
	v_mul_f32_e32 v76, s37, v76
	v_mul_f32_e32 v77, s37, v77
	v_fma_f32 v76, v76, v252, v254
	v_fma_f32 v77, v77, v253, v255
	ds_read_b64 v[252:253], v168 offset:4096
	ds_read_b64 v[254:255], v168 offset:12288
	s_waitcnt lgkmcnt(2)
	v_mul_f32_e32 v78, s37, v78
	v_mul_f32_e32 v79, s37, v79
	v_fma_f32 v78, v78, v88, v242
	v_fma_f32 v79, v79, v89, v243
	v_cvt_pk_bf16_f32 v72, v72, v73
	v_cvt_pk_bf16_f32 v73, v74, v75
	v_cvt_pk_bf16_f32 v74, v76, v77
	v_cvt_pk_bf16_f32 v75, v78, v79
	global_store_dwordx4 v90, v[72:75], s[12:13] offset:1024
	ds_read_b64 v[88:89], v168 offset:4608
	ds_read_b64 v[242:243], v168 offset:12800
	s_waitcnt lgkmcnt(2)
	v_mul_f32_e32 v80, s37, v80
	v_mul_f32_e32 v81, s37, v81
	v_fma_f32 v80, v80, v252, v254
	v_fma_f32 v81, v81, v253, v255
	ds_read_b64 v[252:253], v168 offset:5120
	ds_read_b64 v[254:255], v168 offset:13312
	s_waitcnt lgkmcnt(2)
	v_mul_f32_e32 v82, s37, v82
	v_mul_f32_e32 v83, s37, v83
	v_fma_f32 v82, v82, v88, v242
	v_fma_f32 v83, v83, v89, v243
	ds_read_b64 v[88:89], v168 offset:5632
	ds_read_b64 v[242:243], v168 offset:13824
	s_waitcnt lgkmcnt(2)
	v_mul_f32_e32 v84, s37, v84
	v_mul_f32_e32 v85, s37, v85
	v_fma_f32 v84, v84, v252, v254
	v_fma_f32 v85, v85, v253, v255
	ds_read_b64 v[252:253], v168 offset:6144
	ds_read_b64 v[254:255], v168 offset:14336
	s_waitcnt lgkmcnt(2)
	v_mul_f32_e32 v86, s37, v86
	v_mul_f32_e32 v87, s37, v87
	v_fma_f32 v86, v86, v88, v242
	v_fma_f32 v87, v87, v89, v243
	v_cvt_pk_bf16_f32 v80, v80, v81
	v_cvt_pk_bf16_f32 v81, v82, v83
	v_cvt_pk_bf16_f32 v82, v84, v85
	v_cvt_pk_bf16_f32 v83, v86, v87
	global_store_dwordx4 v90, v[80:83], s[12:13] offset:2048
	ds_read_b64 v[88:89], v168 offset:6656
	ds_read_b64 v[242:243], v168 offset:14848
	s_waitcnt lgkmcnt(2)
	v_mul_f32_e32 v244, s37, v244
	v_mul_f32_e32 v245, s37, v245
	v_fma_f32 v244, v244, v252, v254
	v_fma_f32 v245, v245, v253, v255
	ds_read_b64 v[252:253], v168 offset:7168
	ds_read_b64 v[254:255], v168 offset:15360
	s_waitcnt lgkmcnt(2)
	v_mul_f32_e32 v246, s37, v246
	v_mul_f32_e32 v247, s37, v247
	v_fma_f32 v246, v246, v88, v242
	v_fma_f32 v247, v247, v89, v243
	ds_read_b64 v[88:89], v168 offset:7680
	ds_read_b64 v[242:243], v168 offset:15872
	s_waitcnt lgkmcnt(2)
	v_mul_f32_e32 v248, s37, v248
	v_mul_f32_e32 v249, s37, v249
	v_fma_f32 v248, v248, v252, v254
	v_fma_f32 v249, v249, v253, v255
	s_waitcnt lgkmcnt(0)
	v_mul_f32_e32 v250, s37, v250
	v_mul_f32_e32 v251, s37, v251
	v_fma_f32 v250, v250, v88, v242
	v_fma_f32 v251, v251, v89, v243
	v_cvt_pk_bf16_f32 v244, v244, v245
	v_cvt_pk_bf16_f32 v245, v246, v247
	v_cvt_pk_bf16_f32 v246, v248, v249
	v_cvt_pk_bf16_f32 v247, v250, v251
	global_store_dwordx4 v90, v[244:247], s[12:13] offset:3072
	s_branch .LBB0_1118
.Lln1_hi_1:
	global_load_dwordx4 v[0:3], v90, s[4:5]
	global_load_dwordx4 v[4:7], v90, s[4:5] offset:1024
	global_load_dwordx4 v[8:11], v90, s[4:5] offset:2048
	global_load_dwordx4 v[12:15], v90, s[4:5] offset:3072
	global_load_dwordx4 v[16:19], v90, s[6:7]
	global_load_dwordx4 v[20:23], v90, s[6:7] offset:1024
	global_load_dwordx4 v[24:27], v90, s[6:7] offset:2048
	global_load_dwordx4 v[28:31], v90, s[6:7] offset:3072
	s_add_u32 s12, s4, 0x800000
	s_addc_u32 s13, s5, 0
	global_load_dwordx4 v[32:35], v90, s[12:13]
	global_load_dwordx4 v[36:39], v90, s[12:13] offset:1024
	global_load_dwordx4 v[40:43], v90, s[12:13] offset:2048
	global_load_dwordx4 v[44:47], v90, s[12:13] offset:3072
	s_add_u32 s12, s6, 0x800000
	s_addc_u32 s13, s7, 0
	global_load_dwordx4 v[48:51], v90, s[12:13]
	global_load_dwordx4 v[52:55], v90, s[12:13] offset:1024
	global_load_dwordx4 v[56:59], v90, s[12:13] offset:2048
	global_load_dwordx4 v[60:63], v90, s[12:13] offset:3072
	s_waitcnt vmcnt(8)
	v_lshlrev_b32_e32 v64, 16, v16
	v_and_b32_e32 v65, 0xffff0000, v16
	v_and_b32_e32 v252, 0xffff0000, v0
	v_lshlrev_b32_e32 v0, 16, v0
	v_fmac_f32_e32 v64, 0x3fb504f3, v0
	v_fmac_f32_e32 v65, 0x3fb504f3, v252
	v_lshlrev_b32_e32 v66, 16, v17
	v_and_b32_e32 v67, 0xffff0000, v17
	v_and_b32_e32 v252, 0xffff0000, v1
	v_lshlrev_b32_e32 v1, 16, v1
	v_fmac_f32_e32 v66, 0x3fb504f3, v1
	v_fmac_f32_e32 v67, 0x3fb504f3, v252
	v_add_f32_e32 v252, v64, v65
	v_add_f32_e32 v253, v66, v67
	v_add_f32_e32 v254, v252, v253
	v_lshlrev_b32_e32 v68, 16, v18
	v_and_b32_e32 v69, 0xffff0000, v18
	v_and_b32_e32 v252, 0xffff0000, v2
	v_lshlrev_b32_e32 v2, 16, v2
	v_fmac_f32_e32 v68, 0x3fb504f3, v2
	v_fmac_f32_e32 v69, 0x3fb504f3, v252
	v_lshlrev_b32_e32 v70, 16, v19
	v_and_b32_e32 v71, 0xffff0000, v19
	v_and_b32_e32 v252, 0xffff0000, v3
	v_lshlrev_b32_e32 v3, 16, v3
	v_fmac_f32_e32 v70, 0x3fb504f3, v3
	v_fmac_f32_e32 v71, 0x3fb504f3, v252
	v_add_f32_e32 v252, v68, v69
	v_add_f32_e32 v253, v70, v71
	v_add_f32_e32 v252, v252, v253
	v_add_f32_e32 v254, v254, v252
	v_lshlrev_b32_e32 v72, 16, v20
	v_and_b32_e32 v73, 0xffff0000, v20
	v_and_b32_e32 v252, 0xffff0000, v4
	v_lshlrev_b32_e32 v4, 16, v4
	v_fmac_f32_e32 v72, 0x3fb504f3, v4
	v_fmac_f32_e32 v73, 0x3fb504f3, v252
	v_lshlrev_b32_e32 v74, 16, v21
	v_and_b32_e32 v75, 0xffff0000, v21
	v_and_b32_e32 v252, 0xffff0000, v5
	v_lshlrev_b32_e32 v5, 16, v5
	v_fmac_f32_e32 v74, 0x3fb504f3, v5
	v_fmac_f32_e32 v75, 0x3fb504f3, v252
	v_add_f32_e32 v252, v72, v73
	v_add_f32_e32 v253, v74, v75
	v_add_f32_e32 v252, v252, v253
	v_add_f32_e32 v254, v254, v252
	v_lshlrev_b32_e32 v76, 16, v22
	v_and_b32_e32 v77, 0xffff0000, v22
	v_and_b32_e32 v252, 0xffff0000, v6
	v_lshlrev_b32_e32 v6, 16, v6
	v_fmac_f32_e32 v76, 0x3fb504f3, v6
	v_fmac_f32_e32 v77, 0x3fb504f3, v252
	v_lshlrev_b32_e32 v78, 16, v23
	v_and_b32_e32 v79, 0xffff0000, v23
	v_and_b32_e32 v252, 0xffff0000, v7
	v_lshlrev_b32_e32 v7, 16, v7
	v_fmac_f32_e32 v78, 0x3fb504f3, v7
	v_fmac_f32_e32 v79, 0x3fb504f3, v252
	v_add_f32_e32 v252, v76, v77
	v_add_f32_e32 v253, v78, v79
	v_add_f32_e32 v252, v252, v253
	v_add_f32_e32 v254, v254, v252
	v_lshlrev_b32_e32 v80, 16, v24
	v_and_b32_e32 v81, 0xffff0000, v24
	v_and_b32_e32 v252, 0xffff0000, v8
	v_lshlrev_b32_e32 v8, 16, v8
	v_fmac_f32_e32 v80, 0x3fb504f3, v8
	v_fmac_f32_e32 v81, 0x3fb504f3, v252
	v_lshlrev_b32_e32 v82, 16, v25
	v_and_b32_e32 v83, 0xffff0000, v25
	v_and_b32_e32 v252, 0xffff0000, v9
	v_lshlrev_b32_e32 v9, 16, v9
	v_fmac_f32_e32 v82, 0x3fb504f3, v9
	v_fmac_f32_e32 v83, 0x3fb504f3, v252
	v_add_f32_e32 v252, v80, v81
	v_add_f32_e32 v253, v82, v83
	v_add_f32_e32 v252, v252, v253
	v_add_f32_e32 v254, v254, v252
	v_lshlrev_b32_e32 v84, 16, v26
	v_and_b32_e32 v85, 0xffff0000, v26
	v_and_b32_e32 v252, 0xffff0000, v10
	v_lshlrev_b32_e32 v10, 16, v10
	v_fmac_f32_e32 v84, 0x3fb504f3, v10
	v_fmac_f32_e32 v85, 0x3fb504f3, v252
	v_lshlrev_b32_e32 v86, 16, v27
	v_and_b32_e32 v87, 0xffff0000, v27
	v_and_b32_e32 v252, 0xffff0000, v11
	v_lshlrev_b32_e32 v11, 16, v11
	v_fmac_f32_e32 v86, 0x3fb504f3, v11
	v_fmac_f32_e32 v87, 0x3fb504f3, v252
	v_add_f32_e32 v252, v84, v85
	v_add_f32_e32 v253, v86, v87
	v_add_f32_e32 v252, v252, v253
	v_add_f32_e32 v254, v254, v252
	v_lshlrev_b32_e32 v244, 16, v28
	v_and_b32_e32 v245, 0xffff0000, v28
	v_and_b32_e32 v252, 0xffff0000, v12
	v_lshlrev_b32_e32 v12, 16, v12
	v_fmac_f32_e32 v244, 0x3fb504f3, v12
	v_fmac_f32_e32 v245, 0x3fb504f3, v252
	v_lshlrev_b32_e32 v246, 16, v29
	v_and_b32_e32 v247, 0xffff0000, v29
	v_and_b32_e32 v252, 0xffff0000, v13
	v_lshlrev_b32_e32 v13, 16, v13
	v_fmac_f32_e32 v246, 0x3fb504f3, v13
	v_fmac_f32_e32 v247, 0x3fb504f3, v252
	v_add_f32_e32 v252, v244, v245
	v_add_f32_e32 v253, v246, v247
	v_add_f32_e32 v252, v252, v253
	v_add_f32_e32 v254, v254, v252
	v_lshlrev_b32_e32 v248, 16, v30
	v_and_b32_e32 v249, 0xffff0000, v30
	v_and_b32_e32 v252, 0xffff0000, v14
	v_lshlrev_b32_e32 v14, 16, v14
	v_fmac_f32_e32 v248, 0x3fb504f3, v14
	v_fmac_f32_e32 v249, 0x3fb504f3, v252
	v_lshlrev_b32_e32 v250, 16, v31
	v_and_b32_e32 v251, 0xffff0000, v31
	v_and_b32_e32 v252, 0xffff0000, v15
	v_lshlrev_b32_e32 v15, 16, v15
	v_fmac_f32_e32 v250, 0x3fb504f3, v15
	v_fmac_f32_e32 v251, 0x3fb504f3, v252
	v_add_f32_e32 v252, v248, v249
	v_add_f32_e32 v253, v250, v251
	v_add_f32_e32 v252, v252, v253
	v_add_f32_e32 v254, v254, v252
	s_add_u32 s12, s4, 0x1000000
	s_addc_u32 s13, s5, 0
	global_load_dwordx4 v[0:3], v90, s[12:13]
	global_load_dwordx4 v[4:7], v90, s[12:13] offset:1024
	global_load_dwordx4 v[8:11], v90, s[12:13] offset:2048
	global_load_dwordx4 v[12:15], v90, s[12:13] offset:3072
	s_add_u32 s12, s6, 0x1000000
	s_addc_u32 s13, s7, 0
	global_load_dwordx4 v[16:19], v90, s[12:13]
	global_load_dwordx4 v[20:23], v90, s[12:13] offset:1024
	global_load_dwordx4 v[24:27], v90, s[12:13] offset:2048
	global_load_dwordx4 v[28:31], v90, s[12:13] offset:3072
	s_nop 1
	v_add_f32_dpp v252, v254, v254 quad_perm:[1,0,3,2] row_mask:0xf bank_mask:0xf
	s_nop 1
	v_add_f32_dpp v252, v252, v252 quad_perm:[2,3,0,1] row_mask:0xf bank_mask:0xf
	s_nop 1
	v_add_f32_dpp v252, v252, v252 row_half_mirror row_mask:0xf bank_mask:0xf
	s_nop 1
	v_add_f32_dpp v252, v252, v252 row_mirror row_mask:0xf bank_mask:0xf
	s_nop 1
	v_readlane_b32 s40, v252, 0
	v_readlane_b32 s41, v252, 16
	v_readlane_b32 s42, v252, 32
	v_readlane_b32 s43, v252, 48
	s_nop 1
	v_mov_b32_e32 v253, s40
	v_add_f32_e32 v253, s41, v253
	v_add_f32_e32 v253, s42, v253
	v_add_f32_e32 v253, s43, v253
	v_mul_f32_e32 v253, 0x3a000000, v253
	s_nop 0
	v_readfirstlane_b32 s37, v253
	s_nop 1
	v_subrev_f32_e32 v64, s37, v64
	v_subrev_f32_e32 v65, s37, v65
	v_subrev_f32_e32 v66, s37, v66
	v_subrev_f32_e32 v67, s37, v67
	v_subrev_f32_e32 v68, s37, v68
	v_subrev_f32_e32 v69, s37, v69
	v_subrev_f32_e32 v70, s37, v70
	v_subrev_f32_e32 v71, s37, v71
	v_mul_f32_e32 v252, v64, v64
	v_fmac_f32_e32 v252, v65, v65
	v_mul_f32_e32 v253, v66, v66
	v_fmac_f32_e32 v253, v67, v67
	v_add_f32_e32 v254, v252, v253
	v_mul_f32_e32 v252, v68, v68
	v_fmac_f32_e32 v252, v69, v69
	v_mul_f32_e32 v253, v70, v70
	v_fmac_f32_e32 v253, v71, v71
	v_add_f32_e32 v252, v252, v253
	v_add_f32_e32 v254, v254, v252
	v_subrev_f32_e32 v72, s37, v72
	v_subrev_f32_e32 v73, s37, v73
	v_subrev_f32_e32 v74, s37, v74
	v_subrev_f32_e32 v75, s37, v75
	v_subrev_f32_e32 v76, s37, v76
	v_subrev_f32_e32 v77, s37, v77
	v_subrev_f32_e32 v78, s37, v78
	v_subrev_f32_e32 v79, s37, v79
	v_mul_f32_e32 v252, v72, v72
	v_fmac_f32_e32 v252, v73, v73
	v_mul_f32_e32 v253, v74, v74
	v_fmac_f32_e32 v253, v75, v75
	v_add_f32_e32 v252, v252, v253
	v_add_f32_e32 v254, v254, v252
	v_mul_f32_e32 v252, v76, v76
	v_fmac_f32_e32 v252, v77, v77
	v_mul_f32_e32 v253, v78, v78
	v_fmac_f32_e32 v253, v79, v79
	v_add_f32_e32 v252, v252, v253
	v_add_f32_e32 v254, v254, v252
	v_subrev_f32_e32 v80, s37, v80
	v_subrev_f32_e32 v81, s37, v81
	v_subrev_f32_e32 v82, s37, v82
	v_subrev_f32_e32 v83, s37, v83
	v_subrev_f32_e32 v84, s37, v84
	v_subrev_f32_e32 v85, s37, v85
	v_subrev_f32_e32 v86, s37, v86
	v_subrev_f32_e32 v87, s37, v87
	v_mul_f32_e32 v252, v80, v80
	v_fmac_f32_e32 v252, v81, v81
	v_mul_f32_e32 v253, v82, v82
	v_fmac_f32_e32 v253, v83, v83
	v_add_f32_e32 v252, v252, v253
	v_add_f32_e32 v254, v254, v252
	v_mul_f32_e32 v252, v84, v84
	v_fmac_f32_e32 v252, v85, v85
	v_mul_f32_e32 v253, v86, v86
	v_fmac_f32_e32 v253, v87, v87
	v_add_f32_e32 v252, v252, v253
	v_add_f32_e32 v254, v254, v252
	v_subrev_f32_e32 v244, s37, v244
	v_subrev_f32_e32 v245, s37, v245
	v_subrev_f32_e32 v246, s37, v246
	v_subrev_f32_e32 v247, s37, v247
	v_subrev_f32_e32 v248, s37, v248
	v_subrev_f32_e32 v249, s37, v249
	v_subrev_f32_e32 v250, s37, v250
	v_subrev_f32_e32 v251, s37, v251
	v_mul_f32_e32 v252, v244, v244
	v_fmac_f32_e32 v252, v245, v245
	v_mul_f32_e32 v253, v246, v246
	v_fmac_f32_e32 v253, v247, v247
	v_add_f32_e32 v252, v252, v253
	v_add_f32_e32 v254, v254, v252
	v_mul_f32_e32 v252, v248, v248
	v_fmac_f32_e32 v252, v249, v249
	v_mul_f32_e32 v253, v250, v250
	v_fmac_f32_e32 v253, v251, v251
	v_add_f32_e32 v252, v252, v253
	v_add_f32_e32 v254, v254, v252
	s_nop 1
	v_add_f32_dpp v252, v254, v254 quad_perm:[1,0,3,2] row_mask:0xf bank_mask:0xf
	s_nop 1
	v_add_f32_dpp v252, v252, v252 quad_perm:[2,3,0,1] row_mask:0xf bank_mask:0xf
	s_nop 1
	v_add_f32_dpp v252, v252, v252 row_half_mirror row_mask:0xf bank_mask:0xf
	s_nop 1
	v_add_f32_dpp v252, v252, v252 row_mirror row_mask:0xf bank_mask:0xf
	s_nop 1
	v_readlane_b32 s40, v252, 0
	v_readlane_b32 s41, v252, 16
	v_readlane_b32 s42, v252, 32
	v_readlane_b32 s43, v252, 48
	s_nop 1
	v_mov_b32_e32 v253, s40
	v_add_f32_e32 v253, s41, v253
	v_add_f32_e32 v253, s42, v253
	v_add_f32_e32 v253, s43, v253
	v_mov_b32_e32 v252, 0x3a000000
	v_fmaak_f32 v253, v253, v252, 0x3727c5ac
	v_rsq_f32_e32 v253, v253
	s_nop 1
	v_readfirstlane_b32 s37, v253
	s_mov_b32 s12, s4
	s_mov_b32 s13, s5
	ds_read_b64 v[252:253], v168
	ds_read_b64 v[254:255], v168 offset:8192
	ds_read_b64 v[88:89], v168 offset:512
	ds_read_b64 v[242:243], v168 offset:8704
	s_waitcnt lgkmcnt(2)
	v_mul_f32_e32 v64, s37, v64
	v_mul_f32_e32 v65, s37, v65
	v_fma_f32 v64, v64, v252, v254
	v_fma_f32 v65, v65, v253, v255
	ds_read_b64 v[252:253], v168 offset:1024
	ds_read_b64 v[254:255], v168 offset:9216
	s_waitcnt lgkmcnt(2)
	v_mul_f32_e32 v66, s37, v66
	v_mul_f32_e32 v67, s37, v67
	v_fma_f32 v66, v66, v88, v242
	v_fma_f32 v67, v67, v89, v243
	ds_read_b64 v[88:89], v168 offset:1536
	ds_read_b64 v[242:243], v168 offset:9728
	s_waitcnt lgkmcnt(2)
	v_mul_f32_e32 v68, s37, v68
	v_mul_f32_e32 v69, s37, v69
	v_fma_f32 v68, v68, v252, v254
	v_fma_f32 v69, v69, v253, v255
	ds_read_b64 v[252:253], v168 offset:2048
	ds_read_b64 v[254:255], v168 offset:10240
	s_waitcnt lgkmcnt(2)
	v_mul_f32_e32 v70, s37, v70
	v_mul_f32_e32 v71, s37, v71
	v_fma_f32 v70, v70, v88, v242
	v_fma_f32 v71, v71, v89, v243
	v_cvt_pk_bf16_f32 v64, v64, v65
	v_cvt_pk_bf16_f32 v65, v66, v67
	v_cvt_pk_bf16_f32 v66, v68, v69
	v_cvt_pk_bf16_f32 v67, v70, v71
	global_store_dwordx4 v90, v[64:67], s[12:13]
	ds_read_b64 v[88:89], v168 offset:2560
	ds_read_b64 v[242:243], v168 offset:10752
	s_waitcnt lgkmcnt(2)
	v_mul_f32_e32 v72, s37, v72
	v_mul_f32_e32 v73, s37, v73
	v_fma_f32 v72, v72, v252, v254
	v_fma_f32 v73, v73, v253, v255
	ds_read_b64 v[252:253], v168 offset:3072
	ds_read_b64 v[254:255], v168 offset:11264
	s_waitcnt lgkmcnt(2)
	v_mul_f32_e32 v74, s37, v74
	v_mul_f32_e32 v75, s37, v75
	v_fma_f32 v74, v74, v88, v242
	v_fma_f32 v75, v75, v89, v243
	ds_read_b64 v[88:89], v168 offset:3584
	ds_read_b64 v[242:243], v168 offset:11776
	s_waitcnt lgkmcnt(2)
	v_mul_f32_e32 v76, s37, v76
	v_mul_f32_e32 v77, s37, v77
	v_fma_f32 v76, v76, v252, v254
	v_fma_f32 v77, v77, v253, v255
	ds_read_b64 v[252:253], v168 offset:4096
	ds_read_b64 v[254:255], v168 offset:12288
	s_waitcnt lgkmcnt(2)
	v_mul_f32_e32 v78, s37, v78
	v_mul_f32_e32 v79, s37, v79
	v_fma_f32 v78, v78, v88, v242
	v_fma_f32 v79, v79, v89, v243
	v_cvt_pk_bf16_f32 v72, v72, v73
	v_cvt_pk_bf16_f32 v73, v74, v75
	v_cvt_pk_bf16_f32 v74, v76, v77
	v_cvt_pk_bf16_f32 v75, v78, v79
	global_store_dwordx4 v90, v[72:75], s[12:13] offset:1024
	ds_read_b64 v[88:89], v168 offset:4608
	ds_read_b64 v[242:243], v168 offset:12800
	s_waitcnt lgkmcnt(2)
	v_mul_f32_e32 v80, s37, v80
	v_mul_f32_e32 v81, s37, v81
	v_fma_f32 v80, v80, v252, v254
	v_fma_f32 v81, v81, v253, v255
	ds_read_b64 v[252:253], v168 offset:5120
	ds_read_b64 v[254:255], v168 offset:13312
	s_waitcnt lgkmcnt(2)
	v_mul_f32_e32 v82, s37, v82
	v_mul_f32_e32 v83, s37, v83
	v_fma_f32 v82, v82, v88, v242
	v_fma_f32 v83, v83, v89, v243
	ds_read_b64 v[88:89], v168 offset:5632
	ds_read_b64 v[242:243], v168 offset:13824
	s_waitcnt lgkmcnt(2)
	v_mul_f32_e32 v84, s37, v84
	v_mul_f32_e32 v85, s37, v85
	v_fma_f32 v84, v84, v252, v254
	v_fma_f32 v85, v85, v253, v255
	ds_read_b64 v[252:253], v168 offset:6144
	ds_read_b64 v[254:255], v168 offset:14336
	s_waitcnt lgkmcnt(2)
	v_mul_f32_e32 v86, s37, v86
	v_mul_f32_e32 v87, s37, v87
	v_fma_f32 v86, v86, v88, v242
	v_fma_f32 v87, v87, v89, v243
	v_cvt_pk_bf16_f32 v80, v80, v81
	v_cvt_pk_bf16_f32 v81, v82, v83
	v_cvt_pk_bf16_f32 v82, v84, v85
	v_cvt_pk_bf16_f32 v83, v86, v87
	global_store_dwordx4 v90, v[80:83], s[12:13] offset:2048
	ds_read_b64 v[88:89], v168 offset:6656
	ds_read_b64 v[242:243], v168 offset:14848
	s_waitcnt lgkmcnt(2)
	v_mul_f32_e32 v244, s37, v244
	v_mul_f32_e32 v245, s37, v245
	v_fma_f32 v244, v244, v252, v254
	v_fma_f32 v245, v245, v253, v255
	ds_read_b64 v[252:253], v168 offset:7168
	ds_read_b64 v[254:255], v168 offset:15360
	s_waitcnt lgkmcnt(2)
	v_mul_f32_e32 v246, s37, v246
	v_mul_f32_e32 v247, s37, v247
	v_fma_f32 v246, v246, v88, v242
	v_fma_f32 v247, v247, v89, v243
	ds_read_b64 v[88:89], v168 offset:7680
	ds_read_b64 v[242:243], v168 offset:15872
	s_waitcnt lgkmcnt(2)
	v_mul_f32_e32 v248, s37, v248
	v_mul_f32_e32 v249, s37, v249
	v_fma_f32 v248, v248, v252, v254
	v_fma_f32 v249, v249, v253, v255
	s_waitcnt lgkmcnt(0)
	v_mul_f32_e32 v250, s37, v250
	v_mul_f32_e32 v251, s37, v251
	v_fma_f32 v250, v250, v88, v242
	v_fma_f32 v251, v251, v89, v243
	v_cvt_pk_bf16_f32 v244, v244, v245
	v_cvt_pk_bf16_f32 v245, v246, v247
	v_cvt_pk_bf16_f32 v246, v248, v249
	v_cvt_pk_bf16_f32 v247, v250, v251
	global_store_dwordx4 v90, v[244:247], s[12:13] offset:3072
	s_waitcnt vmcnt(12)
	v_lshlrev_b32_e32 v64, 16, v48
	v_and_b32_e32 v65, 0xffff0000, v48
	v_and_b32_e32 v252, 0xffff0000, v32
	v_lshlrev_b32_e32 v32, 16, v32
	v_fmac_f32_e32 v64, 0x3fb504f3, v32
	v_fmac_f32_e32 v65, 0x3fb504f3, v252
	v_lshlrev_b32_e32 v66, 16, v49
	v_and_b32_e32 v67, 0xffff0000, v49
	v_and_b32_e32 v252, 0xffff0000, v33
	v_lshlrev_b32_e32 v33, 16, v33
	v_fmac_f32_e32 v66, 0x3fb504f3, v33
	v_fmac_f32_e32 v67, 0x3fb504f3, v252
	v_add_f32_e32 v252, v64, v65
	v_add_f32_e32 v253, v66, v67
	v_add_f32_e32 v254, v252, v253
	v_lshlrev_b32_e32 v68, 16, v50
	v_and_b32_e32 v69, 0xffff0000, v50
	v_and_b32_e32 v252, 0xffff0000, v34
	v_lshlrev_b32_e32 v34, 16, v34
	v_fmac_f32_e32 v68, 0x3fb504f3, v34
	v_fmac_f32_e32 v69, 0x3fb504f3, v252
	v_lshlrev_b32_e32 v70, 16, v51
	v_and_b32_e32 v71, 0xffff0000, v51
	v_and_b32_e32 v252, 0xffff0000, v35
	v_lshlrev_b32_e32 v35, 16, v35
	v_fmac_f32_e32 v70, 0x3fb504f3, v35
	v_fmac_f32_e32 v71, 0x3fb504f3, v252
	v_add_f32_e32 v252, v68, v69
	v_add_f32_e32 v253, v70, v71
	v_add_f32_e32 v252, v252, v253
	v_add_f32_e32 v254, v254, v252
	v_lshlrev_b32_e32 v72, 16, v52
	v_and_b32_e32 v73, 0xffff0000, v52
	v_and_b32_e32 v252, 0xffff0000, v36
	v_lshlrev_b32_e32 v36, 16, v36
	v_fmac_f32_e32 v72, 0x3fb504f3, v36
	v_fmac_f32_e32 v73, 0x3fb504f3, v252
	v_lshlrev_b32_e32 v74, 16, v53
	v_and_b32_e32 v75, 0xffff0000, v53
	v_and_b32_e32 v252, 0xffff0000, v37
	v_lshlrev_b32_e32 v37, 16, v37
	v_fmac_f32_e32 v74, 0x3fb504f3, v37
	v_fmac_f32_e32 v75, 0x3fb504f3, v252
	v_add_f32_e32 v252, v72, v73
	v_add_f32_e32 v253, v74, v75
	v_add_f32_e32 v252, v252, v253
	v_add_f32_e32 v254, v254, v252
	v_lshlrev_b32_e32 v76, 16, v54
	v_and_b32_e32 v77, 0xffff0000, v54
	v_and_b32_e32 v252, 0xffff0000, v38
	v_lshlrev_b32_e32 v38, 16, v38
	v_fmac_f32_e32 v76, 0x3fb504f3, v38
	v_fmac_f32_e32 v77, 0x3fb504f3, v252
	v_lshlrev_b32_e32 v78, 16, v55
	v_and_b32_e32 v79, 0xffff0000, v55
	v_and_b32_e32 v252, 0xffff0000, v39
	v_lshlrev_b32_e32 v39, 16, v39
	v_fmac_f32_e32 v78, 0x3fb504f3, v39
	v_fmac_f32_e32 v79, 0x3fb504f3, v252
	v_add_f32_e32 v252, v76, v77
	v_add_f32_e32 v253, v78, v79
	v_add_f32_e32 v252, v252, v253
	v_add_f32_e32 v254, v254, v252
	v_lshlrev_b32_e32 v80, 16, v56
	v_and_b32_e32 v81, 0xffff0000, v56
	v_and_b32_e32 v252, 0xffff0000, v40
	v_lshlrev_b32_e32 v40, 16, v40
	v_fmac_f32_e32 v80, 0x3fb504f3, v40
	v_fmac_f32_e32 v81, 0x3fb504f3, v252
	v_lshlrev_b32_e32 v82, 16, v57
	v_and_b32_e32 v83, 0xffff0000, v57
	v_and_b32_e32 v252, 0xffff0000, v41
	v_lshlrev_b32_e32 v41, 16, v41
	v_fmac_f32_e32 v82, 0x3fb504f3, v41
	v_fmac_f32_e32 v83, 0x3fb504f3, v252
	v_add_f32_e32 v252, v80, v81
	v_add_f32_e32 v253, v82, v83
	v_add_f32_e32 v252, v252, v253
	v_add_f32_e32 v254, v254, v252
	v_lshlrev_b32_e32 v84, 16, v58
	v_and_b32_e32 v85, 0xffff0000, v58
	v_and_b32_e32 v252, 0xffff0000, v42
	v_lshlrev_b32_e32 v42, 16, v42
	v_fmac_f32_e32 v84, 0x3fb504f3, v42
	v_fmac_f32_e32 v85, 0x3fb504f3, v252
	v_lshlrev_b32_e32 v86, 16, v59
	v_and_b32_e32 v87, 0xffff0000, v59
	v_and_b32_e32 v252, 0xffff0000, v43
	v_lshlrev_b32_e32 v43, 16, v43
	v_fmac_f32_e32 v86, 0x3fb504f3, v43
	v_fmac_f32_e32 v87, 0x3fb504f3, v252
	v_add_f32_e32 v252, v84, v85
	v_add_f32_e32 v253, v86, v87
	v_add_f32_e32 v252, v252, v253
	v_add_f32_e32 v254, v254, v252
	v_lshlrev_b32_e32 v244, 16, v60
	v_and_b32_e32 v245, 0xffff0000, v60
	v_and_b32_e32 v252, 0xffff0000, v44
	v_lshlrev_b32_e32 v44, 16, v44
	v_fmac_f32_e32 v244, 0x3fb504f3, v44
	v_fmac_f32_e32 v245, 0x3fb504f3, v252
	v_lshlrev_b32_e32 v246, 16, v61
	v_and_b32_e32 v247, 0xffff0000, v61
	v_and_b32_e32 v252, 0xffff0000, v45
	v_lshlrev_b32_e32 v45, 16, v45
	v_fmac_f32_e32 v246, 0x3fb504f3, v45
	v_fmac_f32_e32 v247, 0x3fb504f3, v252
	v_add_f32_e32 v252, v244, v245
	v_add_f32_e32 v253, v246, v247
	v_add_f32_e32 v252, v252, v253
	v_add_f32_e32 v254, v254, v252
	v_lshlrev_b32_e32 v248, 16, v62
	v_and_b32_e32 v249, 0xffff0000, v62
	v_and_b32_e32 v252, 0xffff0000, v46
	v_lshlrev_b32_e32 v46, 16, v46
	v_fmac_f32_e32 v248, 0x3fb504f3, v46
	v_fmac_f32_e32 v249, 0x3fb504f3, v252
	v_lshlrev_b32_e32 v250, 16, v63
	v_and_b32_e32 v251, 0xffff0000, v63
	v_and_b32_e32 v252, 0xffff0000, v47
	v_lshlrev_b32_e32 v47, 16, v47
	v_fmac_f32_e32 v250, 0x3fb504f3, v47
	v_fmac_f32_e32 v251, 0x3fb504f3, v252
	v_add_f32_e32 v252, v248, v249
	v_add_f32_e32 v253, v250, v251
	v_add_f32_e32 v252, v252, v253
	v_add_f32_e32 v254, v254, v252
	s_add_u32 s12, s4, 0x1800000
	s_addc_u32 s13, s5, 0
	global_load_dwordx4 v[32:35], v90, s[12:13]
	global_load_dwordx4 v[36:39], v90, s[12:13] offset:1024
	global_load_dwordx4 v[40:43], v90, s[12:13] offset:2048
	global_load_dwordx4 v[44:47], v90, s[12:13] offset:3072
	s_add_u32 s12, s6, 0x1800000
	s_addc_u32 s13, s7, 0
	global_load_dwordx4 v[48:51], v90, s[12:13]
	global_load_dwordx4 v[52:55], v90, s[12:13] offset:1024
	global_load_dwordx4 v[56:59], v90, s[12:13] offset:2048
	global_load_dwordx4 v[60:63], v90, s[12:13] offset:3072
	s_nop 1
	v_add_f32_dpp v252, v254, v254 quad_perm:[1,0,3,2] row_mask:0xf bank_mask:0xf
	s_nop 1
	v_add_f32_dpp v252, v252, v252 quad_perm:[2,3,0,1] row_mask:0xf bank_mask:0xf
	s_nop 1
	v_add_f32_dpp v252, v252, v252 row_half_mirror row_mask:0xf bank_mask:0xf
	s_nop 1
	v_add_f32_dpp v252, v252, v252 row_mirror row_mask:0xf bank_mask:0xf
	s_nop 1
	v_readlane_b32 s40, v252, 0
	v_readlane_b32 s41, v252, 16
	v_readlane_b32 s42, v252, 32
	v_readlane_b32 s43, v252, 48
	s_nop 1
	v_mov_b32_e32 v253, s40
	v_add_f32_e32 v253, s41, v253
	v_add_f32_e32 v253, s42, v253
	v_add_f32_e32 v253, s43, v253
	v_mul_f32_e32 v253, 0x3a000000, v253
	s_nop 0
	v_readfirstlane_b32 s37, v253
	s_nop 1
	v_subrev_f32_e32 v64, s37, v64
	v_subrev_f32_e32 v65, s37, v65
	v_subrev_f32_e32 v66, s37, v66
	v_subrev_f32_e32 v67, s37, v67
	v_subrev_f32_e32 v68, s37, v68
	v_subrev_f32_e32 v69, s37, v69
	v_subrev_f32_e32 v70, s37, v70
	v_subrev_f32_e32 v71, s37, v71
	v_mul_f32_e32 v252, v64, v64
	v_fmac_f32_e32 v252, v65, v65
	v_mul_f32_e32 v253, v66, v66
	v_fmac_f32_e32 v253, v67, v67
	v_add_f32_e32 v254, v252, v253
	v_mul_f32_e32 v252, v68, v68
	v_fmac_f32_e32 v252, v69, v69
	v_mul_f32_e32 v253, v70, v70
	v_fmac_f32_e32 v253, v71, v71
	v_add_f32_e32 v252, v252, v253
	v_add_f32_e32 v254, v254, v252
	v_subrev_f32_e32 v72, s37, v72
	v_subrev_f32_e32 v73, s37, v73
	v_subrev_f32_e32 v74, s37, v74
	v_subrev_f32_e32 v75, s37, v75
	v_subrev_f32_e32 v76, s37, v76
	v_subrev_f32_e32 v77, s37, v77
	v_subrev_f32_e32 v78, s37, v78
	v_subrev_f32_e32 v79, s37, v79
	v_mul_f32_e32 v252, v72, v72
	v_fmac_f32_e32 v252, v73, v73
	v_mul_f32_e32 v253, v74, v74
	v_fmac_f32_e32 v253, v75, v75
	v_add_f32_e32 v252, v252, v253
	v_add_f32_e32 v254, v254, v252
	v_mul_f32_e32 v252, v76, v76
	v_fmac_f32_e32 v252, v77, v77
	v_mul_f32_e32 v253, v78, v78
	v_fmac_f32_e32 v253, v79, v79
	v_add_f32_e32 v252, v252, v253
	v_add_f32_e32 v254, v254, v252
	v_subrev_f32_e32 v80, s37, v80
	v_subrev_f32_e32 v81, s37, v81
	v_subrev_f32_e32 v82, s37, v82
	v_subrev_f32_e32 v83, s37, v83
	v_subrev_f32_e32 v84, s37, v84
	v_subrev_f32_e32 v85, s37, v85
	v_subrev_f32_e32 v86, s37, v86
	v_subrev_f32_e32 v87, s37, v87
	v_mul_f32_e32 v252, v80, v80
	v_fmac_f32_e32 v252, v81, v81
	v_mul_f32_e32 v253, v82, v82
	v_fmac_f32_e32 v253, v83, v83
	v_add_f32_e32 v252, v252, v253
	v_add_f32_e32 v254, v254, v252
	v_mul_f32_e32 v252, v84, v84
	v_fmac_f32_e32 v252, v85, v85
	v_mul_f32_e32 v253, v86, v86
	v_fmac_f32_e32 v253, v87, v87
	v_add_f32_e32 v252, v252, v253
	v_add_f32_e32 v254, v254, v252
	v_subrev_f32_e32 v244, s37, v244
	v_subrev_f32_e32 v245, s37, v245
	v_subrev_f32_e32 v246, s37, v246
	v_subrev_f32_e32 v247, s37, v247
	v_subrev_f32_e32 v248, s37, v248
	v_subrev_f32_e32 v249, s37, v249
	v_subrev_f32_e32 v250, s37, v250
	v_subrev_f32_e32 v251, s37, v251
	v_mul_f32_e32 v252, v244, v244
	v_fmac_f32_e32 v252, v245, v245
	v_mul_f32_e32 v253, v246, v246
	v_fmac_f32_e32 v253, v247, v247
	v_add_f32_e32 v252, v252, v253
	v_add_f32_e32 v254, v254, v252
	v_mul_f32_e32 v252, v248, v248
	v_fmac_f32_e32 v252, v249, v249
	v_mul_f32_e32 v253, v250, v250
	v_fmac_f32_e32 v253, v251, v251
	v_add_f32_e32 v252, v252, v253
	v_add_f32_e32 v254, v254, v252
	s_nop 1
	v_add_f32_dpp v252, v254, v254 quad_perm:[1,0,3,2] row_mask:0xf bank_mask:0xf
	s_nop 1
	v_add_f32_dpp v252, v252, v252 quad_perm:[2,3,0,1] row_mask:0xf bank_mask:0xf
	s_nop 1
	v_add_f32_dpp v252, v252, v252 row_half_mirror row_mask:0xf bank_mask:0xf
	s_nop 1
	v_add_f32_dpp v252, v252, v252 row_mirror row_mask:0xf bank_mask:0xf
	s_nop 1
	v_readlane_b32 s40, v252, 0
	v_readlane_b32 s41, v252, 16
	v_readlane_b32 s42, v252, 32
	v_readlane_b32 s43, v252, 48
	s_nop 1
	v_mov_b32_e32 v253, s40
	v_add_f32_e32 v253, s41, v253
	v_add_f32_e32 v253, s42, v253
	v_add_f32_e32 v253, s43, v253
	v_mov_b32_e32 v252, 0x3a000000
	v_fmaak_f32 v253, v253, v252, 0x3727c5ac
	v_rsq_f32_e32 v253, v253
	s_nop 1
	v_readfirstlane_b32 s37, v253
	s_add_u32 s12, s4, 0x800000
	s_addc_u32 s13, s5, 0
	ds_read_b64 v[252:253], v168
	ds_read_b64 v[254:255], v168 offset:8192
	ds_read_b64 v[88:89], v168 offset:512
	ds_read_b64 v[242:243], v168 offset:8704
	s_waitcnt lgkmcnt(2)
	v_mul_f32_e32 v64, s37, v64
	v_mul_f32_e32 v65, s37, v65
	v_fma_f32 v64, v64, v252, v254
	v_fma_f32 v65, v65, v253, v255
	ds_read_b64 v[252:253], v168 offset:1024
	ds_read_b64 v[254:255], v168 offset:9216
	s_waitcnt lgkmcnt(2)
	v_mul_f32_e32 v66, s37, v66
	v_mul_f32_e32 v67, s37, v67
	v_fma_f32 v66, v66, v88, v242
	v_fma_f32 v67, v67, v89, v243
	ds_read_b64 v[88:89], v168 offset:1536
	ds_read_b64 v[242:243], v168 offset:9728
	s_waitcnt lgkmcnt(2)
	v_mul_f32_e32 v68, s37, v68
	v_mul_f32_e32 v69, s37, v69
	v_fma_f32 v68, v68, v252, v254
	v_fma_f32 v69, v69, v253, v255
	ds_read_b64 v[252:253], v168 offset:2048
	ds_read_b64 v[254:255], v168 offset:10240
	s_waitcnt lgkmcnt(2)
	v_mul_f32_e32 v70, s37, v70
	v_mul_f32_e32 v71, s37, v71
	v_fma_f32 v70, v70, v88, v242
	v_fma_f32 v71, v71, v89, v243
	v_cvt_pk_bf16_f32 v64, v64, v65
	v_cvt_pk_bf16_f32 v65, v66, v67
	v_cvt_pk_bf16_f32 v66, v68, v69
	v_cvt_pk_bf16_f32 v67, v70, v71
	global_store_dwordx4 v90, v[64:67], s[12:13]
	ds_read_b64 v[88:89], v168 offset:2560
	ds_read_b64 v[242:243], v168 offset:10752
	s_waitcnt lgkmcnt(2)
	v_mul_f32_e32 v72, s37, v72
	v_mul_f32_e32 v73, s37, v73
	v_fma_f32 v72, v72, v252, v254
	v_fma_f32 v73, v73, v253, v255
	ds_read_b64 v[252:253], v168 offset:3072
	ds_read_b64 v[254:255], v168 offset:11264
	s_waitcnt lgkmcnt(2)
	v_mul_f32_e32 v74, s37, v74
	v_mul_f32_e32 v75, s37, v75
	v_fma_f32 v74, v74, v88, v242
	v_fma_f32 v75, v75, v89, v243
	ds_read_b64 v[88:89], v168 offset:3584
	ds_read_b64 v[242:243], v168 offset:11776
	s_waitcnt lgkmcnt(2)
	v_mul_f32_e32 v76, s37, v76
	v_mul_f32_e32 v77, s37, v77
	v_fma_f32 v76, v76, v252, v254
	v_fma_f32 v77, v77, v253, v255
	ds_read_b64 v[252:253], v168 offset:4096
	ds_read_b64 v[254:255], v168 offset:12288
	s_waitcnt lgkmcnt(2)
	v_mul_f32_e32 v78, s37, v78
	v_mul_f32_e32 v79, s37, v79
	v_fma_f32 v78, v78, v88, v242
	v_fma_f32 v79, v79, v89, v243
	v_cvt_pk_bf16_f32 v72, v72, v73
	v_cvt_pk_bf16_f32 v73, v74, v75
	v_cvt_pk_bf16_f32 v74, v76, v77
	v_cvt_pk_bf16_f32 v75, v78, v79
	global_store_dwordx4 v90, v[72:75], s[12:13] offset:1024
	ds_read_b64 v[88:89], v168 offset:4608
	ds_read_b64 v[242:243], v168 offset:12800
	s_waitcnt lgkmcnt(2)
	v_mul_f32_e32 v80, s37, v80
	v_mul_f32_e32 v81, s37, v81
	v_fma_f32 v80, v80, v252, v254
	v_fma_f32 v81, v81, v253, v255
	ds_read_b64 v[252:253], v168 offset:5120
	ds_read_b64 v[254:255], v168 offset:13312
	s_waitcnt lgkmcnt(2)
	v_mul_f32_e32 v82, s37, v82
	v_mul_f32_e32 v83, s37, v83
	v_fma_f32 v82, v82, v88, v242
	v_fma_f32 v83, v83, v89, v243
	ds_read_b64 v[88:89], v168 offset:5632
	ds_read_b64 v[242:243], v168 offset:13824
	s_waitcnt lgkmcnt(2)
	v_mul_f32_e32 v84, s37, v84
	v_mul_f32_e32 v85, s37, v85
	v_fma_f32 v84, v84, v252, v254
	v_fma_f32 v85, v85, v253, v255
	ds_read_b64 v[252:253], v168 offset:6144
	ds_read_b64 v[254:255], v168 offset:14336
	s_waitcnt lgkmcnt(2)
	v_mul_f32_e32 v86, s37, v86
	v_mul_f32_e32 v87, s37, v87
	v_fma_f32 v86, v86, v88, v242
	v_fma_f32 v87, v87, v89, v243
	v_cvt_pk_bf16_f32 v80, v80, v81
	v_cvt_pk_bf16_f32 v81, v82, v83
	v_cvt_pk_bf16_f32 v82, v84, v85
	v_cvt_pk_bf16_f32 v83, v86, v87
	global_store_dwordx4 v90, v[80:83], s[12:13] offset:2048
	ds_read_b64 v[88:89], v168 offset:6656
	ds_read_b64 v[242:243], v168 offset:14848
	s_waitcnt lgkmcnt(2)
	v_mul_f32_e32 v244, s37, v244
	v_mul_f32_e32 v245, s37, v245
	v_fma_f32 v244, v244, v252, v254
	v_fma_f32 v245, v245, v253, v255
	ds_read_b64 v[252:253], v168 offset:7168
	ds_read_b64 v[254:255], v168 offset:15360
	s_waitcnt lgkmcnt(2)
	v_mul_f32_e32 v246, s37, v246
	v_mul_f32_e32 v247, s37, v247
	v_fma_f32 v246, v246, v88, v242
	v_fma_f32 v247, v247, v89, v243
	ds_read_b64 v[88:89], v168 offset:7680
	ds_read_b64 v[242:243], v168 offset:15872
	s_waitcnt lgkmcnt(2)
	v_mul_f32_e32 v248, s37, v248
	v_mul_f32_e32 v249, s37, v249
	v_fma_f32 v248, v248, v252, v254
	v_fma_f32 v249, v249, v253, v255
	s_waitcnt lgkmcnt(0)
	v_mul_f32_e32 v250, s37, v250
	v_mul_f32_e32 v251, s37, v251
	v_fma_f32 v250, v250, v88, v242
	v_fma_f32 v251, v251, v89, v243
	v_cvt_pk_bf16_f32 v244, v244, v245
	v_cvt_pk_bf16_f32 v245, v246, v247
	v_cvt_pk_bf16_f32 v246, v248, v249
	v_cvt_pk_bf16_f32 v247, v250, v251
	global_store_dwordx4 v90, v[244:247], s[12:13] offset:3072
	s_waitcnt vmcnt(16)
	v_lshlrev_b32_e32 v64, 16, v16
	v_and_b32_e32 v65, 0xffff0000, v16
	v_and_b32_e32 v252, 0xffff0000, v0
	v_lshlrev_b32_e32 v0, 16, v0
	v_fmac_f32_e32 v64, 0x3fb504f3, v0
	v_fmac_f32_e32 v65, 0x3fb504f3, v252
	v_lshlrev_b32_e32 v66, 16, v17
	v_and_b32_e32 v67, 0xffff0000, v17
	v_and_b32_e32 v252, 0xffff0000, v1
	v_lshlrev_b32_e32 v1, 16, v1
	v_fmac_f32_e32 v66, 0x3fb504f3, v1
	v_fmac_f32_e32 v67, 0x3fb504f3, v252
	v_add_f32_e32 v252, v64, v65
	v_add_f32_e32 v253, v66, v67
	v_add_f32_e32 v254, v252, v253
	v_lshlrev_b32_e32 v68, 16, v18
	v_and_b32_e32 v69, 0xffff0000, v18
	v_and_b32_e32 v252, 0xffff0000, v2
	v_lshlrev_b32_e32 v2, 16, v2
	v_fmac_f32_e32 v68, 0x3fb504f3, v2
	v_fmac_f32_e32 v69, 0x3fb504f3, v252
	v_lshlrev_b32_e32 v70, 16, v19
	v_and_b32_e32 v71, 0xffff0000, v19
	v_and_b32_e32 v252, 0xffff0000, v3
	v_lshlrev_b32_e32 v3, 16, v3
	v_fmac_f32_e32 v70, 0x3fb504f3, v3
	v_fmac_f32_e32 v71, 0x3fb504f3, v252
	v_add_f32_e32 v252, v68, v69
	v_add_f32_e32 v253, v70, v71
	v_add_f32_e32 v252, v252, v253
	v_add_f32_e32 v254, v254, v252
	v_lshlrev_b32_e32 v72, 16, v20
	v_and_b32_e32 v73, 0xffff0000, v20
	v_and_b32_e32 v252, 0xffff0000, v4
	v_lshlrev_b32_e32 v4, 16, v4
	v_fmac_f32_e32 v72, 0x3fb504f3, v4
	v_fmac_f32_e32 v73, 0x3fb504f3, v252
	v_lshlrev_b32_e32 v74, 16, v21
	v_and_b32_e32 v75, 0xffff0000, v21
	v_and_b32_e32 v252, 0xffff0000, v5
	v_lshlrev_b32_e32 v5, 16, v5
	v_fmac_f32_e32 v74, 0x3fb504f3, v5
	v_fmac_f32_e32 v75, 0x3fb504f3, v252
	v_add_f32_e32 v252, v72, v73
	v_add_f32_e32 v253, v74, v75
	v_add_f32_e32 v252, v252, v253
	v_add_f32_e32 v254, v254, v252
	v_lshlrev_b32_e32 v76, 16, v22
	v_and_b32_e32 v77, 0xffff0000, v22
	v_and_b32_e32 v252, 0xffff0000, v6
	v_lshlrev_b32_e32 v6, 16, v6
	v_fmac_f32_e32 v76, 0x3fb504f3, v6
	v_fmac_f32_e32 v77, 0x3fb504f3, v252
	v_lshlrev_b32_e32 v78, 16, v23
	v_and_b32_e32 v79, 0xffff0000, v23
	v_and_b32_e32 v252, 0xffff0000, v7
	v_lshlrev_b32_e32 v7, 16, v7
	v_fmac_f32_e32 v78, 0x3fb504f3, v7
	v_fmac_f32_e32 v79, 0x3fb504f3, v252
	v_add_f32_e32 v252, v76, v77
	v_add_f32_e32 v253, v78, v79
	v_add_f32_e32 v252, v252, v253
	v_add_f32_e32 v254, v254, v252
	v_lshlrev_b32_e32 v80, 16, v24
	v_and_b32_e32 v81, 0xffff0000, v24
	v_and_b32_e32 v252, 0xffff0000, v8
	v_lshlrev_b32_e32 v8, 16, v8
	v_fmac_f32_e32 v80, 0x3fb504f3, v8
	v_fmac_f32_e32 v81, 0x3fb504f3, v252
	v_lshlrev_b32_e32 v82, 16, v25
	v_and_b32_e32 v83, 0xffff0000, v25
	v_and_b32_e32 v252, 0xffff0000, v9
	v_lshlrev_b32_e32 v9, 16, v9
	v_fmac_f32_e32 v82, 0x3fb504f3, v9
	v_fmac_f32_e32 v83, 0x3fb504f3, v252
	v_add_f32_e32 v252, v80, v81
	v_add_f32_e32 v253, v82, v83
	v_add_f32_e32 v252, v252, v253
	v_add_f32_e32 v254, v254, v252
	v_lshlrev_b32_e32 v84, 16, v26
	v_and_b32_e32 v85, 0xffff0000, v26
	v_and_b32_e32 v252, 0xffff0000, v10
	v_lshlrev_b32_e32 v10, 16, v10
	v_fmac_f32_e32 v84, 0x3fb504f3, v10
	v_fmac_f32_e32 v85, 0x3fb504f3, v252
	v_lshlrev_b32_e32 v86, 16, v27
	v_and_b32_e32 v87, 0xffff0000, v27
	v_and_b32_e32 v252, 0xffff0000, v11
	v_lshlrev_b32_e32 v11, 16, v11
	v_fmac_f32_e32 v86, 0x3fb504f3, v11
	v_fmac_f32_e32 v87, 0x3fb504f3, v252
	v_add_f32_e32 v252, v84, v85
	v_add_f32_e32 v253, v86, v87
	v_add_f32_e32 v252, v252, v253
	v_add_f32_e32 v254, v254, v252
	v_lshlrev_b32_e32 v244, 16, v28
	v_and_b32_e32 v245, 0xffff0000, v28
	v_and_b32_e32 v252, 0xffff0000, v12
	v_lshlrev_b32_e32 v12, 16, v12
	v_fmac_f32_e32 v244, 0x3fb504f3, v12
	v_fmac_f32_e32 v245, 0x3fb504f3, v252
	v_lshlrev_b32_e32 v246, 16, v29
	v_and_b32_e32 v247, 0xffff0000, v29
	v_and_b32_e32 v252, 0xffff0000, v13
	v_lshlrev_b32_e32 v13, 16, v13
	v_fmac_f32_e32 v246, 0x3fb504f3, v13
	v_fmac_f32_e32 v247, 0x3fb504f3, v252
	v_add_f32_e32 v252, v244, v245
	v_add_f32_e32 v253, v246, v247
	v_add_f32_e32 v252, v252, v253
	v_add_f32_e32 v254, v254, v252
	v_lshlrev_b32_e32 v248, 16, v30
	v_and_b32_e32 v249, 0xffff0000, v30
	v_and_b32_e32 v252, 0xffff0000, v14
	v_lshlrev_b32_e32 v14, 16, v14
	v_fmac_f32_e32 v248, 0x3fb504f3, v14
	v_fmac_f32_e32 v249, 0x3fb504f3, v252
	v_lshlrev_b32_e32 v250, 16, v31
	v_and_b32_e32 v251, 0xffff0000, v31
	v_and_b32_e32 v252, 0xffff0000, v15
	v_lshlrev_b32_e32 v15, 16, v15
	v_fmac_f32_e32 v250, 0x3fb504f3, v15
	v_fmac_f32_e32 v251, 0x3fb504f3, v252
	v_add_f32_e32 v252, v248, v249
	v_add_f32_e32 v253, v250, v251
	v_add_f32_e32 v252, v252, v253
	v_add_f32_e32 v254, v254, v252
	s_add_u32 s12, s4, 0x17fc000
	s_addc_u32 s13, s5, 0
	global_load_dwordx4 v[0:3], v90, s[12:13]
	global_load_dwordx4 v[4:7], v90, s[12:13] offset:1024
	global_load_dwordx4 v[8:11], v90, s[12:13] offset:2048
	global_load_dwordx4 v[12:15], v90, s[12:13] offset:3072
	s_add_u32 s12, s6, 0x17fc000
	s_addc_u32 s13, s7, 0
	global_load_dwordx4 v[16:19], v90, s[12:13]
	global_load_dwordx4 v[20:23], v90, s[12:13] offset:1024
	global_load_dwordx4 v[24:27], v90, s[12:13] offset:2048
	global_load_dwordx4 v[28:31], v90, s[12:13] offset:3072
	s_nop 1
	v_add_f32_dpp v252, v254, v254 quad_perm:[1,0,3,2] row_mask:0xf bank_mask:0xf
	s_nop 1
	v_add_f32_dpp v252, v252, v252 quad_perm:[2,3,0,1] row_mask:0xf bank_mask:0xf
	s_nop 1
	v_add_f32_dpp v252, v252, v252 row_half_mirror row_mask:0xf bank_mask:0xf
	s_nop 1
	v_add_f32_dpp v252, v252, v252 row_mirror row_mask:0xf bank_mask:0xf
	s_nop 1
	v_readlane_b32 s40, v252, 0
	v_readlane_b32 s41, v252, 16
	v_readlane_b32 s42, v252, 32
	v_readlane_b32 s43, v252, 48
	s_nop 1
	v_mov_b32_e32 v253, s40
	v_add_f32_e32 v253, s41, v253
	v_add_f32_e32 v253, s42, v253
	v_add_f32_e32 v253, s43, v253
	v_mul_f32_e32 v253, 0x3a000000, v253
	s_nop 0
	v_readfirstlane_b32 s37, v253
	s_nop 1
	v_subrev_f32_e32 v64, s37, v64
	v_subrev_f32_e32 v65, s37, v65
	v_subrev_f32_e32 v66, s37, v66
	v_subrev_f32_e32 v67, s37, v67
	v_subrev_f32_e32 v68, s37, v68
	v_subrev_f32_e32 v69, s37, v69
	v_subrev_f32_e32 v70, s37, v70
	v_subrev_f32_e32 v71, s37, v71
	v_mul_f32_e32 v252, v64, v64
	v_fmac_f32_e32 v252, v65, v65
	v_mul_f32_e32 v253, v66, v66
	v_fmac_f32_e32 v253, v67, v67
	v_add_f32_e32 v254, v252, v253
	v_mul_f32_e32 v252, v68, v68
	v_fmac_f32_e32 v252, v69, v69
	v_mul_f32_e32 v253, v70, v70
	v_fmac_f32_e32 v253, v71, v71
	v_add_f32_e32 v252, v252, v253
	v_add_f32_e32 v254, v254, v252
	v_subrev_f32_e32 v72, s37, v72
	v_subrev_f32_e32 v73, s37, v73
	v_subrev_f32_e32 v74, s37, v74
	v_subrev_f32_e32 v75, s37, v75
	v_subrev_f32_e32 v76, s37, v76
	v_subrev_f32_e32 v77, s37, v77
	v_subrev_f32_e32 v78, s37, v78
	v_subrev_f32_e32 v79, s37, v79
	v_mul_f32_e32 v252, v72, v72
	v_fmac_f32_e32 v252, v73, v73
	v_mul_f32_e32 v253, v74, v74
	v_fmac_f32_e32 v253, v75, v75
	v_add_f32_e32 v252, v252, v253
	v_add_f32_e32 v254, v254, v252
	v_mul_f32_e32 v252, v76, v76
	v_fmac_f32_e32 v252, v77, v77
	v_mul_f32_e32 v253, v78, v78
	v_fmac_f32_e32 v253, v79, v79
	v_add_f32_e32 v252, v252, v253
	v_add_f32_e32 v254, v254, v252
	v_subrev_f32_e32 v80, s37, v80
	v_subrev_f32_e32 v81, s37, v81
	v_subrev_f32_e32 v82, s37, v82
	v_subrev_f32_e32 v83, s37, v83
	v_subrev_f32_e32 v84, s37, v84
	v_subrev_f32_e32 v85, s37, v85
	v_subrev_f32_e32 v86, s37, v86
	v_subrev_f32_e32 v87, s37, v87
	v_mul_f32_e32 v252, v80, v80
	v_fmac_f32_e32 v252, v81, v81
	v_mul_f32_e32 v253, v82, v82
	v_fmac_f32_e32 v253, v83, v83
	v_add_f32_e32 v252, v252, v253
	v_add_f32_e32 v254, v254, v252
	v_mul_f32_e32 v252, v84, v84
	v_fmac_f32_e32 v252, v85, v85
	v_mul_f32_e32 v253, v86, v86
	v_fmac_f32_e32 v253, v87, v87
	v_add_f32_e32 v252, v252, v253
	v_add_f32_e32 v254, v254, v252
	v_subrev_f32_e32 v244, s37, v244
	v_subrev_f32_e32 v245, s37, v245
	v_subrev_f32_e32 v246, s37, v246
	v_subrev_f32_e32 v247, s37, v247
	v_subrev_f32_e32 v248, s37, v248
	v_subrev_f32_e32 v249, s37, v249
	v_subrev_f32_e32 v250, s37, v250
	v_subrev_f32_e32 v251, s37, v251
	v_mul_f32_e32 v252, v244, v244
	v_fmac_f32_e32 v252, v245, v245
	v_mul_f32_e32 v253, v246, v246
	v_fmac_f32_e32 v253, v247, v247
	v_add_f32_e32 v252, v252, v253
	v_add_f32_e32 v254, v254, v252
	v_mul_f32_e32 v252, v248, v248
	v_fmac_f32_e32 v252, v249, v249
	v_mul_f32_e32 v253, v250, v250
	v_fmac_f32_e32 v253, v251, v251
	v_add_f32_e32 v252, v252, v253
	v_add_f32_e32 v254, v254, v252
	s_nop 1
	v_add_f32_dpp v252, v254, v254 quad_perm:[1,0,3,2] row_mask:0xf bank_mask:0xf
	s_nop 1
	v_add_f32_dpp v252, v252, v252 quad_perm:[2,3,0,1] row_mask:0xf bank_mask:0xf
	s_nop 1
	v_add_f32_dpp v252, v252, v252 row_half_mirror row_mask:0xf bank_mask:0xf
	s_nop 1
	v_add_f32_dpp v252, v252, v252 row_mirror row_mask:0xf bank_mask:0xf
	s_nop 1
	v_readlane_b32 s40, v252, 0
	v_readlane_b32 s41, v252, 16
	v_readlane_b32 s42, v252, 32
	v_readlane_b32 s43, v252, 48
	s_nop 1
	v_mov_b32_e32 v253, s40
	v_add_f32_e32 v253, s41, v253
	v_add_f32_e32 v253, s42, v253
	v_add_f32_e32 v253, s43, v253
	v_mov_b32_e32 v252, 0x3a000000
	v_fmaak_f32 v253, v253, v252, 0x3727c5ac
	v_rsq_f32_e32 v253, v253
	s_nop 1
	v_readfirstlane_b32 s37, v253
	s_add_u32 s12, s4, 0x1000000
	s_addc_u32 s13, s5, 0
	ds_read_b64 v[252:253], v168
	ds_read_b64 v[254:255], v168 offset:8192
	ds_read_b64 v[88:89], v168 offset:512
	ds_read_b64 v[242:243], v168 offset:8704
	s_waitcnt lgkmcnt(2)
	v_mul_f32_e32 v64, s37, v64
	v_mul_f32_e32 v65, s37, v65
	v_fma_f32 v64, v64, v252, v254
	v_fma_f32 v65, v65, v253, v255
	ds_read_b64 v[252:253], v168 offset:1024
	ds_read_b64 v[254:255], v168 offset:9216
	s_waitcnt lgkmcnt(2)
	v_mul_f32_e32 v66, s37, v66
	v_mul_f32_e32 v67, s37, v67
	v_fma_f32 v66, v66, v88, v242
	v_fma_f32 v67, v67, v89, v243
	ds_read_b64 v[88:89], v168 offset:1536
	ds_read_b64 v[242:243], v168 offset:9728
	s_waitcnt lgkmcnt(2)
	v_mul_f32_e32 v68, s37, v68
	v_mul_f32_e32 v69, s37, v69
	v_fma_f32 v68, v68, v252, v254
	v_fma_f32 v69, v69, v253, v255
	ds_read_b64 v[252:253], v168 offset:2048
	ds_read_b64 v[254:255], v168 offset:10240
	s_waitcnt lgkmcnt(2)
	v_mul_f32_e32 v70, s37, v70
	v_mul_f32_e32 v71, s37, v71
	v_fma_f32 v70, v70, v88, v242
	v_fma_f32 v71, v71, v89, v243
	v_cvt_pk_bf16_f32 v64, v64, v65
	v_cvt_pk_bf16_f32 v65, v66, v67
	v_cvt_pk_bf16_f32 v66, v68, v69
	v_cvt_pk_bf16_f32 v67, v70, v71
	global_store_dwordx4 v90, v[64:67], s[12:13]
	ds_read_b64 v[88:89], v168 offset:2560
	ds_read_b64 v[242:243], v168 offset:10752
	s_waitcnt lgkmcnt(2)
	v_mul_f32_e32 v72, s37, v72
	v_mul_f32_e32 v73, s37, v73
	v_fma_f32 v72, v72, v252, v254
	v_fma_f32 v73, v73, v253, v255
	ds_read_b64 v[252:253], v168 offset:3072
	ds_read_b64 v[254:255], v168 offset:11264
	s_waitcnt lgkmcnt(2)
	v_mul_f32_e32 v74, s37, v74
	v_mul_f32_e32 v75, s37, v75
	v_fma_f32 v74, v74, v88, v242
	v_fma_f32 v75, v75, v89, v243
	ds_read_b64 v[88:89], v168 offset:3584
	ds_read_b64 v[242:243], v168 offset:11776
	s_waitcnt lgkmcnt(2)
	v_mul_f32_e32 v76, s37, v76
	v_mul_f32_e32 v77, s37, v77
	v_fma_f32 v76, v76, v252, v254
	v_fma_f32 v77, v77, v253, v255
	ds_read_b64 v[252:253], v168 offset:4096
	ds_read_b64 v[254:255], v168 offset:12288
	s_waitcnt lgkmcnt(2)
	v_mul_f32_e32 v78, s37, v78
	v_mul_f32_e32 v79, s37, v79
	v_fma_f32 v78, v78, v88, v242
	v_fma_f32 v79, v79, v89, v243
	v_cvt_pk_bf16_f32 v72, v72, v73
	v_cvt_pk_bf16_f32 v73, v74, v75
	v_cvt_pk_bf16_f32 v74, v76, v77
	v_cvt_pk_bf16_f32 v75, v78, v79
	global_store_dwordx4 v90, v[72:75], s[12:13] offset:1024
	ds_read_b64 v[88:89], v168 offset:4608
	ds_read_b64 v[242:243], v168 offset:12800
	s_waitcnt lgkmcnt(2)
	v_mul_f32_e32 v80, s37, v80
	v_mul_f32_e32 v81, s37, v81
	v_fma_f32 v80, v80, v252, v254
	v_fma_f32 v81, v81, v253, v255
	ds_read_b64 v[252:253], v168 offset:5120
	ds_read_b64 v[254:255], v168 offset:13312
	s_waitcnt lgkmcnt(2)
	v_mul_f32_e32 v82, s37, v82
	v_mul_f32_e32 v83, s37, v83
	v_fma_f32 v82, v82, v88, v242
	v_fma_f32 v83, v83, v89, v243
	ds_read_b64 v[88:89], v168 offset:5632
	ds_read_b64 v[242:243], v168 offset:13824
	s_waitcnt lgkmcnt(2)
	v_mul_f32_e32 v84, s37, v84
	v_mul_f32_e32 v85, s37, v85
	v_fma_f32 v84, v84, v252, v254
	v_fma_f32 v85, v85, v253, v255
	ds_read_b64 v[252:253], v168 offset:6144
	ds_read_b64 v[254:255], v168 offset:14336
	s_waitcnt lgkmcnt(2)
	v_mul_f32_e32 v86, s37, v86
	v_mul_f32_e32 v87, s37, v87
	v_fma_f32 v86, v86, v88, v242
	v_fma_f32 v87, v87, v89, v243
	v_cvt_pk_bf16_f32 v80, v80, v81
	v_cvt_pk_bf16_f32 v81, v82, v83
	v_cvt_pk_bf16_f32 v82, v84, v85
	v_cvt_pk_bf16_f32 v83, v86, v87
	global_store_dwordx4 v90, v[80:83], s[12:13] offset:2048
	ds_read_b64 v[88:89], v168 offset:6656
	ds_read_b64 v[242:243], v168 offset:14848
	s_waitcnt lgkmcnt(2)
	v_mul_f32_e32 v244, s37, v244
	v_mul_f32_e32 v245, s37, v245
	v_fma_f32 v244, v244, v252, v254
	v_fma_f32 v245, v245, v253, v255
	ds_read_b64 v[252:253], v168 offset:7168
	ds_read_b64 v[254:255], v168 offset:15360
	s_waitcnt lgkmcnt(2)
	v_mul_f32_e32 v246, s37, v246
	v_mul_f32_e32 v247, s37, v247
	v_fma_f32 v246, v246, v88, v242
	v_fma_f32 v247, v247, v89, v243
	ds_read_b64 v[88:89], v168 offset:7680
	ds_read_b64 v[242:243], v168 offset:15872
	s_waitcnt lgkmcnt(2)
	v_mul_f32_e32 v248, s37, v248
	v_mul_f32_e32 v249, s37, v249
	v_fma_f32 v248, v248, v252, v254
	v_fma_f32 v249, v249, v253, v255
	s_waitcnt lgkmcnt(0)
	v_mul_f32_e32 v250, s37, v250
	v_mul_f32_e32 v251, s37, v251
	v_fma_f32 v250, v250, v88, v242
	v_fma_f32 v251, v251, v89, v243
	v_cvt_pk_bf16_f32 v244, v244, v245
	v_cvt_pk_bf16_f32 v245, v246, v247
	v_cvt_pk_bf16_f32 v246, v248, v249
	v_cvt_pk_bf16_f32 v247, v250, v251
	global_store_dwordx4 v90, v[244:247], s[12:13] offset:3072
	s_waitcnt vmcnt(16)
	v_lshlrev_b32_e32 v64, 16, v48
	v_and_b32_e32 v65, 0xffff0000, v48
	v_and_b32_e32 v252, 0xffff0000, v32
	v_lshlrev_b32_e32 v32, 16, v32
	v_fmac_f32_e32 v64, 0x3fb504f3, v32
	v_fmac_f32_e32 v65, 0x3fb504f3, v252
	v_lshlrev_b32_e32 v66, 16, v49
	v_and_b32_e32 v67, 0xffff0000, v49
	v_and_b32_e32 v252, 0xffff0000, v33
	v_lshlrev_b32_e32 v33, 16, v33
	v_fmac_f32_e32 v66, 0x3fb504f3, v33
	v_fmac_f32_e32 v67, 0x3fb504f3, v252
	v_add_f32_e32 v252, v64, v65
	v_add_f32_e32 v253, v66, v67
	v_add_f32_e32 v254, v252, v253
	v_lshlrev_b32_e32 v68, 16, v50
	v_and_b32_e32 v69, 0xffff0000, v50
	v_and_b32_e32 v252, 0xffff0000, v34
	v_lshlrev_b32_e32 v34, 16, v34
	v_fmac_f32_e32 v68, 0x3fb504f3, v34
	v_fmac_f32_e32 v69, 0x3fb504f3, v252
	v_lshlrev_b32_e32 v70, 16, v51
	v_and_b32_e32 v71, 0xffff0000, v51
	v_and_b32_e32 v252, 0xffff0000, v35
	v_lshlrev_b32_e32 v35, 16, v35
	v_fmac_f32_e32 v70, 0x3fb504f3, v35
	v_fmac_f32_e32 v71, 0x3fb504f3, v252
	v_add_f32_e32 v252, v68, v69
	v_add_f32_e32 v253, v70, v71
	v_add_f32_e32 v252, v252, v253
	v_add_f32_e32 v254, v254, v252
	v_lshlrev_b32_e32 v72, 16, v52
	v_and_b32_e32 v73, 0xffff0000, v52
	v_and_b32_e32 v252, 0xffff0000, v36
	v_lshlrev_b32_e32 v36, 16, v36
	v_fmac_f32_e32 v72, 0x3fb504f3, v36
	v_fmac_f32_e32 v73, 0x3fb504f3, v252
	v_lshlrev_b32_e32 v74, 16, v53
	v_and_b32_e32 v75, 0xffff0000, v53
	v_and_b32_e32 v252, 0xffff0000, v37
	v_lshlrev_b32_e32 v37, 16, v37
	v_fmac_f32_e32 v74, 0x3fb504f3, v37
	v_fmac_f32_e32 v75, 0x3fb504f3, v252
	v_add_f32_e32 v252, v72, v73
	v_add_f32_e32 v253, v74, v75
	v_add_f32_e32 v252, v252, v253
	v_add_f32_e32 v254, v254, v252
	v_lshlrev_b32_e32 v76, 16, v54
	v_and_b32_e32 v77, 0xffff0000, v54
	v_and_b32_e32 v252, 0xffff0000, v38
	v_lshlrev_b32_e32 v38, 16, v38
	v_fmac_f32_e32 v76, 0x3fb504f3, v38
	v_fmac_f32_e32 v77, 0x3fb504f3, v252
	v_lshlrev_b32_e32 v78, 16, v55
	v_and_b32_e32 v79, 0xffff0000, v55
	v_and_b32_e32 v252, 0xffff0000, v39
	v_lshlrev_b32_e32 v39, 16, v39
	v_fmac_f32_e32 v78, 0x3fb504f3, v39
	v_fmac_f32_e32 v79, 0x3fb504f3, v252
	v_add_f32_e32 v252, v76, v77
	v_add_f32_e32 v253, v78, v79
	v_add_f32_e32 v252, v252, v253
	v_add_f32_e32 v254, v254, v252
	v_lshlrev_b32_e32 v80, 16, v56
	v_and_b32_e32 v81, 0xffff0000, v56
	v_and_b32_e32 v252, 0xffff0000, v40
	v_lshlrev_b32_e32 v40, 16, v40
	v_fmac_f32_e32 v80, 0x3fb504f3, v40
	v_fmac_f32_e32 v81, 0x3fb504f3, v252
	v_lshlrev_b32_e32 v82, 16, v57
	v_and_b32_e32 v83, 0xffff0000, v57
	v_and_b32_e32 v252, 0xffff0000, v41
	v_lshlrev_b32_e32 v41, 16, v41
	v_fmac_f32_e32 v82, 0x3fb504f3, v41
	v_fmac_f32_e32 v83, 0x3fb504f3, v252
	v_add_f32_e32 v252, v80, v81
	v_add_f32_e32 v253, v82, v83
	v_add_f32_e32 v252, v252, v253
	v_add_f32_e32 v254, v254, v252
	v_lshlrev_b32_e32 v84, 16, v58
	v_and_b32_e32 v85, 0xffff0000, v58
	v_and_b32_e32 v252, 0xffff0000, v42
	v_lshlrev_b32_e32 v42, 16, v42
	v_fmac_f32_e32 v84, 0x3fb504f3, v42
	v_fmac_f32_e32 v85, 0x3fb504f3, v252
	v_lshlrev_b32_e32 v86, 16, v59
	v_and_b32_e32 v87, 0xffff0000, v59
	v_and_b32_e32 v252, 0xffff0000, v43
	v_lshlrev_b32_e32 v43, 16, v43
	v_fmac_f32_e32 v86, 0x3fb504f3, v43
	v_fmac_f32_e32 v87, 0x3fb504f3, v252
	v_add_f32_e32 v252, v84, v85
	v_add_f32_e32 v253, v86, v87
	v_add_f32_e32 v252, v252, v253
	v_add_f32_e32 v254, v254, v252
	v_lshlrev_b32_e32 v244, 16, v60
	v_and_b32_e32 v245, 0xffff0000, v60
	v_and_b32_e32 v252, 0xffff0000, v44
	v_lshlrev_b32_e32 v44, 16, v44
	v_fmac_f32_e32 v244, 0x3fb504f3, v44
	v_fmac_f32_e32 v245, 0x3fb504f3, v252
	v_lshlrev_b32_e32 v246, 16, v61
	v_and_b32_e32 v247, 0xffff0000, v61
	v_and_b32_e32 v252, 0xffff0000, v45
	v_lshlrev_b32_e32 v45, 16, v45
	v_fmac_f32_e32 v246, 0x3fb504f3, v45
	v_fmac_f32_e32 v247, 0x3fb504f3, v252
	v_add_f32_e32 v252, v244, v245
	v_add_f32_e32 v253, v246, v247
	v_add_f32_e32 v252, v252, v253
	v_add_f32_e32 v254, v254, v252
	v_lshlrev_b32_e32 v248, 16, v62
	v_and_b32_e32 v249, 0xffff0000, v62
	v_and_b32_e32 v252, 0xffff0000, v46
	v_lshlrev_b32_e32 v46, 16, v46
	v_fmac_f32_e32 v248, 0x3fb504f3, v46
	v_fmac_f32_e32 v249, 0x3fb504f3, v252
	v_lshlrev_b32_e32 v250, 16, v63
	v_and_b32_e32 v251, 0xffff0000, v63
	v_and_b32_e32 v252, 0xffff0000, v47
	v_lshlrev_b32_e32 v47, 16, v47
	v_fmac_f32_e32 v250, 0x3fb504f3, v47
	v_fmac_f32_e32 v251, 0x3fb504f3, v252
	v_add_f32_e32 v252, v248, v249
	v_add_f32_e32 v253, v250, v251
	v_add_f32_e32 v252, v252, v253
	v_add_f32_e32 v254, v254, v252
	s_nop 1
	v_add_f32_dpp v252, v254, v254 quad_perm:[1,0,3,2] row_mask:0xf bank_mask:0xf
	s_nop 1
	v_add_f32_dpp v252, v252, v252 quad_perm:[2,3,0,1] row_mask:0xf bank_mask:0xf
	s_nop 1
	v_add_f32_dpp v252, v252, v252 row_half_mirror row_mask:0xf bank_mask:0xf
	s_nop 1
	v_add_f32_dpp v252, v252, v252 row_mirror row_mask:0xf bank_mask:0xf
	s_nop 1
	v_readlane_b32 s40, v252, 0
	v_readlane_b32 s41, v252, 16
	v_readlane_b32 s42, v252, 32
	v_readlane_b32 s43, v252, 48
	s_nop 1
	v_mov_b32_e32 v253, s40
	v_add_f32_e32 v253, s41, v253
	v_add_f32_e32 v253, s42, v253
	v_add_f32_e32 v253, s43, v253
	v_mul_f32_e32 v253, 0x3a000000, v253
	s_nop 0
	v_readfirstlane_b32 s37, v253
	s_nop 1
	v_subrev_f32_e32 v64, s37, v64
	v_subrev_f32_e32 v65, s37, v65
	v_subrev_f32_e32 v66, s37, v66
	v_subrev_f32_e32 v67, s37, v67
	v_subrev_f32_e32 v68, s37, v68
	v_subrev_f32_e32 v69, s37, v69
	v_subrev_f32_e32 v70, s37, v70
	v_subrev_f32_e32 v71, s37, v71
	v_mul_f32_e32 v252, v64, v64
	v_fmac_f32_e32 v252, v65, v65
	v_mul_f32_e32 v253, v66, v66
	v_fmac_f32_e32 v253, v67, v67
	v_add_f32_e32 v254, v252, v253
	v_mul_f32_e32 v252, v68, v68
	v_fmac_f32_e32 v252, v69, v69
	v_mul_f32_e32 v253, v70, v70
	v_fmac_f32_e32 v253, v71, v71
	v_add_f32_e32 v252, v252, v253
	v_add_f32_e32 v254, v254, v252
	v_subrev_f32_e32 v72, s37, v72
	v_subrev_f32_e32 v73, s37, v73
	v_subrev_f32_e32 v74, s37, v74
	v_subrev_f32_e32 v75, s37, v75
	v_subrev_f32_e32 v76, s37, v76
	v_subrev_f32_e32 v77, s37, v77
	v_subrev_f32_e32 v78, s37, v78
	v_subrev_f32_e32 v79, s37, v79
	v_mul_f32_e32 v252, v72, v72
	v_fmac_f32_e32 v252, v73, v73
	v_mul_f32_e32 v253, v74, v74
	v_fmac_f32_e32 v253, v75, v75
	v_add_f32_e32 v252, v252, v253
	v_add_f32_e32 v254, v254, v252
	v_mul_f32_e32 v252, v76, v76
	v_fmac_f32_e32 v252, v77, v77
	v_mul_f32_e32 v253, v78, v78
	v_fmac_f32_e32 v253, v79, v79
	v_add_f32_e32 v252, v252, v253
	v_add_f32_e32 v254, v254, v252
	v_subrev_f32_e32 v80, s37, v80
	v_subrev_f32_e32 v81, s37, v81
	v_subrev_f32_e32 v82, s37, v82
	v_subrev_f32_e32 v83, s37, v83
	v_subrev_f32_e32 v84, s37, v84
	v_subrev_f32_e32 v85, s37, v85
	v_subrev_f32_e32 v86, s37, v86
	v_subrev_f32_e32 v87, s37, v87
	v_mul_f32_e32 v252, v80, v80
	v_fmac_f32_e32 v252, v81, v81
	v_mul_f32_e32 v253, v82, v82
	v_fmac_f32_e32 v253, v83, v83
	v_add_f32_e32 v252, v252, v253
	v_add_f32_e32 v254, v254, v252
	v_mul_f32_e32 v252, v84, v84
	v_fmac_f32_e32 v252, v85, v85
	v_mul_f32_e32 v253, v86, v86
	v_fmac_f32_e32 v253, v87, v87
	v_add_f32_e32 v252, v252, v253
	v_add_f32_e32 v254, v254, v252
	v_subrev_f32_e32 v244, s37, v244
	v_subrev_f32_e32 v245, s37, v245
	v_subrev_f32_e32 v246, s37, v246
	v_subrev_f32_e32 v247, s37, v247
	v_subrev_f32_e32 v248, s37, v248
	v_subrev_f32_e32 v249, s37, v249
	v_subrev_f32_e32 v250, s37, v250
	v_subrev_f32_e32 v251, s37, v251
	v_mul_f32_e32 v252, v244, v244
	v_fmac_f32_e32 v252, v245, v245
	v_mul_f32_e32 v253, v246, v246
	v_fmac_f32_e32 v253, v247, v247
	v_add_f32_e32 v252, v252, v253
	v_add_f32_e32 v254, v254, v252
	v_mul_f32_e32 v252, v248, v248
	v_fmac_f32_e32 v252, v249, v249
	v_mul_f32_e32 v253, v250, v250
	v_fmac_f32_e32 v253, v251, v251
	v_add_f32_e32 v252, v252, v253
	v_add_f32_e32 v254, v254, v252
	s_nop 1
	v_add_f32_dpp v252, v254, v254 quad_perm:[1,0,3,2] row_mask:0xf bank_mask:0xf
	s_nop 1
	v_add_f32_dpp v252, v252, v252 quad_perm:[2,3,0,1] row_mask:0xf bank_mask:0xf
	s_nop 1
	v_add_f32_dpp v252, v252, v252 row_half_mirror row_mask:0xf bank_mask:0xf
	s_nop 1
	v_add_f32_dpp v252, v252, v252 row_mirror row_mask:0xf bank_mask:0xf
	s_nop 1
	v_readlane_b32 s40, v252, 0
	v_readlane_b32 s41, v252, 16
	v_readlane_b32 s42, v252, 32
	v_readlane_b32 s43, v252, 48
	s_nop 1
	v_mov_b32_e32 v253, s40
	v_add_f32_e32 v253, s41, v253
	v_add_f32_e32 v253, s42, v253
	v_add_f32_e32 v253, s43, v253
	v_mov_b32_e32 v252, 0x3a000000
	v_fmaak_f32 v253, v253, v252, 0x3727c5ac
	v_rsq_f32_e32 v253, v253
	s_nop 1
	v_readfirstlane_b32 s37, v253
	s_add_u32 s12, s4, 0x1800000
	s_addc_u32 s13, s5, 0
	ds_read_b64 v[252:253], v168
	ds_read_b64 v[254:255], v168 offset:8192
	ds_read_b64 v[88:89], v168 offset:512
	ds_read_b64 v[242:243], v168 offset:8704
	s_waitcnt lgkmcnt(2)
	v_mul_f32_e32 v64, s37, v64
	v_mul_f32_e32 v65, s37, v65
	v_fma_f32 v64, v64, v252, v254
	v_fma_f32 v65, v65, v253, v255
	ds_read_b64 v[252:253], v168 offset:1024
	ds_read_b64 v[254:255], v168 offset:9216
	s_waitcnt lgkmcnt(2)
	v_mul_f32_e32 v66, s37, v66
	v_mul_f32_e32 v67, s37, v67
	v_fma_f32 v66, v66, v88, v242
	v_fma_f32 v67, v67, v89, v243
	ds_read_b64 v[88:89], v168 offset:1536
	ds_read_b64 v[242:243], v168 offset:9728
	s_waitcnt lgkmcnt(2)
	v_mul_f32_e32 v68, s37, v68
	v_mul_f32_e32 v69, s37, v69
	v_fma_f32 v68, v68, v252, v254
	v_fma_f32 v69, v69, v253, v255
	ds_read_b64 v[252:253], v168 offset:2048
	ds_read_b64 v[254:255], v168 offset:10240
	s_waitcnt lgkmcnt(2)
	v_mul_f32_e32 v70, s37, v70
	v_mul_f32_e32 v71, s37, v71
	v_fma_f32 v70, v70, v88, v242
	v_fma_f32 v71, v71, v89, v243
	v_cvt_pk_bf16_f32 v64, v64, v65
	v_cvt_pk_bf16_f32 v65, v66, v67
	v_cvt_pk_bf16_f32 v66, v68, v69
	v_cvt_pk_bf16_f32 v67, v70, v71
	global_store_dwordx4 v90, v[64:67], s[12:13]
	ds_read_b64 v[88:89], v168 offset:2560
	ds_read_b64 v[242:243], v168 offset:10752
	s_waitcnt lgkmcnt(2)
	v_mul_f32_e32 v72, s37, v72
	v_mul_f32_e32 v73, s37, v73
	v_fma_f32 v72, v72, v252, v254
	v_fma_f32 v73, v73, v253, v255
	ds_read_b64 v[252:253], v168 offset:3072
	ds_read_b64 v[254:255], v168 offset:11264
	s_waitcnt lgkmcnt(2)
	v_mul_f32_e32 v74, s37, v74
	v_mul_f32_e32 v75, s37, v75
	v_fma_f32 v74, v74, v88, v242
	v_fma_f32 v75, v75, v89, v243
	ds_read_b64 v[88:89], v168 offset:3584
	ds_read_b64 v[242:243], v168 offset:11776
	s_waitcnt lgkmcnt(2)
	v_mul_f32_e32 v76, s37, v76
	v_mul_f32_e32 v77, s37, v77
	v_fma_f32 v76, v76, v252, v254
	v_fma_f32 v77, v77, v253, v255
	ds_read_b64 v[252:253], v168 offset:4096
	ds_read_b64 v[254:255], v168 offset:12288
	s_waitcnt lgkmcnt(2)
	v_mul_f32_e32 v78, s37, v78
	v_mul_f32_e32 v79, s37, v79
	v_fma_f32 v78, v78, v88, v242
	v_fma_f32 v79, v79, v89, v243
	v_cvt_pk_bf16_f32 v72, v72, v73
	v_cvt_pk_bf16_f32 v73, v74, v75
	v_cvt_pk_bf16_f32 v74, v76, v77
	v_cvt_pk_bf16_f32 v75, v78, v79
	global_store_dwordx4 v90, v[72:75], s[12:13] offset:1024
	ds_read_b64 v[88:89], v168 offset:4608
	ds_read_b64 v[242:243], v168 offset:12800
	s_waitcnt lgkmcnt(2)
	v_mul_f32_e32 v80, s37, v80
	v_mul_f32_e32 v81, s37, v81
	v_fma_f32 v80, v80, v252, v254
	v_fma_f32 v81, v81, v253, v255
	ds_read_b64 v[252:253], v168 offset:5120
	ds_read_b64 v[254:255], v168 offset:13312
	s_waitcnt lgkmcnt(2)
	v_mul_f32_e32 v82, s37, v82
	v_mul_f32_e32 v83, s37, v83
	v_fma_f32 v82, v82, v88, v242
	v_fma_f32 v83, v83, v89, v243
	ds_read_b64 v[88:89], v168 offset:5632
	ds_read_b64 v[242:243], v168 offset:13824
	s_waitcnt lgkmcnt(2)
	v_mul_f32_e32 v84, s37, v84
	v_mul_f32_e32 v85, s37, v85
	v_fma_f32 v84, v84, v252, v254
	v_fma_f32 v85, v85, v253, v255
	ds_read_b64 v[252:253], v168 offset:6144
	ds_read_b64 v[254:255], v168 offset:14336
	s_waitcnt lgkmcnt(2)
	v_mul_f32_e32 v86, s37, v86
	v_mul_f32_e32 v87, s37, v87
	v_fma_f32 v86, v86, v88, v242
	v_fma_f32 v87, v87, v89, v243
	v_cvt_pk_bf16_f32 v80, v80, v81
	v_cvt_pk_bf16_f32 v81, v82, v83
	v_cvt_pk_bf16_f32 v82, v84, v85
	v_cvt_pk_bf16_f32 v83, v86, v87
	global_store_dwordx4 v90, v[80:83], s[12:13] offset:2048
	ds_read_b64 v[88:89], v168 offset:6656
	ds_read_b64 v[242:243], v168 offset:14848
	s_waitcnt lgkmcnt(2)
	v_mul_f32_e32 v244, s37, v244
	v_mul_f32_e32 v245, s37, v245
	v_fma_f32 v244, v244, v252, v254
	v_fma_f32 v245, v245, v253, v255
	ds_read_b64 v[252:253], v168 offset:7168
	ds_read_b64 v[254:255], v168 offset:15360
	s_waitcnt lgkmcnt(2)
	v_mul_f32_e32 v246, s37, v246
	v_mul_f32_e32 v247, s37, v247
	v_fma_f32 v246, v246, v88, v242
	v_fma_f32 v247, v247, v89, v243
	ds_read_b64 v[88:89], v168 offset:7680
	ds_read_b64 v[242:243], v168 offset:15872
	s_waitcnt lgkmcnt(2)
	v_mul_f32_e32 v248, s37, v248
	v_mul_f32_e32 v249, s37, v249
	v_fma_f32 v248, v248, v252, v254
	v_fma_f32 v249, v249, v253, v255
	s_waitcnt lgkmcnt(0)
	v_mul_f32_e32 v250, s37, v250
	v_mul_f32_e32 v251, s37, v251
	v_fma_f32 v250, v250, v88, v242
	v_fma_f32 v251, v251, v89, v243
	v_cvt_pk_bf16_f32 v244, v244, v245
	v_cvt_pk_bf16_f32 v245, v246, v247
	v_cvt_pk_bf16_f32 v246, v248, v249
	v_cvt_pk_bf16_f32 v247, v250, v251
	global_store_dwordx4 v90, v[244:247], s[12:13] offset:3072
	s_waitcnt vmcnt(8)
	v_lshlrev_b32_e32 v64, 16, v16
	v_and_b32_e32 v65, 0xffff0000, v16
	v_and_b32_e32 v252, 0xffff0000, v0
	v_lshlrev_b32_e32 v0, 16, v0
	v_fmac_f32_e32 v64, 0x3fb504f3, v0
	v_fmac_f32_e32 v65, 0x3fb504f3, v252
	v_lshlrev_b32_e32 v66, 16, v17
	v_and_b32_e32 v67, 0xffff0000, v17
	v_and_b32_e32 v252, 0xffff0000, v1
	v_lshlrev_b32_e32 v1, 16, v1
	v_fmac_f32_e32 v66, 0x3fb504f3, v1
	v_fmac_f32_e32 v67, 0x3fb504f3, v252
	v_add_f32_e32 v252, v64, v65
	v_add_f32_e32 v253, v66, v67
	v_add_f32_e32 v254, v252, v253
	v_lshlrev_b32_e32 v68, 16, v18
	v_and_b32_e32 v69, 0xffff0000, v18
	v_and_b32_e32 v252, 0xffff0000, v2
	v_lshlrev_b32_e32 v2, 16, v2
	v_fmac_f32_e32 v68, 0x3fb504f3, v2
	v_fmac_f32_e32 v69, 0x3fb504f3, v252
	v_lshlrev_b32_e32 v70, 16, v19
	v_and_b32_e32 v71, 0xffff0000, v19
	v_and_b32_e32 v252, 0xffff0000, v3
	v_lshlrev_b32_e32 v3, 16, v3
	v_fmac_f32_e32 v70, 0x3fb504f3, v3
	v_fmac_f32_e32 v71, 0x3fb504f3, v252
	v_add_f32_e32 v252, v68, v69
	v_add_f32_e32 v253, v70, v71
	v_add_f32_e32 v252, v252, v253
	v_add_f32_e32 v254, v254, v252
	v_lshlrev_b32_e32 v72, 16, v20
	v_and_b32_e32 v73, 0xffff0000, v20
	v_and_b32_e32 v252, 0xffff0000, v4
	v_lshlrev_b32_e32 v4, 16, v4
	v_fmac_f32_e32 v72, 0x3fb504f3, v4
	v_fmac_f32_e32 v73, 0x3fb504f3, v252
	v_lshlrev_b32_e32 v74, 16, v21
	v_and_b32_e32 v75, 0xffff0000, v21
	v_and_b32_e32 v252, 0xffff0000, v5
	v_lshlrev_b32_e32 v5, 16, v5
	v_fmac_f32_e32 v74, 0x3fb504f3, v5
	v_fmac_f32_e32 v75, 0x3fb504f3, v252
	v_add_f32_e32 v252, v72, v73
	v_add_f32_e32 v253, v74, v75
	v_add_f32_e32 v252, v252, v253
	v_add_f32_e32 v254, v254, v252
	v_lshlrev_b32_e32 v76, 16, v22
	v_and_b32_e32 v77, 0xffff0000, v22
	v_and_b32_e32 v252, 0xffff0000, v6
	v_lshlrev_b32_e32 v6, 16, v6
	v_fmac_f32_e32 v76, 0x3fb504f3, v6
	v_fmac_f32_e32 v77, 0x3fb504f3, v252
	v_lshlrev_b32_e32 v78, 16, v23
	v_and_b32_e32 v79, 0xffff0000, v23
	v_and_b32_e32 v252, 0xffff0000, v7
	v_lshlrev_b32_e32 v7, 16, v7
	v_fmac_f32_e32 v78, 0x3fb504f3, v7
	v_fmac_f32_e32 v79, 0x3fb504f3, v252
	v_add_f32_e32 v252, v76, v77
	v_add_f32_e32 v253, v78, v79
	v_add_f32_e32 v252, v252, v253
	v_add_f32_e32 v254, v254, v252
	v_lshlrev_b32_e32 v80, 16, v24
	v_and_b32_e32 v81, 0xffff0000, v24
	v_and_b32_e32 v252, 0xffff0000, v8
	v_lshlrev_b32_e32 v8, 16, v8
	v_fmac_f32_e32 v80, 0x3fb504f3, v8
	v_fmac_f32_e32 v81, 0x3fb504f3, v252
	v_lshlrev_b32_e32 v82, 16, v25
	v_and_b32_e32 v83, 0xffff0000, v25
	v_and_b32_e32 v252, 0xffff0000, v9
	v_lshlrev_b32_e32 v9, 16, v9
	v_fmac_f32_e32 v82, 0x3fb504f3, v9
	v_fmac_f32_e32 v83, 0x3fb504f3, v252
	v_add_f32_e32 v252, v80, v81
	v_add_f32_e32 v253, v82, v83
	v_add_f32_e32 v252, v252, v253
	v_add_f32_e32 v254, v254, v252
	v_lshlrev_b32_e32 v84, 16, v26
	v_and_b32_e32 v85, 0xffff0000, v26
	v_and_b32_e32 v252, 0xffff0000, v10
	v_lshlrev_b32_e32 v10, 16, v10
	v_fmac_f32_e32 v84, 0x3fb504f3, v10
	v_fmac_f32_e32 v85, 0x3fb504f3, v252
	v_lshlrev_b32_e32 v86, 16, v27
	v_and_b32_e32 v87, 0xffff0000, v27
	v_and_b32_e32 v252, 0xffff0000, v11
	v_lshlrev_b32_e32 v11, 16, v11
	v_fmac_f32_e32 v86, 0x3fb504f3, v11
	v_fmac_f32_e32 v87, 0x3fb504f3, v252
	v_add_f32_e32 v252, v84, v85
	v_add_f32_e32 v253, v86, v87
	v_add_f32_e32 v252, v252, v253
	v_add_f32_e32 v254, v254, v252
	v_lshlrev_b32_e32 v244, 16, v28
	v_and_b32_e32 v245, 0xffff0000, v28
	v_and_b32_e32 v252, 0xffff0000, v12
	v_lshlrev_b32_e32 v12, 16, v12
	v_fmac_f32_e32 v244, 0x3fb504f3, v12
	v_fmac_f32_e32 v245, 0x3fb504f3, v252
	v_lshlrev_b32_e32 v246, 16, v29
	v_and_b32_e32 v247, 0xffff0000, v29
	v_and_b32_e32 v252, 0xffff0000, v13
	v_lshlrev_b32_e32 v13, 16, v13
	v_fmac_f32_e32 v246, 0x3fb504f3, v13
	v_fmac_f32_e32 v247, 0x3fb504f3, v252
	v_add_f32_e32 v252, v244, v245
	v_add_f32_e32 v253, v246, v247
	v_add_f32_e32 v252, v252, v253
	v_add_f32_e32 v254, v254, v252
	v_lshlrev_b32_e32 v248, 16, v30
	v_and_b32_e32 v249, 0xffff0000, v30
	v_and_b32_e32 v252, 0xffff0000, v14
	v_lshlrev_b32_e32 v14, 16, v14
	v_fmac_f32_e32 v248, 0x3fb504f3, v14
	v_fmac_f32_e32 v249, 0x3fb504f3, v252
	v_lshlrev_b32_e32 v250, 16, v31
	v_and_b32_e32 v251, 0xffff0000, v31
	v_and_b32_e32 v252, 0xffff0000, v15
	v_lshlrev_b32_e32 v15, 16, v15
	v_fmac_f32_e32 v250, 0x3fb504f3, v15
	v_fmac_f32_e32 v251, 0x3fb504f3, v252
	v_add_f32_e32 v252, v248, v249
	v_add_f32_e32 v253, v250, v251
	v_add_f32_e32 v252, v252, v253
	v_add_f32_e32 v254, v254, v252
	s_nop 1
	v_add_f32_dpp v252, v254, v254 quad_perm:[1,0,3,2] row_mask:0xf bank_mask:0xf
	s_nop 1
	v_add_f32_dpp v252, v252, v252 quad_perm:[2,3,0,1] row_mask:0xf bank_mask:0xf
	s_nop 1
	v_add_f32_dpp v252, v252, v252 row_half_mirror row_mask:0xf bank_mask:0xf
	s_nop 1
	v_add_f32_dpp v252, v252, v252 row_mirror row_mask:0xf bank_mask:0xf
	s_nop 1
	v_readlane_b32 s40, v252, 0
	v_readlane_b32 s41, v252, 16
	v_readlane_b32 s42, v252, 32
	v_readlane_b32 s43, v252, 48
	s_nop 1
	v_mov_b32_e32 v253, s40
	v_add_f32_e32 v253, s41, v253
	v_add_f32_e32 v253, s42, v253
	v_add_f32_e32 v253, s43, v253
	v_mul_f32_e32 v253, 0x3a000000, v253
	s_nop 0
	v_readfirstlane_b32 s37, v253
	s_nop 1
	v_subrev_f32_e32 v64, s37, v64
	v_subrev_f32_e32 v65, s37, v65
	v_subrev_f32_e32 v66, s37, v66
	v_subrev_f32_e32 v67, s37, v67
	v_subrev_f32_e32 v68, s37, v68
	v_subrev_f32_e32 v69, s37, v69
	v_subrev_f32_e32 v70, s37, v70
	v_subrev_f32_e32 v71, s37, v71
	v_mul_f32_e32 v252, v64, v64
	v_fmac_f32_e32 v252, v65, v65
	v_mul_f32_e32 v253, v66, v66
	v_fmac_f32_e32 v253, v67, v67
	v_add_f32_e32 v254, v252, v253
	v_mul_f32_e32 v252, v68, v68
	v_fmac_f32_e32 v252, v69, v69
	v_mul_f32_e32 v253, v70, v70
	v_fmac_f32_e32 v253, v71, v71
	v_add_f32_e32 v252, v252, v253
	v_add_f32_e32 v254, v254, v252
	v_subrev_f32_e32 v72, s37, v72
	v_subrev_f32_e32 v73, s37, v73
	v_subrev_f32_e32 v74, s37, v74
	v_subrev_f32_e32 v75, s37, v75
	v_subrev_f32_e32 v76, s37, v76
	v_subrev_f32_e32 v77, s37, v77
	v_subrev_f32_e32 v78, s37, v78
	v_subrev_f32_e32 v79, s37, v79
	v_mul_f32_e32 v252, v72, v72
	v_fmac_f32_e32 v252, v73, v73
	v_mul_f32_e32 v253, v74, v74
	v_fmac_f32_e32 v253, v75, v75
	v_add_f32_e32 v252, v252, v253
	v_add_f32_e32 v254, v254, v252
	v_mul_f32_e32 v252, v76, v76
	v_fmac_f32_e32 v252, v77, v77
	v_mul_f32_e32 v253, v78, v78
	v_fmac_f32_e32 v253, v79, v79
	v_add_f32_e32 v252, v252, v253
	v_add_f32_e32 v254, v254, v252
	v_subrev_f32_e32 v80, s37, v80
	v_subrev_f32_e32 v81, s37, v81
	v_subrev_f32_e32 v82, s37, v82
	v_subrev_f32_e32 v83, s37, v83
	v_subrev_f32_e32 v84, s37, v84
	v_subrev_f32_e32 v85, s37, v85
	v_subrev_f32_e32 v86, s37, v86
	v_subrev_f32_e32 v87, s37, v87
	v_mul_f32_e32 v252, v80, v80
	v_fmac_f32_e32 v252, v81, v81
	v_mul_f32_e32 v253, v82, v82
	v_fmac_f32_e32 v253, v83, v83
	v_add_f32_e32 v252, v252, v253
	v_add_f32_e32 v254, v254, v252
	v_mul_f32_e32 v252, v84, v84
	v_fmac_f32_e32 v252, v85, v85
	v_mul_f32_e32 v253, v86, v86
	v_fmac_f32_e32 v253, v87, v87
	v_add_f32_e32 v252, v252, v253
	v_add_f32_e32 v254, v254, v252
	v_subrev_f32_e32 v244, s37, v244
	v_subrev_f32_e32 v245, s37, v245
	v_subrev_f32_e32 v246, s37, v246
	v_subrev_f32_e32 v247, s37, v247
	v_subrev_f32_e32 v248, s37, v248
	v_subrev_f32_e32 v249, s37, v249
	v_subrev_f32_e32 v250, s37, v250
	v_subrev_f32_e32 v251, s37, v251
	v_mul_f32_e32 v252, v244, v244
	v_fmac_f32_e32 v252, v245, v245
	v_mul_f32_e32 v253, v246, v246
	v_fmac_f32_e32 v253, v247, v247
	v_add_f32_e32 v252, v252, v253
	v_add_f32_e32 v254, v254, v252
	v_mul_f32_e32 v252, v248, v248
	v_fmac_f32_e32 v252, v249, v249
	v_mul_f32_e32 v253, v250, v250
	v_fmac_f32_e32 v253, v251, v251
	v_add_f32_e32 v252, v252, v253
	v_add_f32_e32 v254, v254, v252
	s_nop 1
	v_add_f32_dpp v252, v254, v254 quad_perm:[1,0,3,2] row_mask:0xf bank_mask:0xf
	s_nop 1
	v_add_f32_dpp v252, v252, v252 quad_perm:[2,3,0,1] row_mask:0xf bank_mask:0xf
	s_nop 1
	v_add_f32_dpp v252, v252, v252 row_half_mirror row_mask:0xf bank_mask:0xf
	s_nop 1
	v_add_f32_dpp v252, v252, v252 row_mirror row_mask:0xf bank_mask:0xf
	s_nop 1
	v_readlane_b32 s40, v252, 0
	v_readlane_b32 s41, v252, 16
	v_readlane_b32 s42, v252, 32
	v_readlane_b32 s43, v252, 48
	s_nop 1
	v_mov_b32_e32 v253, s40
	v_add_f32_e32 v253, s41, v253
	v_add_f32_e32 v253, s42, v253
	v_add_f32_e32 v253, s43, v253
	v_mov_b32_e32 v252, 0x3a000000
	v_fmaak_f32 v253, v253, v252, 0x3727c5ac
	v_rsq_f32_e32 v253, v253
	s_nop 1
	v_readfirstlane_b32 s37, v253
	s_add_u32 s12, s4, 0x17fc000
	s_addc_u32 s13, s5, 0
	ds_read_b64 v[252:253], v168
	ds_read_b64 v[254:255], v168 offset:8192
	ds_read_b64 v[88:89], v168 offset:512
	ds_read_b64 v[242:243], v168 offset:8704
	s_waitcnt lgkmcnt(2)
	v_mul_f32_e32 v64, s37, v64
	v_mul_f32_e32 v65, s37, v65
	v_fma_f32 v64, v64, v252, v254
	v_fma_f32 v65, v65, v253, v255
	ds_read_b64 v[252:253], v168 offset:1024
	ds_read_b64 v[254:255], v168 offset:9216
	s_waitcnt lgkmcnt(2)
	v_mul_f32_e32 v66, s37, v66
	v_mul_f32_e32 v67, s37, v67
	v_fma_f32 v66, v66, v88, v242
	v_fma_f32 v67, v67, v89, v243
	ds_read_b64 v[88:89], v168 offset:1536
	ds_read_b64 v[242:243], v168 offset:9728
	s_waitcnt lgkmcnt(2)
	v_mul_f32_e32 v68, s37, v68
	v_mul_f32_e32 v69, s37, v69
	v_fma_f32 v68, v68, v252, v254
	v_fma_f32 v69, v69, v253, v255
	ds_read_b64 v[252:253], v168 offset:2048
	ds_read_b64 v[254:255], v168 offset:10240
	s_waitcnt lgkmcnt(2)
	v_mul_f32_e32 v70, s37, v70
	v_mul_f32_e32 v71, s37, v71
	v_fma_f32 v70, v70, v88, v242
	v_fma_f32 v71, v71, v89, v243
	v_cvt_pk_bf16_f32 v64, v64, v65
	v_cvt_pk_bf16_f32 v65, v66, v67
	v_cvt_pk_bf16_f32 v66, v68, v69
	v_cvt_pk_bf16_f32 v67, v70, v71
	global_store_dwordx4 v90, v[64:67], s[12:13]
	ds_read_b64 v[88:89], v168 offset:2560
	ds_read_b64 v[242:243], v168 offset:10752
	s_waitcnt lgkmcnt(2)
	v_mul_f32_e32 v72, s37, v72
	v_mul_f32_e32 v73, s37, v73
	v_fma_f32 v72, v72, v252, v254
	v_fma_f32 v73, v73, v253, v255
	ds_read_b64 v[252:253], v168 offset:3072
	ds_read_b64 v[254:255], v168 offset:11264
	s_waitcnt lgkmcnt(2)
	v_mul_f32_e32 v74, s37, v74
	v_mul_f32_e32 v75, s37, v75
	v_fma_f32 v74, v74, v88, v242
	v_fma_f32 v75, v75, v89, v243
	ds_read_b64 v[88:89], v168 offset:3584
	ds_read_b64 v[242:243], v168 offset:11776
	s_waitcnt lgkmcnt(2)
	v_mul_f32_e32 v76, s37, v76
	v_mul_f32_e32 v77, s37, v77
	v_fma_f32 v76, v76, v252, v254
	v_fma_f32 v77, v77, v253, v255
	ds_read_b64 v[252:253], v168 offset:4096
	ds_read_b64 v[254:255], v168 offset:12288
	s_waitcnt lgkmcnt(2)
	v_mul_f32_e32 v78, s37, v78
	v_mul_f32_e32 v79, s37, v79
	v_fma_f32 v78, v78, v88, v242
	v_fma_f32 v79, v79, v89, v243
	v_cvt_pk_bf16_f32 v72, v72, v73
	v_cvt_pk_bf16_f32 v73, v74, v75
	v_cvt_pk_bf16_f32 v74, v76, v77
	v_cvt_pk_bf16_f32 v75, v78, v79
	global_store_dwordx4 v90, v[72:75], s[12:13] offset:1024
	ds_read_b64 v[88:89], v168 offset:4608
	ds_read_b64 v[242:243], v168 offset:12800
	s_waitcnt lgkmcnt(2)
	v_mul_f32_e32 v80, s37, v80
	v_mul_f32_e32 v81, s37, v81
	v_fma_f32 v80, v80, v252, v254
	v_fma_f32 v81, v81, v253, v255
	ds_read_b64 v[252:253], v168 offset:5120
	ds_read_b64 v[254:255], v168 offset:13312
	s_waitcnt lgkmcnt(2)
	v_mul_f32_e32 v82, s37, v82
	v_mul_f32_e32 v83, s37, v83
	v_fma_f32 v82, v82, v88, v242
	v_fma_f32 v83, v83, v89, v243
	ds_read_b64 v[88:89], v168 offset:5632
	ds_read_b64 v[242:243], v168 offset:13824
	s_waitcnt lgkmcnt(2)
	v_mul_f32_e32 v84, s37, v84
	v_mul_f32_e32 v85, s37, v85
	v_fma_f32 v84, v84, v252, v254
	v_fma_f32 v85, v85, v253, v255
	ds_read_b64 v[252:253], v168 offset:6144
	ds_read_b64 v[254:255], v168 offset:14336
	s_waitcnt lgkmcnt(2)
	v_mul_f32_e32 v86, s37, v86
	v_mul_f32_e32 v87, s37, v87
	v_fma_f32 v86, v86, v88, v242
	v_fma_f32 v87, v87, v89, v243
	v_cvt_pk_bf16_f32 v80, v80, v81
	v_cvt_pk_bf16_f32 v81, v82, v83
	v_cvt_pk_bf16_f32 v82, v84, v85
	v_cvt_pk_bf16_f32 v83, v86, v87
	global_store_dwordx4 v90, v[80:83], s[12:13] offset:2048
	ds_read_b64 v[88:89], v168 offset:6656
	ds_read_b64 v[242:243], v168 offset:14848
	s_waitcnt lgkmcnt(2)
	v_mul_f32_e32 v244, s37, v244
	v_mul_f32_e32 v245, s37, v245
	v_fma_f32 v244, v244, v252, v254
	v_fma_f32 v245, v245, v253, v255
	ds_read_b64 v[252:253], v168 offset:7168
	ds_read_b64 v[254:255], v168 offset:15360
	s_waitcnt lgkmcnt(2)
	v_mul_f32_e32 v246, s37, v246
	v_mul_f32_e32 v247, s37, v247
	v_fma_f32 v246, v246, v88, v242
	v_fma_f32 v247, v247, v89, v243
	ds_read_b64 v[88:89], v168 offset:7680
	ds_read_b64 v[242:243], v168 offset:15872
	s_waitcnt lgkmcnt(2)
	v_mul_f32_e32 v248, s37, v248
	v_mul_f32_e32 v249, s37, v249
	v_fma_f32 v248, v248, v252, v254
	v_fma_f32 v249, v249, v253, v255
	s_waitcnt lgkmcnt(0)
	v_mul_f32_e32 v250, s37, v250
	v_mul_f32_e32 v251, s37, v251
	v_fma_f32 v250, v250, v88, v242
	v_fma_f32 v251, v251, v89, v243
	v_cvt_pk_bf16_f32 v244, v244, v245
	v_cvt_pk_bf16_f32 v245, v246, v247
	v_cvt_pk_bf16_f32 v246, v248, v249
	v_cvt_pk_bf16_f32 v247, v250, v251
	global_store_dwordx4 v90, v[244:247], s[12:13] offset:3072
	s_branch .LBB0_1118

.LBB0_1636:
	v_readlane_b32 s30, v241, 9
	s_cmpk_lg_i32 s30, 0x100
	s_cbranch_scc1 .Lln2_old
	v_readlane_b32 s91, v241, 0
	v_readlane_b32 s12, v239, 42
	v_readlane_b32 s13, v239, 43
	v_readlane_b32 s30, v239, 37
	s_add_u32 s4, s12, 0xc700000
	s_addc_u32 s5, s13, 0
	s_add_u32 s6, s12, 0x1d080000
	s_addc_u32 s7, s13, 0
	s_add_u32 s8, s12, 0x33ac0000
	s_addc_u32 s9, s13, 0
	s_mov_b32 s90, s30
	s_lshl_b32 s30, s30, 13
	v_readlane_b32 s86, v241, 3
	v_readlane_b32 s87, v241, 4
	v_readlane_b32 s88, v241, 5
	v_readlane_b32 s89, v241, 6
	s_add_u32 s86, s86, s30
	s_addc_u32 s87, s87, 0
	s_add_u32 s88, s88, s30
	s_addc_u32 s89, s89, 0
	v_lshlrev_b32_e32 v252, 4, v178
	global_load_dwordx4 v[0:3], v252, s[86:87]
	global_load_dwordx4 v[4:7], v252, s[88:89]
	v_lshrrev_b32_e32 v253, 7, v178
	v_lshlrev_b32_e32 v253, 11, v253
	v_and_b32_e32 v254, 1, v178
	v_lshl_or_b32 v253, v254, 10, v253
	v_bfe_u32 v254, v178, 1, 6
	v_lshl_or_b32 v253, v254, 3, v253
	v_readfirstlane_b32 s84, v178
	v_and_b32_e32 v168, 63, v178
	s_lshr_b32 s84, s84, 6
	s_lshl_b32 s30, s91, 3
	s_add_i32 s30, s30, s84
	s_lshl_b32 s30, s30, 12
	v_lshl_add_u32 v90, v168, 4, s30
	v_lshlrev_b32_e32 v168, 3, v168
	s_waitcnt vmcnt(0)
	ds_write_b64 v253, v[0:1]
	ds_write_b64 v253, v[2:3] offset:512
	ds_write_b64 v253, v[4:5] offset:8192
	ds_write_b64 v253, v[6:7] offset:8704
	s_waitcnt lgkmcnt(0)
	s_barrier
	s_cmp_lt_u32 s84, 4
	s_cbranch_scc0 .Lln2_hi_1
	global_load_dwordx4 v[0:3], v90, s[4:5]
	global_load_dwordx4 v[4:7], v90, s[4:5] offset:1024
	global_load_dwordx4 v[8:11], v90, s[4:5] offset:2048
	global_load_dwordx4 v[12:15], v90, s[4:5] offset:3072
	global_load_dwordx4 v[16:19], v90, s[6:7]
	global_load_dwordx4 v[20:23], v90, s[6:7] offset:1024
	global_load_dwordx4 v[24:27], v90, s[6:7] offset:2048
	global_load_dwordx4 v[28:31], v90, s[6:7] offset:3072
	s_add_u32 s12, s4, 0x800000
	s_addc_u32 s13, s5, 0
	global_load_dwordx4 v[32:35], v90, s[12:13]
	global_load_dwordx4 v[36:39], v90, s[12:13] offset:1024
	global_load_dwordx4 v[40:43], v90, s[12:13] offset:2048
	global_load_dwordx4 v[44:47], v90, s[12:13] offset:3072
	s_add_u32 s12, s6, 0x800000
	s_addc_u32 s13, s7, 0
	global_load_dwordx4 v[48:51], v90, s[12:13]
	global_load_dwordx4 v[52:55], v90, s[12:13] offset:1024
	global_load_dwordx4 v[56:59], v90, s[12:13] offset:2048
	global_load_dwordx4 v[60:63], v90, s[12:13] offset:3072
	s_waitcnt vmcnt(8)
	v_lshlrev_b32_e32 v64, 16, v16
	v_and_b32_e32 v65, 0xffff0000, v16
	v_and_b32_e32 v252, 0xffff0000, v0
	v_lshlrev_b32_e32 v0, 16, v0
	v_fmac_f32_e32 v64, 0x3fb504f3, v0
	v_fmac_f32_e32 v65, 0x3fb504f3, v252
	v_lshlrev_b32_e32 v66, 16, v17
	v_and_b32_e32 v67, 0xffff0000, v17
	v_and_b32_e32 v252, 0xffff0000, v1
	v_lshlrev_b32_e32 v1, 16, v1
	v_fmac_f32_e32 v66, 0x3fb504f3, v1
	v_fmac_f32_e32 v67, 0x3fb504f3, v252
	v_add_f32_e32 v252, v64, v65
	v_add_f32_e32 v253, v66, v67
	v_add_f32_e32 v254, v252, v253
	v_lshlrev_b32_e32 v68, 16, v18
	v_and_b32_e32 v69, 0xffff0000, v18
	v_and_b32_e32 v252, 0xffff0000, v2
	v_lshlrev_b32_e32 v2, 16, v2
	v_fmac_f32_e32 v68, 0x3fb504f3, v2
	v_fmac_f32_e32 v69, 0x3fb504f3, v252
	v_lshlrev_b32_e32 v70, 16, v19
	v_and_b32_e32 v71, 0xffff0000, v19
	v_and_b32_e32 v252, 0xffff0000, v3
	v_lshlrev_b32_e32 v3, 16, v3
	v_fmac_f32_e32 v70, 0x3fb504f3, v3
	v_fmac_f32_e32 v71, 0x3fb504f3, v252
	v_add_f32_e32 v252, v68, v69
	v_add_f32_e32 v253, v70, v71
	v_add_f32_e32 v252, v252, v253
	v_add_f32_e32 v254, v254, v252
	v_lshlrev_b32_e32 v72, 16, v20
	v_and_b32_e32 v73, 0xffff0000, v20
	v_and_b32_e32 v252, 0xffff0000, v4
	v_lshlrev_b32_e32 v4, 16, v4
	v_fmac_f32_e32 v72, 0x3fb504f3, v4
	v_fmac_f32_e32 v73, 0x3fb504f3, v252
	v_lshlrev_b32_e32 v74, 16, v21
	v_and_b32_e32 v75, 0xffff0000, v21
	v_and_b32_e32 v252, 0xffff0000, v5
	v_lshlrev_b32_e32 v5, 16, v5
	v_fmac_f32_e32 v74, 0x3fb504f3, v5
	v_fmac_f32_e32 v75, 0x3fb504f3, v252
	v_add_f32_e32 v252, v72, v73
	v_add_f32_e32 v253, v74, v75
	v_add_f32_e32 v252, v252, v253
	v_add_f32_e32 v254, v254, v252
	v_lshlrev_b32_e32 v76, 16, v22
	v_and_b32_e32 v77, 0xffff0000, v22
	v_and_b32_e32 v252, 0xffff0000, v6
	v_lshlrev_b32_e32 v6, 16, v6
	v_fmac_f32_e32 v76, 0x3fb504f3, v6
	v_fmac_f32_e32 v77, 0x3fb504f3, v252
	v_lshlrev_b32_e32 v78, 16, v23
	v_and_b32_e32 v79, 0xffff0000, v23
	v_and_b32_e32 v252, 0xffff0000, v7
	v_lshlrev_b32_e32 v7, 16, v7
	v_fmac_f32_e32 v78, 0x3fb504f3, v7
	v_fmac_f32_e32 v79, 0x3fb504f3, v252
	v_add_f32_e32 v252, v76, v77
	v_add_f32_e32 v253, v78, v79
	v_add_f32_e32 v252, v252, v253
	v_add_f32_e32 v254, v254, v252
	v_lshlrev_b32_e32 v80, 16, v24
	v_and_b32_e32 v81, 0xffff0000, v24
	v_and_b32_e32 v252, 0xffff0000, v8
	v_lshlrev_b32_e32 v8, 16, v8
	v_fmac_f32_e32 v80, 0x3fb504f3, v8
	v_fmac_f32_e32 v81, 0x3fb504f3, v252
	v_lshlrev_b32_e32 v82, 16, v25
	v_and_b32_e32 v83, 0xffff0000, v25
	v_and_b32_e32 v252, 0xffff0000, v9
	v_lshlrev_b32_e32 v9, 16, v9
	v_fmac_f32_e32 v82, 0x3fb504f3, v9
	v_fmac_f32_e32 v83, 0x3fb504f3, v252
	v_add_f32_e32 v252, v80, v81
	v_add_f32_e32 v253, v82, v83
	v_add_f32_e32 v252, v252, v253
	v_add_f32_e32 v254, v254, v252
	v_lshlrev_b32_e32 v84, 16, v26
	v_and_b32_e32 v85, 0xffff0000, v26
	v_and_b32_e32 v252, 0xffff0000, v10
	v_lshlrev_b32_e32 v10, 16, v10
	v_fmac_f32_e32 v84, 0x3fb504f3, v10
	v_fmac_f32_e32 v85, 0x3fb504f3, v252
	v_lshlrev_b32_e32 v86, 16, v27
	v_and_b32_e32 v87, 0xffff0000, v27
	v_and_b32_e32 v252, 0xffff0000, v11
	v_lshlrev_b32_e32 v11, 16, v11
	v_fmac_f32_e32 v86, 0x3fb504f3, v11
	v_fmac_f32_e32 v87, 0x3fb504f3, v252
	v_add_f32_e32 v252, v84, v85
	v_add_f32_e32 v253, v86, v87
	v_add_f32_e32 v252, v252, v253
	v_add_f32_e32 v254, v254, v252
	v_lshlrev_b32_e32 v244, 16, v28
	v_and_b32_e32 v245, 0xffff0000, v28
	v_and_b32_e32 v252, 0xffff0000, v12
	v_lshlrev_b32_e32 v12, 16, v12
	v_fmac_f32_e32 v244, 0x3fb504f3, v12
	v_fmac_f32_e32 v245, 0x3fb504f3, v252
	v_lshlrev_b32_e32 v246, 16, v29
	v_and_b32_e32 v247, 0xffff0000, v29
	v_and_b32_e32 v252, 0xffff0000, v13
	v_lshlrev_b32_e32 v13, 16, v13
	v_fmac_f32_e32 v246, 0x3fb504f3, v13
	v_fmac_f32_e32 v247, 0x3fb504f3, v252
	v_add_f32_e32 v252, v244, v245
	v_add_f32_e32 v253, v246, v247
	v_add_f32_e32 v252, v252, v253
	v_add_f32_e32 v254, v254, v252
	v_lshlrev_b32_e32 v248, 16, v30
	v_and_b32_e32 v249, 0xffff0000, v30
	v_and_b32_e32 v252, 0xffff0000, v14
	v_lshlrev_b32_e32 v14, 16, v14
	v_fmac_f32_e32 v248, 0x3fb504f3, v14
	v_fmac_f32_e32 v249, 0x3fb504f3, v252
	v_lshlrev_b32_e32 v250, 16, v31
	v_and_b32_e32 v251, 0xffff0000, v31
	v_and_b32_e32 v252, 0xffff0000, v15
	v_lshlrev_b32_e32 v15, 16, v15
	v_fmac_f32_e32 v250, 0x3fb504f3, v15
	v_fmac_f32_e32 v251, 0x3fb504f3, v252
	v_add_f32_e32 v252, v248, v249
	v_add_f32_e32 v253, v250, v251
	v_add_f32_e32 v252, v252, v253
	v_add_f32_e32 v254, v254, v252
	s_add_u32 s12, s4, 0x1000000
	s_addc_u32 s13, s5, 0
	global_load_dwordx4 v[0:3], v90, s[12:13]
	global_load_dwordx4 v[4:7], v90, s[12:13] offset:1024
	global_load_dwordx4 v[8:11], v90, s[12:13] offset:2048
	global_load_dwordx4 v[12:15], v90, s[12:13] offset:3072
	s_add_u32 s12, s6, 0x1000000
	s_addc_u32 s13, s7, 0
	global_load_dwordx4 v[16:19], v90, s[12:13]
	global_load_dwordx4 v[20:23], v90, s[12:13] offset:1024
	global_load_dwordx4 v[24:27], v90, s[12:13] offset:2048
	global_load_dwordx4 v[28:31], v90, s[12:13] offset:3072
	s_nop 1
	v_add_f32_dpp v252, v254, v254 quad_perm:[1,0,3,2] row_mask:0xf bank_mask:0xf
	s_nop 1
	v_add_f32_dpp v252, v252, v252 quad_perm:[2,3,0,1] row_mask:0xf bank_mask:0xf
	s_nop 1
	v_add_f32_dpp v252, v252, v252 row_half_mirror row_mask:0xf bank_mask:0xf
	s_nop 1
	v_add_f32_dpp v252, v252, v252 row_mirror row_mask:0xf bank_mask:0xf
	s_nop 1
	v_readlane_b32 s86, v252, 0
	v_readlane_b32 s87, v252, 16
	v_readlane_b32 s88, v252, 32
	v_readlane_b32 s89, v252, 48
	s_nop 1
	v_mov_b32_e32 v253, s86
	v_add_f32_e32 v253, s87, v253
	v_add_f32_e32 v253, s88, v253
	v_add_f32_e32 v253, s89, v253
	v_mul_f32_e32 v253, 0x3a000000, v253
	s_nop 0
	v_readfirstlane_b32 s85, v253
	s_nop 1
	v_subrev_f32_e32 v64, s85, v64
	v_subrev_f32_e32 v65, s85, v65
	v_subrev_f32_e32 v66, s85, v66
	v_subrev_f32_e32 v67, s85, v67
	v_subrev_f32_e32 v68, s85, v68
	v_subrev_f32_e32 v69, s85, v69
	v_subrev_f32_e32 v70, s85, v70
	v_subrev_f32_e32 v71, s85, v71
	v_mul_f32_e32 v252, v64, v64
	v_fmac_f32_e32 v252, v65, v65
	v_mul_f32_e32 v253, v66, v66
	v_fmac_f32_e32 v253, v67, v67
	v_add_f32_e32 v254, v252, v253
	v_mul_f32_e32 v252, v68, v68
	v_fmac_f32_e32 v252, v69, v69
	v_mul_f32_e32 v253, v70, v70
	v_fmac_f32_e32 v253, v71, v71
	v_add_f32_e32 v252, v252, v253
	v_add_f32_e32 v254, v254, v252
	v_subrev_f32_e32 v72, s85, v72
	v_subrev_f32_e32 v73, s85, v73
	v_subrev_f32_e32 v74, s85, v74
	v_subrev_f32_e32 v75, s85, v75
	v_subrev_f32_e32 v76, s85, v76
	v_subrev_f32_e32 v77, s85, v77
	v_subrev_f32_e32 v78, s85, v78
	v_subrev_f32_e32 v79, s85, v79
	v_mul_f32_e32 v252, v72, v72
	v_fmac_f32_e32 v252, v73, v73
	v_mul_f32_e32 v253, v74, v74
	v_fmac_f32_e32 v253, v75, v75
	v_add_f32_e32 v252, v252, v253
	v_add_f32_e32 v254, v254, v252
	v_mul_f32_e32 v252, v76, v76
	v_fmac_f32_e32 v252, v77, v77
	v_mul_f32_e32 v253, v78, v78
	v_fmac_f32_e32 v253, v79, v79
	v_add_f32_e32 v252, v252, v253
	v_add_f32_e32 v254, v254, v252
	v_subrev_f32_e32 v80, s85, v80
	v_subrev_f32_e32 v81, s85, v81
	v_subrev_f32_e32 v82, s85, v82
	v_subrev_f32_e32 v83, s85, v83
	v_subrev_f32_e32 v84, s85, v84
	v_subrev_f32_e32 v85, s85, v85
	v_subrev_f32_e32 v86, s85, v86
	v_subrev_f32_e32 v87, s85, v87
	v_mul_f32_e32 v252, v80, v80
	v_fmac_f32_e32 v252, v81, v81
	v_mul_f32_e32 v253, v82, v82
	v_fmac_f32_e32 v253, v83, v83
	v_add_f32_e32 v252, v252, v253
	v_add_f32_e32 v254, v254, v252
	v_mul_f32_e32 v252, v84, v84
	v_fmac_f32_e32 v252, v85, v85
	v_mul_f32_e32 v253, v86, v86
	v_fmac_f32_e32 v253, v87, v87
	v_add_f32_e32 v252, v252, v253
	v_add_f32_e32 v254, v254, v252
	v_subrev_f32_e32 v244, s85, v244
	v_subrev_f32_e32 v245, s85, v245
	v_subrev_f32_e32 v246, s85, v246
	v_subrev_f32_e32 v247, s85, v247
	v_subrev_f32_e32 v248, s85, v248
	v_subrev_f32_e32 v249, s85, v249
	v_subrev_f32_e32 v250, s85, v250
	v_subrev_f32_e32 v251, s85, v251
	v_mul_f32_e32 v252, v244, v244
	v_fmac_f32_e32 v252, v245, v245
	v_mul_f32_e32 v253, v246, v246
	v_fmac_f32_e32 v253, v247, v247
	v_add_f32_e32 v252, v252, v253
	v_add_f32_e32 v254, v254, v252
	v_mul_f32_e32 v252, v248, v248
	v_fmac_f32_e32 v252, v249, v249
	v_mul_f32_e32 v253, v250, v250
	v_fmac_f32_e32 v253, v251, v251
	v_add_f32_e32 v252, v252, v253
	v_add_f32_e32 v254, v254, v252
	s_nop 1
	v_add_f32_dpp v252, v254, v254 quad_perm:[1,0,3,2] row_mask:0xf bank_mask:0xf
	s_nop 1
	v_add_f32_dpp v252, v252, v252 quad_perm:[2,3,0,1] row_mask:0xf bank_mask:0xf
	s_nop 1
	v_add_f32_dpp v252, v252, v252 row_half_mirror row_mask:0xf bank_mask:0xf
	s_nop 1
	v_add_f32_dpp v252, v252, v252 row_mirror row_mask:0xf bank_mask:0xf
	s_nop 1
	v_readlane_b32 s86, v252, 0
	v_readlane_b32 s87, v252, 16
	v_readlane_b32 s88, v252, 32
	v_readlane_b32 s89, v252, 48
	s_nop 1
	v_mov_b32_e32 v253, s86
	v_add_f32_e32 v253, s87, v253
	v_add_f32_e32 v253, s88, v253
	v_add_f32_e32 v253, s89, v253
	v_mov_b32_e32 v252, 0x3a000000
	v_fmaak_f32 v253, v253, v252, 0x3727c5ac
	v_rsq_f32_e32 v253, v253
	s_nop 1
	v_readfirstlane_b32 s85, v253
	s_mov_b32 s12, s4
	s_mov_b32 s13, s5
	v_readlane_b32 s86, v241, 7
	v_readlane_b32 s87, v241, 8
	s_add_u32 s86, s86, 0x0
	s_addc_u32 s87, s87, 0
	s_add_u32 s88, s86, 0x1000
	s_addc_u32 s89, s87, 0
	ds_read_b64 v[252:253], v168
	ds_read_b64 v[254:255], v168 offset:8192
	ds_read_b64 v[88:89], v168 offset:512
	ds_read_b64 v[242:243], v168 offset:8704
	s_waitcnt lgkmcnt(2)
	v_mul_f32_e32 v64, s85, v64
	v_mul_f32_e32 v65, s85, v65
	v_fma_f32 v64, v64, v252, v254
	v_fma_f32 v65, v65, v253, v255
	ds_read_b64 v[252:253], v168 offset:1024
	ds_read_b64 v[254:255], v168 offset:9216
	s_waitcnt lgkmcnt(2)
	v_mul_f32_e32 v66, s85, v66
	v_mul_f32_e32 v67, s85, v67
	v_fma_f32 v66, v66, v88, v242
	v_fma_f32 v67, v67, v89, v243
	ds_read_b64 v[88:89], v168 offset:1536
	ds_read_b64 v[242:243], v168 offset:9728
	s_waitcnt lgkmcnt(2)
	v_mul_f32_e32 v68, s85, v68
	v_mul_f32_e32 v69, s85, v69
	v_fma_f32 v68, v68, v252, v254
	v_fma_f32 v69, v69, v253, v255
	ds_read_b64 v[252:253], v168 offset:2048
	ds_read_b64 v[254:255], v168 offset:10240
	s_waitcnt lgkmcnt(2)
	v_mul_f32_e32 v70, s85, v70
	v_mul_f32_e32 v71, s85, v71
	v_fma_f32 v70, v70, v88, v242
	v_fma_f32 v71, v71, v89, v243
	s_cmp_lg_u32 s90, 0
	s_cbranch_scc1 .Lln2_f32_2
	v_cvt_pk_bf16_f32 v64, v64, v65
	v_cvt_pk_bf16_f32 v65, v66, v67
	v_cvt_pk_bf16_f32 v66, v68, v69
	v_cvt_pk_bf16_f32 v67, v70, v71
	global_store_dwordx4 v90, v[64:67], s[12:13]
	s_branch .Lln2_st_3

.Lln2_st_9:
	s_waitcnt vmcnt(12)
	v_lshlrev_b32_e32 v64, 16, v48
	v_and_b32_e32 v65, 0xffff0000, v48
	v_and_b32_e32 v252, 0xffff0000, v32
	v_lshlrev_b32_e32 v32, 16, v32
	v_fmac_f32_e32 v64, 0x3fb504f3, v32
	v_fmac_f32_e32 v65, 0x3fb504f3, v252
	v_lshlrev_b32_e32 v66, 16, v49
	v_and_b32_e32 v67, 0xffff0000, v49
	v_and_b32_e32 v252, 0xffff0000, v33
	v_lshlrev_b32_e32 v33, 16, v33
	v_fmac_f32_e32 v66, 0x3fb504f3, v33
	v_fmac_f32_e32 v67, 0x3fb504f3, v252
	v_add_f32_e32 v252, v64, v65
	v_add_f32_e32 v253, v66, v67
	v_add_f32_e32 v254, v252, v253
	v_lshlrev_b32_e32 v68, 16, v50
	v_and_b32_e32 v69, 0xffff0000, v50
	v_and_b32_e32 v252, 0xffff0000, v34
	v_lshlrev_b32_e32 v34, 16, v34
	v_fmac_f32_e32 v68, 0x3fb504f3, v34
	v_fmac_f32_e32 v69, 0x3fb504f3, v252
	v_lshlrev_b32_e32 v70, 16, v51
	v_and_b32_e32 v71, 0xffff0000, v51
	v_and_b32_e32 v252, 0xffff0000, v35
	v_lshlrev_b32_e32 v35, 16, v35
	v_fmac_f32_e32 v70, 0x3fb504f3, v35
	v_fmac_f32_e32 v71, 0x3fb504f3, v252
	v_add_f32_e32 v252, v68, v69
	v_add_f32_e32 v253, v70, v71
	v_add_f32_e32 v252, v252, v253
	v_add_f32_e32 v254, v254, v252
	v_lshlrev_b32_e32 v72, 16, v52
	v_and_b32_e32 v73, 0xffff0000, v52
	v_and_b32_e32 v252, 0xffff0000, v36
	v_lshlrev_b32_e32 v36, 16, v36
	v_fmac_f32_e32 v72, 0x3fb504f3, v36
	v_fmac_f32_e32 v73, 0x3fb504f3, v252
	v_lshlrev_b32_e32 v74, 16, v53
	v_and_b32_e32 v75, 0xffff0000, v53
	v_and_b32_e32 v252, 0xffff0000, v37
	v_lshlrev_b32_e32 v37, 16, v37
	v_fmac_f32_e32 v74, 0x3fb504f3, v37
	v_fmac_f32_e32 v75, 0x3fb504f3, v252
	v_add_f32_e32 v252, v72, v73
	v_add_f32_e32 v253, v74, v75
	v_add_f32_e32 v252, v252, v253
	v_add_f32_e32 v254, v254, v252
	v_lshlrev_b32_e32 v76, 16, v54
	v_and_b32_e32 v77, 0xffff0000, v54
	v_and_b32_e32 v252, 0xffff0000, v38
	v_lshlrev_b32_e32 v38, 16, v38
	v_fmac_f32_e32 v76, 0x3fb504f3, v38
	v_fmac_f32_e32 v77, 0x3fb504f3, v252
	v_lshlrev_b32_e32 v78, 16, v55
	v_and_b32_e32 v79, 0xffff0000, v55
	v_and_b32_e32 v252, 0xffff0000, v39
	v_lshlrev_b32_e32 v39, 16, v39
	v_fmac_f32_e32 v78, 0x3fb504f3, v39
	v_fmac_f32_e32 v79, 0x3fb504f3, v252
	v_add_f32_e32 v252, v76, v77
	v_add_f32_e32 v253, v78, v79
	v_add_f32_e32 v252, v252, v253
	v_add_f32_e32 v254, v254, v252
	v_lshlrev_b32_e32 v80, 16, v56
	v_and_b32_e32 v81, 0xffff0000, v56
	v_and_b32_e32 v252, 0xffff0000, v40
	v_lshlrev_b32_e32 v40, 16, v40
	v_fmac_f32_e32 v80, 0x3fb504f3, v40
	v_fmac_f32_e32 v81, 0x3fb504f3, v252
	v_lshlrev_b32_e32 v82, 16, v57
	v_and_b32_e32 v83, 0xffff0000, v57
	v_and_b32_e32 v252, 0xffff0000, v41
	v_lshlrev_b32_e32 v41, 16, v41
	v_fmac_f32_e32 v82, 0x3fb504f3, v41
	v_fmac_f32_e32 v83, 0x3fb504f3, v252
	v_add_f32_e32 v252, v80, v81
	v_add_f32_e32 v253, v82, v83
	v_add_f32_e32 v252, v252, v253
	v_add_f32_e32 v254, v254, v252
	v_lshlrev_b32_e32 v84, 16, v58
	v_and_b32_e32 v85, 0xffff0000, v58
	v_and_b32_e32 v252, 0xffff0000, v42
	v_lshlrev_b32_e32 v42, 16, v42
	v_fmac_f32_e32 v84, 0x3fb504f3, v42
	v_fmac_f32_e32 v85, 0x3fb504f3, v252
	v_lshlrev_b32_e32 v86, 16, v59
	v_and_b32_e32 v87, 0xffff0000, v59
	v_and_b32_e32 v252, 0xffff0000, v43
	v_lshlrev_b32_e32 v43, 16, v43
	v_fmac_f32_e32 v86, 0x3fb504f3, v43
	v_fmac_f32_e32 v87, 0x3fb504f3, v252
	v_add_f32_e32 v252, v84, v85
	v_add_f32_e32 v253, v86, v87
	v_add_f32_e32 v252, v252, v253
	v_add_f32_e32 v254, v254, v252
	v_lshlrev_b32_e32 v244, 16, v60
	v_and_b32_e32 v245, 0xffff0000, v60
	v_and_b32_e32 v252, 0xffff0000, v44
	v_lshlrev_b32_e32 v44, 16, v44
	v_fmac_f32_e32 v244, 0x3fb504f3, v44
	v_fmac_f32_e32 v245, 0x3fb504f3, v252
	v_lshlrev_b32_e32 v246, 16, v61
	v_and_b32_e32 v247, 0xffff0000, v61
	v_and_b32_e32 v252, 0xffff0000, v45
	v_lshlrev_b32_e32 v45, 16, v45
	v_fmac_f32_e32 v246, 0x3fb504f3, v45
	v_fmac_f32_e32 v247, 0x3fb504f3, v252
	v_add_f32_e32 v252, v244, v245
	v_add_f32_e32 v253, v246, v247
	v_add_f32_e32 v252, v252, v253
	v_add_f32_e32 v254, v254, v252
	v_lshlrev_b32_e32 v248, 16, v62
	v_and_b32_e32 v249, 0xffff0000, v62
	v_and_b32_e32 v252, 0xffff0000, v46
	v_lshlrev_b32_e32 v46, 16, v46
	v_fmac_f32_e32 v248, 0x3fb504f3, v46
	v_fmac_f32_e32 v249, 0x3fb504f3, v252
	v_lshlrev_b32_e32 v250, 16, v63
	v_and_b32_e32 v251, 0xffff0000, v63
	v_and_b32_e32 v252, 0xffff0000, v47
	v_lshlrev_b32_e32 v47, 16, v47
	v_fmac_f32_e32 v250, 0x3fb504f3, v47
	v_fmac_f32_e32 v251, 0x3fb504f3, v252
	v_add_f32_e32 v252, v248, v249
	v_add_f32_e32 v253, v250, v251
	v_add_f32_e32 v252, v252, v253
	v_add_f32_e32 v254, v254, v252
	v_readlane_b32 s91, v241, 0
	s_lshl_b32 s30, s91, 14
	v_subrev_u32_e32 v88, s30, v90
	s_add_u32 s12, s8, 0x400000
	s_addc_u32 s13, s9, 0
	global_load_dwordx4 v[32:35], v88, s[12:13]
	global_load_dwordx4 v[36:39], v88, s[12:13] offset:1024
	global_load_dwordx4 v[40:43], v88, s[12:13] offset:2048
	global_load_dwordx4 v[44:47], v88, s[12:13] offset:3072
	s_add_u32 s12, s8, 0x800000
	s_addc_u32 s13, s9, 0
	global_load_dwordx4 v[48:51], v88, s[12:13]
	global_load_dwordx4 v[52:55], v88, s[12:13] offset:1024
	global_load_dwordx4 v[56:59], v88, s[12:13] offset:2048
	global_load_dwordx4 v[60:63], v88, s[12:13] offset:3072
	s_nop 1
	v_add_f32_dpp v252, v254, v254 quad_perm:[1,0,3,2] row_mask:0xf bank_mask:0xf
	s_nop 1
	v_add_f32_dpp v252, v252, v252 quad_perm:[2,3,0,1] row_mask:0xf bank_mask:0xf
	s_nop 1
	v_add_f32_dpp v252, v252, v252 row_half_mirror row_mask:0xf bank_mask:0xf
	s_nop 1
	v_add_f32_dpp v252, v252, v252 row_mirror row_mask:0xf bank_mask:0xf
	s_nop 1
	v_readlane_b32 s86, v252, 0
	v_readlane_b32 s87, v252, 16
	v_readlane_b32 s88, v252, 32
	v_readlane_b32 s89, v252, 48
	s_nop 1
	v_mov_b32_e32 v253, s86
	v_add_f32_e32 v253, s87, v253
	v_add_f32_e32 v253, s88, v253
	v_add_f32_e32 v253, s89, v253
	v_mul_f32_e32 v253, 0x3a000000, v253
	s_nop 0
	v_readfirstlane_b32 s85, v253
	s_nop 1
	v_subrev_f32_e32 v64, s85, v64
	v_subrev_f32_e32 v65, s85, v65
	v_subrev_f32_e32 v66, s85, v66
	v_subrev_f32_e32 v67, s85, v67
	v_subrev_f32_e32 v68, s85, v68
	v_subrev_f32_e32 v69, s85, v69
	v_subrev_f32_e32 v70, s85, v70
	v_subrev_f32_e32 v71, s85, v71
	v_mul_f32_e32 v252, v64, v64
	v_fmac_f32_e32 v252, v65, v65
	v_mul_f32_e32 v253, v66, v66
	v_fmac_f32_e32 v253, v67, v67
	v_add_f32_e32 v254, v252, v253
	v_mul_f32_e32 v252, v68, v68
	v_fmac_f32_e32 v252, v69, v69
	v_mul_f32_e32 v253, v70, v70
	v_fmac_f32_e32 v253, v71, v71
	v_add_f32_e32 v252, v252, v253
	v_add_f32_e32 v254, v254, v252
	v_subrev_f32_e32 v72, s85, v72
	v_subrev_f32_e32 v73, s85, v73
	v_subrev_f32_e32 v74, s85, v74
	v_subrev_f32_e32 v75, s85, v75
	v_subrev_f32_e32 v76, s85, v76
	v_subrev_f32_e32 v77, s85, v77
	v_subrev_f32_e32 v78, s85, v78
	v_subrev_f32_e32 v79, s85, v79
	v_mul_f32_e32 v252, v72, v72
	v_fmac_f32_e32 v252, v73, v73
	v_mul_f32_e32 v253, v74, v74
	v_fmac_f32_e32 v253, v75, v75
	v_add_f32_e32 v252, v252, v253
	v_add_f32_e32 v254, v254, v252
	v_mul_f32_e32 v252, v76, v76
	v_fmac_f32_e32 v252, v77, v77
	v_mul_f32_e32 v253, v78, v78
	v_fmac_f32_e32 v253, v79, v79
	v_add_f32_e32 v252, v252, v253
	v_add_f32_e32 v254, v254, v252
	v_subrev_f32_e32 v80, s85, v80
	v_subrev_f32_e32 v81, s85, v81
	v_subrev_f32_e32 v82, s85, v82
	v_subrev_f32_e32 v83, s85, v83
	v_subrev_f32_e32 v84, s85, v84
	v_subrev_f32_e32 v85, s85, v85
	v_subrev_f32_e32 v86, s85, v86
	v_subrev_f32_e32 v87, s85, v87
	v_mul_f32_e32 v252, v80, v80
	v_fmac_f32_e32 v252, v81, v81
	v_mul_f32_e32 v253, v82, v82
	v_fmac_f32_e32 v253, v83, v83
	v_add_f32_e32 v252, v252, v253
	v_add_f32_e32 v254, v254, v252
	v_mul_f32_e32 v252, v84, v84
	v_fmac_f32_e32 v252, v85, v85
	v_mul_f32_e32 v253, v86, v86
	v_fmac_f32_e32 v253, v87, v87
	v_add_f32_e32 v252, v252, v253
	v_add_f32_e32 v254, v254, v252
	v_subrev_f32_e32 v244, s85, v244
	v_subrev_f32_e32 v245, s85, v245
	v_subrev_f32_e32 v246, s85, v246
	v_subrev_f32_e32 v247, s85, v247
	v_subrev_f32_e32 v248, s85, v248
	v_subrev_f32_e32 v249, s85, v249
	v_subrev_f32_e32 v250, s85, v250
	v_subrev_f32_e32 v251, s85, v251
	v_mul_f32_e32 v252, v244, v244
	v_fmac_f32_e32 v252, v245, v245
	v_mul_f32_e32 v253, v246, v246
	v_fmac_f32_e32 v253, v247, v247
	v_add_f32_e32 v252, v252, v253
	v_add_f32_e32 v254, v254, v252
	v_mul_f32_e32 v252, v248, v248
	v_fmac_f32_e32 v252, v249, v249
	v_mul_f32_e32 v253, v250, v250
	v_fmac_f32_e32 v253, v251, v251
	v_add_f32_e32 v252, v252, v253
	v_add_f32_e32 v254, v254, v252
	s_nop 1
	v_add_f32_dpp v252, v254, v254 quad_perm:[1,0,3,2] row_mask:0xf bank_mask:0xf
	s_nop 1
	v_add_f32_dpp v252, v252, v252 quad_perm:[2,3,0,1] row_mask:0xf bank_mask:0xf
	s_nop 1
	v_add_f32_dpp v252, v252, v252 row_half_mirror row_mask:0xf bank_mask:0xf
	s_nop 1
	v_add_f32_dpp v252, v252, v252 row_mirror row_mask:0xf bank_mask:0xf
	s_nop 1
	v_readlane_b32 s86, v252, 0
	v_readlane_b32 s87, v252, 16
	v_readlane_b32 s88, v252, 32
	v_readlane_b32 s89, v252, 48
	s_nop 1
	v_mov_b32_e32 v253, s86
	v_add_f32_e32 v253, s87, v253
	v_add_f32_e32 v253, s88, v253
	v_add_f32_e32 v253, s89, v253
	v_mov_b32_e32 v252, 0x3a000000
	v_fmaak_f32 v253, v253, v252, 0x3727c5ac
	v_rsq_f32_e32 v253, v253
	s_nop 1
	v_readfirstlane_b32 s85, v253
	s_add_u32 s12, s4, 0x800000
	s_addc_u32 s13, s5, 0
	v_readlane_b32 s86, v241, 7
	v_readlane_b32 s87, v241, 8
	s_add_u32 s86, s86, 0x1000000
	s_addc_u32 s87, s87, 0
	s_add_u32 s88, s86, 0x1000
	s_addc_u32 s89, s87, 0
	ds_read_b64 v[252:253], v168
	ds_read_b64 v[254:255], v168 offset:8192
	ds_read_b64 v[88:89], v168 offset:512
	ds_read_b64 v[242:243], v168 offset:8704
	s_waitcnt lgkmcnt(2)
	v_mul_f32_e32 v64, s85, v64
	v_mul_f32_e32 v65, s85, v65
	v_fma_f32 v64, v64, v252, v254
	v_fma_f32 v65, v65, v253, v255
	ds_read_b64 v[252:253], v168 offset:1024
	ds_read_b64 v[254:255], v168 offset:9216
	s_waitcnt lgkmcnt(2)
	v_mul_f32_e32 v66, s85, v66
	v_mul_f32_e32 v67, s85, v67
	v_fma_f32 v66, v66, v88, v242
	v_fma_f32 v67, v67, v89, v243
	ds_read_b64 v[88:89], v168 offset:1536
	ds_read_b64 v[242:243], v168 offset:9728
	s_waitcnt lgkmcnt(2)
	v_mul_f32_e32 v68, s85, v68
	v_mul_f32_e32 v69, s85, v69
	v_fma_f32 v68, v68, v252, v254
	v_fma_f32 v69, v69, v253, v255
	ds_read_b64 v[252:253], v168 offset:2048
	ds_read_b64 v[254:255], v168 offset:10240
	s_waitcnt lgkmcnt(2)
	v_mul_f32_e32 v70, s85, v70
	v_mul_f32_e32 v71, s85, v71
	v_fma_f32 v70, v70, v88, v242
	v_fma_f32 v71, v71, v89, v243
	s_cmp_lg_u32 s90, 0
	s_cbranch_scc1 .Lln2_f32_10
	v_cvt_pk_bf16_f32 v64, v64, v65
	v_cvt_pk_bf16_f32 v65, v66, v67
	v_cvt_pk_bf16_f32 v66, v68, v69
	v_cvt_pk_bf16_f32 v67, v70, v71
	global_store_dwordx4 v90, v[64:67], s[12:13]
	s_branch .Lln2_st_11

.Lln2_st_17:
	s_waitcnt vmcnt(16)
	v_lshlrev_b32_e32 v64, 16, v16
	v_and_b32_e32 v65, 0xffff0000, v16
	v_and_b32_e32 v252, 0xffff0000, v0
	v_lshlrev_b32_e32 v0, 16, v0
	v_fmac_f32_e32 v64, 0x3fb504f3, v0
	v_fmac_f32_e32 v65, 0x3fb504f3, v252
	v_lshlrev_b32_e32 v66, 16, v17
	v_and_b32_e32 v67, 0xffff0000, v17
	v_and_b32_e32 v252, 0xffff0000, v1
	v_lshlrev_b32_e32 v1, 16, v1
	v_fmac_f32_e32 v66, 0x3fb504f3, v1
	v_fmac_f32_e32 v67, 0x3fb504f3, v252
	v_add_f32_e32 v252, v64, v65
	v_add_f32_e32 v253, v66, v67
	v_add_f32_e32 v254, v252, v253
	v_lshlrev_b32_e32 v68, 16, v18
	v_and_b32_e32 v69, 0xffff0000, v18
	v_and_b32_e32 v252, 0xffff0000, v2
	v_lshlrev_b32_e32 v2, 16, v2
	v_fmac_f32_e32 v68, 0x3fb504f3, v2
	v_fmac_f32_e32 v69, 0x3fb504f3, v252
	v_lshlrev_b32_e32 v70, 16, v19
	v_and_b32_e32 v71, 0xffff0000, v19
	v_and_b32_e32 v252, 0xffff0000, v3
	v_lshlrev_b32_e32 v3, 16, v3
	v_fmac_f32_e32 v70, 0x3fb504f3, v3
	v_fmac_f32_e32 v71, 0x3fb504f3, v252
	v_add_f32_e32 v252, v68, v69
	v_add_f32_e32 v253, v70, v71
	v_add_f32_e32 v252, v252, v253
	v_add_f32_e32 v254, v254, v252
	v_lshlrev_b32_e32 v72, 16, v20
	v_and_b32_e32 v73, 0xffff0000, v20
	v_and_b32_e32 v252, 0xffff0000, v4
	v_lshlrev_b32_e32 v4, 16, v4
	v_fmac_f32_e32 v72, 0x3fb504f3, v4
	v_fmac_f32_e32 v73, 0x3fb504f3, v252
	v_lshlrev_b32_e32 v74, 16, v21
	v_and_b32_e32 v75, 0xffff0000, v21
	v_and_b32_e32 v252, 0xffff0000, v5
	v_lshlrev_b32_e32 v5, 16, v5
	v_fmac_f32_e32 v74, 0x3fb504f3, v5
	v_fmac_f32_e32 v75, 0x3fb504f3, v252
	v_add_f32_e32 v252, v72, v73
	v_add_f32_e32 v253, v74, v75
	v_add_f32_e32 v252, v252, v253
	v_add_f32_e32 v254, v254, v252
	v_lshlrev_b32_e32 v76, 16, v22
	v_and_b32_e32 v77, 0xffff0000, v22
	v_and_b32_e32 v252, 0xffff0000, v6
	v_lshlrev_b32_e32 v6, 16, v6
	v_fmac_f32_e32 v76, 0x3fb504f3, v6
	v_fmac_f32_e32 v77, 0x3fb504f3, v252
	v_lshlrev_b32_e32 v78, 16, v23
	v_and_b32_e32 v79, 0xffff0000, v23
	v_and_b32_e32 v252, 0xffff0000, v7
	v_lshlrev_b32_e32 v7, 16, v7
	v_fmac_f32_e32 v78, 0x3fb504f3, v7
	v_fmac_f32_e32 v79, 0x3fb504f3, v252
	v_add_f32_e32 v252, v76, v77
	v_add_f32_e32 v253, v78, v79
	v_add_f32_e32 v252, v252, v253
	v_add_f32_e32 v254, v254, v252
	v_lshlrev_b32_e32 v80, 16, v24
	v_and_b32_e32 v81, 0xffff0000, v24
	v_and_b32_e32 v252, 0xffff0000, v8
	v_lshlrev_b32_e32 v8, 16, v8
	v_fmac_f32_e32 v80, 0x3fb504f3, v8
	v_fmac_f32_e32 v81, 0x3fb504f3, v252
	v_lshlrev_b32_e32 v82, 16, v25
	v_and_b32_e32 v83, 0xffff0000, v25
	v_and_b32_e32 v252, 0xffff0000, v9
	v_lshlrev_b32_e32 v9, 16, v9
	v_fmac_f32_e32 v82, 0x3fb504f3, v9
	v_fmac_f32_e32 v83, 0x3fb504f3, v252
	v_add_f32_e32 v252, v80, v81
	v_add_f32_e32 v253, v82, v83
	v_add_f32_e32 v252, v252, v253
	v_add_f32_e32 v254, v254, v252
	v_lshlrev_b32_e32 v84, 16, v26
	v_and_b32_e32 v85, 0xffff0000, v26
	v_and_b32_e32 v252, 0xffff0000, v10
	v_lshlrev_b32_e32 v10, 16, v10
	v_fmac_f32_e32 v84, 0x3fb504f3, v10
	v_fmac_f32_e32 v85, 0x3fb504f3, v252
	v_lshlrev_b32_e32 v86, 16, v27
	v_and_b32_e32 v87, 0xffff0000, v27
	v_and_b32_e32 v252, 0xffff0000, v11
	v_lshlrev_b32_e32 v11, 16, v11
	v_fmac_f32_e32 v86, 0x3fb504f3, v11
	v_fmac_f32_e32 v87, 0x3fb504f3, v252
	v_add_f32_e32 v252, v84, v85
	v_add_f32_e32 v253, v86, v87
	v_add_f32_e32 v252, v252, v253
	v_add_f32_e32 v254, v254, v252
	v_lshlrev_b32_e32 v244, 16, v28
	v_and_b32_e32 v245, 0xffff0000, v28
	v_and_b32_e32 v252, 0xffff0000, v12
	v_lshlrev_b32_e32 v12, 16, v12
	v_fmac_f32_e32 v244, 0x3fb504f3, v12
	v_fmac_f32_e32 v245, 0x3fb504f3, v252
	v_lshlrev_b32_e32 v246, 16, v29
	v_and_b32_e32 v247, 0xffff0000, v29
	v_and_b32_e32 v252, 0xffff0000, v13
	v_lshlrev_b32_e32 v13, 16, v13
	v_fmac_f32_e32 v246, 0x3fb504f3, v13
	v_fmac_f32_e32 v247, 0x3fb504f3, v252
	v_add_f32_e32 v252, v244, v245
	v_add_f32_e32 v253, v246, v247
	v_add_f32_e32 v252, v252, v253
	v_add_f32_e32 v254, v254, v252
	v_lshlrev_b32_e32 v248, 16, v30
	v_and_b32_e32 v249, 0xffff0000, v30
	v_and_b32_e32 v252, 0xffff0000, v14
	v_lshlrev_b32_e32 v14, 16, v14
	v_fmac_f32_e32 v248, 0x3fb504f3, v14
	v_fmac_f32_e32 v249, 0x3fb504f3, v252
	v_lshlrev_b32_e32 v250, 16, v31
	v_and_b32_e32 v251, 0xffff0000, v31
	v_and_b32_e32 v252, 0xffff0000, v15
	v_lshlrev_b32_e32 v15, 16, v15
	v_fmac_f32_e32 v250, 0x3fb504f3, v15
	v_fmac_f32_e32 v251, 0x3fb504f3, v252
	v_add_f32_e32 v252, v248, v249
	v_add_f32_e32 v253, v250, v251
	v_add_f32_e32 v252, v252, v253
	v_add_f32_e32 v254, v254, v252
	v_readlane_b32 s91, v241, 0
	s_lshl_b32 s30, s91, 14
	v_subrev_u32_e32 v88, s30, v90
	s_add_u32 s12, s4, 0x2000000
	s_addc_u32 s13, s5, 0
	global_load_dwordx4 v[0:3], v88, s[12:13]
	global_load_dwordx4 v[4:7], v88, s[12:13] offset:1024
	global_load_dwordx4 v[8:11], v88, s[12:13] offset:2048
	global_load_dwordx4 v[12:15], v88, s[12:13] offset:3072
	global_load_dwordx4 v[16:19], v88, s[8:9]
	global_load_dwordx4 v[20:23], v88, s[8:9] offset:1024
	global_load_dwordx4 v[24:27], v88, s[8:9] offset:2048
	global_load_dwordx4 v[28:31], v88, s[8:9] offset:3072
	s_nop 1
	v_add_f32_dpp v252, v254, v254 quad_perm:[1,0,3,2] row_mask:0xf bank_mask:0xf
	s_nop 1
	v_add_f32_dpp v252, v252, v252 quad_perm:[2,3,0,1] row_mask:0xf bank_mask:0xf
	s_nop 1
	v_add_f32_dpp v252, v252, v252 row_half_mirror row_mask:0xf bank_mask:0xf
	s_nop 1
	v_add_f32_dpp v252, v252, v252 row_mirror row_mask:0xf bank_mask:0xf
	s_nop 1
	v_readlane_b32 s86, v252, 0
	v_readlane_b32 s87, v252, 16
	v_readlane_b32 s88, v252, 32
	v_readlane_b32 s89, v252, 48
	s_nop 1
	v_mov_b32_e32 v253, s86
	v_add_f32_e32 v253, s87, v253
	v_add_f32_e32 v253, s88, v253
	v_add_f32_e32 v253, s89, v253
	v_mul_f32_e32 v253, 0x3a000000, v253
	s_nop 0
	v_readfirstlane_b32 s85, v253
	s_nop 1
	v_subrev_f32_e32 v64, s85, v64
	v_subrev_f32_e32 v65, s85, v65
	v_subrev_f32_e32 v66, s85, v66
	v_subrev_f32_e32 v67, s85, v67
	v_subrev_f32_e32 v68, s85, v68
	v_subrev_f32_e32 v69, s85, v69
	v_subrev_f32_e32 v70, s85, v70
	v_subrev_f32_e32 v71, s85, v71
	v_mul_f32_e32 v252, v64, v64
	v_fmac_f32_e32 v252, v65, v65
	v_mul_f32_e32 v253, v66, v66
	v_fmac_f32_e32 v253, v67, v67
	v_add_f32_e32 v254, v252, v253
	v_mul_f32_e32 v252, v68, v68
	v_fmac_f32_e32 v252, v69, v69
	v_mul_f32_e32 v253, v70, v70
	v_fmac_f32_e32 v253, v71, v71
	v_add_f32_e32 v252, v252, v253
	v_add_f32_e32 v254, v254, v252
	v_subrev_f32_e32 v72, s85, v72
	v_subrev_f32_e32 v73, s85, v73
	v_subrev_f32_e32 v74, s85, v74
	v_subrev_f32_e32 v75, s85, v75
	v_subrev_f32_e32 v76, s85, v76
	v_subrev_f32_e32 v77, s85, v77
	v_subrev_f32_e32 v78, s85, v78
	v_subrev_f32_e32 v79, s85, v79
	v_mul_f32_e32 v252, v72, v72
	v_fmac_f32_e32 v252, v73, v73
	v_mul_f32_e32 v253, v74, v74
	v_fmac_f32_e32 v253, v75, v75
	v_add_f32_e32 v252, v252, v253
	v_add_f32_e32 v254, v254, v252
	v_mul_f32_e32 v252, v76, v76
	v_fmac_f32_e32 v252, v77, v77
	v_mul_f32_e32 v253, v78, v78
	v_fmac_f32_e32 v253, v79, v79
	v_add_f32_e32 v252, v252, v253
	v_add_f32_e32 v254, v254, v252
	v_subrev_f32_e32 v80, s85, v80
	v_subrev_f32_e32 v81, s85, v81
	v_subrev_f32_e32 v82, s85, v82
	v_subrev_f32_e32 v83, s85, v83
	v_subrev_f32_e32 v84, s85, v84
	v_subrev_f32_e32 v85, s85, v85
	v_subrev_f32_e32 v86, s85, v86
	v_subrev_f32_e32 v87, s85, v87
	v_mul_f32_e32 v252, v80, v80
	v_fmac_f32_e32 v252, v81, v81
	v_mul_f32_e32 v253, v82, v82
	v_fmac_f32_e32 v253, v83, v83
	v_add_f32_e32 v252, v252, v253
	v_add_f32_e32 v254, v254, v252
	v_mul_f32_e32 v252, v84, v84
	v_fmac_f32_e32 v252, v85, v85
	v_mul_f32_e32 v253, v86, v86
	v_fmac_f32_e32 v253, v87, v87
	v_add_f32_e32 v252, v252, v253
	v_add_f32_e32 v254, v254, v252
	v_subrev_f32_e32 v244, s85, v244
	v_subrev_f32_e32 v245, s85, v245
	v_subrev_f32_e32 v246, s85, v246
	v_subrev_f32_e32 v247, s85, v247
	v_subrev_f32_e32 v248, s85, v248
	v_subrev_f32_e32 v249, s85, v249
	v_subrev_f32_e32 v250, s85, v250
	v_subrev_f32_e32 v251, s85, v251
	v_mul_f32_e32 v252, v244, v244
	v_fmac_f32_e32 v252, v245, v245
	v_mul_f32_e32 v253, v246, v246
	v_fmac_f32_e32 v253, v247, v247
	v_add_f32_e32 v252, v252, v253
	v_add_f32_e32 v254, v254, v252
	v_mul_f32_e32 v252, v248, v248
	v_fmac_f32_e32 v252, v249, v249
	v_mul_f32_e32 v253, v250, v250
	v_fmac_f32_e32 v253, v251, v251
	v_add_f32_e32 v252, v252, v253
	v_add_f32_e32 v254, v254, v252
	s_nop 1
	v_add_f32_dpp v252, v254, v254 quad_perm:[1,0,3,2] row_mask:0xf bank_mask:0xf
	s_nop 1
	v_add_f32_dpp v252, v252, v252 quad_perm:[2,3,0,1] row_mask:0xf bank_mask:0xf
	s_nop 1
	v_add_f32_dpp v252, v252, v252 row_half_mirror row_mask:0xf bank_mask:0xf
	s_nop 1
	v_add_f32_dpp v252, v252, v252 row_mirror row_mask:0xf bank_mask:0xf
	s_nop 1
	v_readlane_b32 s86, v252, 0
	v_readlane_b32 s87, v252, 16
	v_readlane_b32 s88, v252, 32
	v_readlane_b32 s89, v252, 48
	s_nop 1
	v_mov_b32_e32 v253, s86
	v_add_f32_e32 v253, s87, v253
	v_add_f32_e32 v253, s88, v253
	v_add_f32_e32 v253, s89, v253
	v_mov_b32_e32 v252, 0x3a000000
	v_fmaak_f32 v253, v253, v252, 0x3727c5ac
	v_rsq_f32_e32 v253, v253
	s_nop 1
	v_readfirstlane_b32 s85, v253
	s_add_u32 s12, s4, 0x1000000
	s_addc_u32 s13, s5, 0
	v_readlane_b32 s86, v241, 7
	v_readlane_b32 s87, v241, 8
	s_add_u32 s86, s86, 0x2000000
	s_addc_u32 s87, s87, 0
	s_add_u32 s88, s86, 0x1000
	s_addc_u32 s89, s87, 0
	ds_read_b64 v[252:253], v168
	ds_read_b64 v[254:255], v168 offset:8192
	ds_read_b64 v[88:89], v168 offset:512
	ds_read_b64 v[242:243], v168 offset:8704
	s_waitcnt lgkmcnt(2)
	v_mul_f32_e32 v64, s85, v64
	v_mul_f32_e32 v65, s85, v65
	v_fma_f32 v64, v64, v252, v254
	v_fma_f32 v65, v65, v253, v255
	ds_read_b64 v[252:253], v168 offset:1024
	ds_read_b64 v[254:255], v168 offset:9216
	s_waitcnt lgkmcnt(2)
	v_mul_f32_e32 v66, s85, v66
	v_mul_f32_e32 v67, s85, v67
	v_fma_f32 v66, v66, v88, v242
	v_fma_f32 v67, v67, v89, v243
	ds_read_b64 v[88:89], v168 offset:1536
	ds_read_b64 v[242:243], v168 offset:9728
	s_waitcnt lgkmcnt(2)
	v_mul_f32_e32 v68, s85, v68
	v_mul_f32_e32 v69, s85, v69
	v_fma_f32 v68, v68, v252, v254
	v_fma_f32 v69, v69, v253, v255
	ds_read_b64 v[252:253], v168 offset:2048
	ds_read_b64 v[254:255], v168 offset:10240
	s_waitcnt lgkmcnt(2)
	v_mul_f32_e32 v70, s85, v70
	v_mul_f32_e32 v71, s85, v71
	v_fma_f32 v70, v70, v88, v242
	v_fma_f32 v71, v71, v89, v243
	s_cmp_lg_u32 s90, 0
	s_cbranch_scc1 .Lln2_f32_18
	v_cvt_pk_bf16_f32 v64, v64, v65
	v_cvt_pk_bf16_f32 v65, v66, v67
	v_cvt_pk_bf16_f32 v66, v68, v69
	v_cvt_pk_bf16_f32 v67, v70, v71
	global_store_dwordx4 v90, v[64:67], s[12:13]
	s_branch .Lln2_st_19

.Lln2_st_25:
	v_readlane_b32 s91, v241, 0
	s_lshl_b32 s30, s91, 14
	v_subrev_u32_e32 v90, s30, v90
	s_waitcnt vmcnt(4)
	v_lshlrev_b32_e32 v64, 16, v16
	v_and_b32_e32 v65, 0xffff0000, v16
	v_lshlrev_b32_e32 v66, 16, v17
	v_and_b32_e32 v67, 0xffff0000, v17
	v_lshlrev_b32_e32 v68, 16, v18
	v_and_b32_e32 v69, 0xffff0000, v18
	v_lshlrev_b32_e32 v70, 16, v19
	v_and_b32_e32 v71, 0xffff0000, v19
	v_lshlrev_b32_e32 v72, 16, v20
	v_and_b32_e32 v73, 0xffff0000, v20
	v_lshlrev_b32_e32 v74, 16, v21
	v_and_b32_e32 v75, 0xffff0000, v21
	v_lshlrev_b32_e32 v76, 16, v22
	v_and_b32_e32 v77, 0xffff0000, v22
	v_lshlrev_b32_e32 v78, 16, v23
	v_and_b32_e32 v79, 0xffff0000, v23
	v_lshlrev_b32_e32 v80, 16, v24
	v_and_b32_e32 v81, 0xffff0000, v24
	v_lshlrev_b32_e32 v82, 16, v25
	v_and_b32_e32 v83, 0xffff0000, v25
	v_lshlrev_b32_e32 v84, 16, v26
	v_and_b32_e32 v85, 0xffff0000, v26
	v_lshlrev_b32_e32 v86, 16, v27
	v_and_b32_e32 v87, 0xffff0000, v27
	v_lshlrev_b32_e32 v244, 16, v28
	v_and_b32_e32 v245, 0xffff0000, v28
	v_lshlrev_b32_e32 v246, 16, v29
	v_and_b32_e32 v247, 0xffff0000, v29
	v_lshlrev_b32_e32 v248, 16, v30
	v_and_b32_e32 v249, 0xffff0000, v30
	v_lshlrev_b32_e32 v250, 16, v31
	v_and_b32_e32 v251, 0xffff0000, v31
	s_add_u32 s12, s8, 0xc00000
	s_addc_u32 s13, s9, 0
	global_load_dwordx4 v[16:19], v90, s[12:13]
	global_load_dwordx4 v[20:23], v90, s[12:13] offset:1024
	global_load_dwordx4 v[24:27], v90, s[12:13] offset:2048
	global_load_dwordx4 v[28:31], v90, s[12:13] offset:3072
	v_lshlrev_b32_e32 v252, 16, v32
	v_and_b32_e32 v253, 0xffff0000, v32
	v_add_f32_e32 v64, v64, v252
	v_add_f32_e32 v65, v65, v253
	v_lshlrev_b32_e32 v252, 16, v33
	v_and_b32_e32 v253, 0xffff0000, v33
	v_add_f32_e32 v66, v66, v252
	v_add_f32_e32 v67, v67, v253
	v_lshlrev_b32_e32 v252, 16, v34
	v_and_b32_e32 v253, 0xffff0000, v34
	v_add_f32_e32 v68, v68, v252
	v_add_f32_e32 v69, v69, v253
	v_lshlrev_b32_e32 v252, 16, v35
	v_and_b32_e32 v253, 0xffff0000, v35
	v_add_f32_e32 v70, v70, v252
	v_add_f32_e32 v71, v71, v253
	v_lshlrev_b32_e32 v252, 16, v36
	v_and_b32_e32 v253, 0xffff0000, v36
	v_add_f32_e32 v72, v72, v252
	v_add_f32_e32 v73, v73, v253
	v_lshlrev_b32_e32 v252, 16, v37
	v_and_b32_e32 v253, 0xffff0000, v37
	v_add_f32_e32 v74, v74, v252
	v_add_f32_e32 v75, v75, v253
	v_lshlrev_b32_e32 v252, 16, v38
	v_and_b32_e32 v253, 0xffff0000, v38
	v_add_f32_e32 v76, v76, v252
	v_add_f32_e32 v77, v77, v253
	v_lshlrev_b32_e32 v252, 16, v39
	v_and_b32_e32 v253, 0xffff0000, v39
	v_add_f32_e32 v78, v78, v252
	v_add_f32_e32 v79, v79, v253
	v_lshlrev_b32_e32 v252, 16, v40
	v_and_b32_e32 v253, 0xffff0000, v40
	v_add_f32_e32 v80, v80, v252
	v_add_f32_e32 v81, v81, v253
	v_lshlrev_b32_e32 v252, 16, v41
	v_and_b32_e32 v253, 0xffff0000, v41
	v_add_f32_e32 v82, v82, v252
	v_add_f32_e32 v83, v83, v253
	v_lshlrev_b32_e32 v252, 16, v42
	v_and_b32_e32 v253, 0xffff0000, v42
	v_add_f32_e32 v84, v84, v252
	v_add_f32_e32 v85, v85, v253
	v_lshlrev_b32_e32 v252, 16, v43
	v_and_b32_e32 v253, 0xffff0000, v43
	v_add_f32_e32 v86, v86, v252
	v_add_f32_e32 v87, v87, v253
	v_lshlrev_b32_e32 v252, 16, v44
	v_and_b32_e32 v253, 0xffff0000, v44
	v_add_f32_e32 v244, v244, v252
	v_add_f32_e32 v245, v245, v253
	v_lshlrev_b32_e32 v252, 16, v45
	v_and_b32_e32 v253, 0xffff0000, v45
	v_add_f32_e32 v246, v246, v252
	v_add_f32_e32 v247, v247, v253
	v_lshlrev_b32_e32 v252, 16, v46
	v_and_b32_e32 v253, 0xffff0000, v46
	v_add_f32_e32 v248, v248, v252
	v_add_f32_e32 v249, v249, v253
	v_lshlrev_b32_e32 v252, 16, v47
	v_and_b32_e32 v253, 0xffff0000, v47
	v_add_f32_e32 v250, v250, v252
	v_add_f32_e32 v251, v251, v253
	s_add_u32 s12, s8, 0x1000000
	s_addc_u32 s13, s9, 0
	global_load_dwordx4 v[32:35], v90, s[12:13]
	global_load_dwordx4 v[36:39], v90, s[12:13] offset:1024
	global_load_dwordx4 v[40:43], v90, s[12:13] offset:2048
	global_load_dwordx4 v[44:47], v90, s[12:13] offset:3072
	v_lshlrev_b32_e32 v252, 16, v48
	v_and_b32_e32 v253, 0xffff0000, v48
	v_add_f32_e32 v64, v64, v252
	v_add_f32_e32 v65, v65, v253
	v_lshlrev_b32_e32 v252, 16, v49
	v_and_b32_e32 v253, 0xffff0000, v49
	v_add_f32_e32 v66, v66, v252
	v_add_f32_e32 v67, v67, v253
	v_lshlrev_b32_e32 v252, 16, v50
	v_and_b32_e32 v253, 0xffff0000, v50
	v_add_f32_e32 v68, v68, v252
	v_add_f32_e32 v69, v69, v253
	v_lshlrev_b32_e32 v252, 16, v51
	v_and_b32_e32 v253, 0xffff0000, v51
	v_add_f32_e32 v70, v70, v252
	v_add_f32_e32 v71, v71, v253
	v_lshlrev_b32_e32 v252, 16, v52
	v_and_b32_e32 v253, 0xffff0000, v52
	v_add_f32_e32 v72, v72, v252
	v_add_f32_e32 v73, v73, v253
	v_lshlrev_b32_e32 v252, 16, v53
	v_and_b32_e32 v253, 0xffff0000, v53
	v_add_f32_e32 v74, v74, v252
	v_add_f32_e32 v75, v75, v253
	v_lshlrev_b32_e32 v252, 16, v54
	v_and_b32_e32 v253, 0xffff0000, v54
	v_add_f32_e32 v76, v76, v252
	v_add_f32_e32 v77, v77, v253
	v_lshlrev_b32_e32 v252, 16, v55
	v_and_b32_e32 v253, 0xffff0000, v55
	v_add_f32_e32 v78, v78, v252
	v_add_f32_e32 v79, v79, v253
	v_lshlrev_b32_e32 v252, 16, v56
	v_and_b32_e32 v253, 0xffff0000, v56
	v_add_f32_e32 v80, v80, v252
	v_add_f32_e32 v81, v81, v253
	v_lshlrev_b32_e32 v252, 16, v57
	v_and_b32_e32 v253, 0xffff0000, v57
	v_add_f32_e32 v82, v82, v252
	v_add_f32_e32 v83, v83, v253
	v_lshlrev_b32_e32 v252, 16, v58
	v_and_b32_e32 v253, 0xffff0000, v58
	v_add_f32_e32 v84, v84, v252
	v_add_f32_e32 v85, v85, v253
	v_lshlrev_b32_e32 v252, 16, v59
	v_and_b32_e32 v253, 0xffff0000, v59
	v_add_f32_e32 v86, v86, v252
	v_add_f32_e32 v87, v87, v253
	v_lshlrev_b32_e32 v252, 16, v60
	v_and_b32_e32 v253, 0xffff0000, v60
	v_add_f32_e32 v244, v244, v252
	v_add_f32_e32 v245, v245, v253
	v_lshlrev_b32_e32 v252, 16, v61
	v_and_b32_e32 v253, 0xffff0000, v61
	v_add_f32_e32 v246, v246, v252
	v_add_f32_e32 v247, v247, v253
	v_lshlrev_b32_e32 v252, 16, v62
	v_and_b32_e32 v253, 0xffff0000, v62
	v_add_f32_e32 v248, v248, v252
	v_add_f32_e32 v249, v249, v253
	v_lshlrev_b32_e32 v252, 16, v63
	v_and_b32_e32 v253, 0xffff0000, v63
	v_add_f32_e32 v250, v250, v252
	v_add_f32_e32 v251, v251, v253
	s_add_u32 s12, s8, 0x1400000
	s_addc_u32 s13, s9, 0
	global_load_dwordx4 v[48:51], v90, s[12:13]
	global_load_dwordx4 v[52:55], v90, s[12:13] offset:1024
	global_load_dwordx4 v[56:59], v90, s[12:13] offset:2048
	global_load_dwordx4 v[60:63], v90, s[12:13] offset:3072
	s_waitcnt vmcnt(8)
	v_lshlrev_b32_e32 v252, 16, v16
	v_and_b32_e32 v253, 0xffff0000, v16
	v_add_f32_e32 v64, v64, v252
	v_add_f32_e32 v65, v65, v253
	v_lshlrev_b32_e32 v252, 16, v17
	v_and_b32_e32 v253, 0xffff0000, v17
	v_add_f32_e32 v66, v66, v252
	v_add_f32_e32 v67, v67, v253
	v_lshlrev_b32_e32 v252, 16, v18
	v_and_b32_e32 v253, 0xffff0000, v18
	v_add_f32_e32 v68, v68, v252
	v_add_f32_e32 v69, v69, v253
	v_lshlrev_b32_e32 v252, 16, v19
	v_and_b32_e32 v253, 0xffff0000, v19
	v_add_f32_e32 v70, v70, v252
	v_add_f32_e32 v71, v71, v253
	v_lshlrev_b32_e32 v252, 16, v20
	v_and_b32_e32 v253, 0xffff0000, v20
	v_add_f32_e32 v72, v72, v252
	v_add_f32_e32 v73, v73, v253
	v_lshlrev_b32_e32 v252, 16, v21
	v_and_b32_e32 v253, 0xffff0000, v21
	v_add_f32_e32 v74, v74, v252
	v_add_f32_e32 v75, v75, v253
	v_lshlrev_b32_e32 v252, 16, v22
	v_and_b32_e32 v253, 0xffff0000, v22
	v_add_f32_e32 v76, v76, v252
	v_add_f32_e32 v77, v77, v253
	v_lshlrev_b32_e32 v252, 16, v23
	v_and_b32_e32 v253, 0xffff0000, v23
	v_add_f32_e32 v78, v78, v252
	v_add_f32_e32 v79, v79, v253
	v_lshlrev_b32_e32 v252, 16, v24
	v_and_b32_e32 v253, 0xffff0000, v24
	v_add_f32_e32 v80, v80, v252
	v_add_f32_e32 v81, v81, v253
	v_lshlrev_b32_e32 v252, 16, v25
	v_and_b32_e32 v253, 0xffff0000, v25
	v_add_f32_e32 v82, v82, v252
	v_add_f32_e32 v83, v83, v253
	v_lshlrev_b32_e32 v252, 16, v26
	v_and_b32_e32 v253, 0xffff0000, v26
	v_add_f32_e32 v84, v84, v252
	v_add_f32_e32 v85, v85, v253
	v_lshlrev_b32_e32 v252, 16, v27
	v_and_b32_e32 v253, 0xffff0000, v27
	v_add_f32_e32 v86, v86, v252
	v_add_f32_e32 v87, v87, v253
	v_lshlrev_b32_e32 v252, 16, v28
	v_and_b32_e32 v253, 0xffff0000, v28
	v_add_f32_e32 v244, v244, v252
	v_add_f32_e32 v245, v245, v253
	v_lshlrev_b32_e32 v252, 16, v29
	v_and_b32_e32 v253, 0xffff0000, v29
	v_add_f32_e32 v246, v246, v252
	v_add_f32_e32 v247, v247, v253
	v_lshlrev_b32_e32 v252, 16, v30
	v_and_b32_e32 v253, 0xffff0000, v30
	v_add_f32_e32 v248, v248, v252
	v_add_f32_e32 v249, v249, v253
	v_lshlrev_b32_e32 v252, 16, v31
	v_and_b32_e32 v253, 0xffff0000, v31
	v_add_f32_e32 v250, v250, v252
	v_add_f32_e32 v251, v251, v253
	s_add_u32 s12, s8, 0x1800000
	s_addc_u32 s13, s9, 0
	global_load_dwordx4 v[16:19], v90, s[12:13]
	global_load_dwordx4 v[20:23], v90, s[12:13] offset:1024
	global_load_dwordx4 v[24:27], v90, s[12:13] offset:2048
	global_load_dwordx4 v[28:31], v90, s[12:13] offset:3072
	s_waitcnt vmcnt(8)
	v_lshlrev_b32_e32 v252, 16, v32
	v_and_b32_e32 v253, 0xffff0000, v32
	v_add_f32_e32 v64, v64, v252
	v_add_f32_e32 v65, v65, v253
	v_lshlrev_b32_e32 v252, 16, v33
	v_and_b32_e32 v253, 0xffff0000, v33
	v_add_f32_e32 v66, v66, v252
	v_add_f32_e32 v67, v67, v253
	v_lshlrev_b32_e32 v252, 16, v34
	v_and_b32_e32 v253, 0xffff0000, v34
	v_add_f32_e32 v68, v68, v252
	v_add_f32_e32 v69, v69, v253
	v_lshlrev_b32_e32 v252, 16, v35
	v_and_b32_e32 v253, 0xffff0000, v35
	v_add_f32_e32 v70, v70, v252
	v_add_f32_e32 v71, v71, v253
	v_lshlrev_b32_e32 v252, 16, v36
	v_and_b32_e32 v253, 0xffff0000, v36
	v_add_f32_e32 v72, v72, v252
	v_add_f32_e32 v73, v73, v253
	v_lshlrev_b32_e32 v252, 16, v37
	v_and_b32_e32 v253, 0xffff0000, v37
	v_add_f32_e32 v74, v74, v252
	v_add_f32_e32 v75, v75, v253
	v_lshlrev_b32_e32 v252, 16, v38
	v_and_b32_e32 v253, 0xffff0000, v38
	v_add_f32_e32 v76, v76, v252
	v_add_f32_e32 v77, v77, v253
	v_lshlrev_b32_e32 v252, 16, v39
	v_and_b32_e32 v253, 0xffff0000, v39
	v_add_f32_e32 v78, v78, v252
	v_add_f32_e32 v79, v79, v253
	v_lshlrev_b32_e32 v252, 16, v40
	v_and_b32_e32 v253, 0xffff0000, v40
	v_add_f32_e32 v80, v80, v252
	v_add_f32_e32 v81, v81, v253
	v_lshlrev_b32_e32 v252, 16, v41
	v_and_b32_e32 v253, 0xffff0000, v41
	v_add_f32_e32 v82, v82, v252
	v_add_f32_e32 v83, v83, v253
	v_lshlrev_b32_e32 v252, 16, v42
	v_and_b32_e32 v253, 0xffff0000, v42
	v_add_f32_e32 v84, v84, v252
	v_add_f32_e32 v85, v85, v253
	v_lshlrev_b32_e32 v252, 16, v43
	v_and_b32_e32 v253, 0xffff0000, v43
	v_add_f32_e32 v86, v86, v252
	v_add_f32_e32 v87, v87, v253
	v_lshlrev_b32_e32 v252, 16, v44
	v_and_b32_e32 v253, 0xffff0000, v44
	v_add_f32_e32 v244, v244, v252
	v_add_f32_e32 v245, v245, v253
	v_lshlrev_b32_e32 v252, 16, v45
	v_and_b32_e32 v253, 0xffff0000, v45
	v_add_f32_e32 v246, v246, v252
	v_add_f32_e32 v247, v247, v253
	v_lshlrev_b32_e32 v252, 16, v46
	v_and_b32_e32 v253, 0xffff0000, v46
	v_add_f32_e32 v248, v248, v252
	v_add_f32_e32 v249, v249, v253
	v_lshlrev_b32_e32 v252, 16, v47
	v_and_b32_e32 v253, 0xffff0000, v47
	v_add_f32_e32 v250, v250, v252
	v_add_f32_e32 v251, v251, v253
	s_add_u32 s12, s8, 0x1c00000
	s_addc_u32 s13, s9, 0
	global_load_dwordx4 v[32:35], v90, s[12:13]
	global_load_dwordx4 v[36:39], v90, s[12:13] offset:1024
	global_load_dwordx4 v[40:43], v90, s[12:13] offset:2048
	global_load_dwordx4 v[44:47], v90, s[12:13] offset:3072
	s_waitcnt vmcnt(8)
	v_lshlrev_b32_e32 v252, 16, v48
	v_and_b32_e32 v253, 0xffff0000, v48
	v_add_f32_e32 v64, v64, v252
	v_add_f32_e32 v65, v65, v253
	v_lshlrev_b32_e32 v252, 16, v49
	v_and_b32_e32 v253, 0xffff0000, v49
	v_add_f32_e32 v66, v66, v252
	v_add_f32_e32 v67, v67, v253
	v_lshlrev_b32_e32 v252, 16, v50
	v_and_b32_e32 v253, 0xffff0000, v50
	v_add_f32_e32 v68, v68, v252
	v_add_f32_e32 v69, v69, v253
	v_lshlrev_b32_e32 v252, 16, v51
	v_and_b32_e32 v253, 0xffff0000, v51
	v_add_f32_e32 v70, v70, v252
	v_add_f32_e32 v71, v71, v253
	v_lshlrev_b32_e32 v252, 16, v52
	v_and_b32_e32 v253, 0xffff0000, v52
	v_add_f32_e32 v72, v72, v252
	v_add_f32_e32 v73, v73, v253
	v_lshlrev_b32_e32 v252, 16, v53
	v_and_b32_e32 v253, 0xffff0000, v53
	v_add_f32_e32 v74, v74, v252
	v_add_f32_e32 v75, v75, v253
	v_lshlrev_b32_e32 v252, 16, v54
	v_and_b32_e32 v253, 0xffff0000, v54
	v_add_f32_e32 v76, v76, v252
	v_add_f32_e32 v77, v77, v253
	v_lshlrev_b32_e32 v252, 16, v55
	v_and_b32_e32 v253, 0xffff0000, v55
	v_add_f32_e32 v78, v78, v252
	v_add_f32_e32 v79, v79, v253
	v_lshlrev_b32_e32 v252, 16, v56
	v_and_b32_e32 v253, 0xffff0000, v56
	v_add_f32_e32 v80, v80, v252
	v_add_f32_e32 v81, v81, v253
	v_lshlrev_b32_e32 v252, 16, v57
	v_and_b32_e32 v253, 0xffff0000, v57
	v_add_f32_e32 v82, v82, v252
	v_add_f32_e32 v83, v83, v253
	v_lshlrev_b32_e32 v252, 16, v58
	v_and_b32_e32 v253, 0xffff0000, v58
	v_add_f32_e32 v84, v84, v252
	v_add_f32_e32 v85, v85, v253
	v_lshlrev_b32_e32 v252, 16, v59
	v_and_b32_e32 v253, 0xffff0000, v59
	v_add_f32_e32 v86, v86, v252
	v_add_f32_e32 v87, v87, v253
	v_lshlrev_b32_e32 v252, 16, v60
	v_and_b32_e32 v253, 0xffff0000, v60
	v_add_f32_e32 v244, v244, v252
	v_add_f32_e32 v245, v245, v253
	v_lshlrev_b32_e32 v252, 16, v61
	v_and_b32_e32 v253, 0xffff0000, v61
	v_add_f32_e32 v246, v246, v252
	v_add_f32_e32 v247, v247, v253
	v_lshlrev_b32_e32 v252, 16, v62
	v_and_b32_e32 v253, 0xffff0000, v62
	v_add_f32_e32 v248, v248, v252
	v_add_f32_e32 v249, v249, v253
	v_lshlrev_b32_e32 v252, 16, v63
	v_and_b32_e32 v253, 0xffff0000, v63
	v_add_f32_e32 v250, v250, v252
	v_add_f32_e32 v251, v251, v253
	s_waitcnt vmcnt(4)
	v_lshlrev_b32_e32 v252, 16, v16
	v_and_b32_e32 v253, 0xffff0000, v16
	v_add_f32_e32 v64, v64, v252
	v_add_f32_e32 v65, v65, v253
	v_lshlrev_b32_e32 v252, 16, v17
	v_and_b32_e32 v253, 0xffff0000, v17
	v_add_f32_e32 v66, v66, v252
	v_add_f32_e32 v67, v67, v253
	v_lshlrev_b32_e32 v252, 16, v18
	v_and_b32_e32 v253, 0xffff0000, v18
	v_add_f32_e32 v68, v68, v252
	v_add_f32_e32 v69, v69, v253
	v_lshlrev_b32_e32 v252, 16, v19
	v_and_b32_e32 v253, 0xffff0000, v19
	v_add_f32_e32 v70, v70, v252
	v_add_f32_e32 v71, v71, v253
	v_lshlrev_b32_e32 v252, 16, v20
	v_and_b32_e32 v253, 0xffff0000, v20
	v_add_f32_e32 v72, v72, v252
	v_add_f32_e32 v73, v73, v253
	v_lshlrev_b32_e32 v252, 16, v21
	v_and_b32_e32 v253, 0xffff0000, v21
	v_add_f32_e32 v74, v74, v252
	v_add_f32_e32 v75, v75, v253
	v_lshlrev_b32_e32 v252, 16, v22
	v_and_b32_e32 v253, 0xffff0000, v22
	v_add_f32_e32 v76, v76, v252
	v_add_f32_e32 v77, v77, v253
	v_lshlrev_b32_e32 v252, 16, v23
	v_and_b32_e32 v253, 0xffff0000, v23
	v_add_f32_e32 v78, v78, v252
	v_add_f32_e32 v79, v79, v253
	v_lshlrev_b32_e32 v252, 16, v24
	v_and_b32_e32 v253, 0xffff0000, v24
	v_add_f32_e32 v80, v80, v252
	v_add_f32_e32 v81, v81, v253
	v_lshlrev_b32_e32 v252, 16, v25
	v_and_b32_e32 v253, 0xffff0000, v25
	v_add_f32_e32 v82, v82, v252
	v_add_f32_e32 v83, v83, v253
	v_lshlrev_b32_e32 v252, 16, v26
	v_and_b32_e32 v253, 0xffff0000, v26
	v_add_f32_e32 v84, v84, v252
	v_add_f32_e32 v85, v85, v253
	v_lshlrev_b32_e32 v252, 16, v27
	v_and_b32_e32 v253, 0xffff0000, v27
	v_add_f32_e32 v86, v86, v252
	v_add_f32_e32 v87, v87, v253
	v_lshlrev_b32_e32 v252, 16, v28
	v_and_b32_e32 v253, 0xffff0000, v28
	v_add_f32_e32 v244, v244, v252
	v_add_f32_e32 v245, v245, v253
	v_lshlrev_b32_e32 v252, 16, v29
	v_and_b32_e32 v253, 0xffff0000, v29
	v_add_f32_e32 v246, v246, v252
	v_add_f32_e32 v247, v247, v253
	v_lshlrev_b32_e32 v252, 16, v30
	v_and_b32_e32 v253, 0xffff0000, v30
	v_add_f32_e32 v248, v248, v252
	v_add_f32_e32 v249, v249, v253
	v_lshlrev_b32_e32 v252, 16, v31
	v_and_b32_e32 v253, 0xffff0000, v31
	v_add_f32_e32 v250, v250, v252
	v_add_f32_e32 v251, v251, v253
	s_waitcnt vmcnt(0)
	v_lshlrev_b32_e32 v252, 16, v32
	v_and_b32_e32 v253, 0xffff0000, v32
	v_add_f32_e32 v64, v64, v252
	v_add_f32_e32 v65, v65, v253
	v_lshlrev_b32_e32 v252, 16, v33
	v_and_b32_e32 v253, 0xffff0000, v33
	v_add_f32_e32 v66, v66, v252
	v_add_f32_e32 v67, v67, v253
	v_lshlrev_b32_e32 v252, 16, v34
	v_and_b32_e32 v253, 0xffff0000, v34
	v_add_f32_e32 v68, v68, v252
	v_add_f32_e32 v69, v69, v253
	v_lshlrev_b32_e32 v252, 16, v35
	v_and_b32_e32 v253, 0xffff0000, v35
	v_add_f32_e32 v70, v70, v252
	v_add_f32_e32 v71, v71, v253
	v_lshlrev_b32_e32 v252, 16, v36
	v_and_b32_e32 v253, 0xffff0000, v36
	v_add_f32_e32 v72, v72, v252
	v_add_f32_e32 v73, v73, v253
	v_lshlrev_b32_e32 v252, 16, v37
	v_and_b32_e32 v253, 0xffff0000, v37
	v_add_f32_e32 v74, v74, v252
	v_add_f32_e32 v75, v75, v253
	v_lshlrev_b32_e32 v252, 16, v38
	v_and_b32_e32 v253, 0xffff0000, v38
	v_add_f32_e32 v76, v76, v252
	v_add_f32_e32 v77, v77, v253
	v_lshlrev_b32_e32 v252, 16, v39
	v_and_b32_e32 v253, 0xffff0000, v39
	v_add_f32_e32 v78, v78, v252
	v_add_f32_e32 v79, v79, v253
	v_lshlrev_b32_e32 v252, 16, v40
	v_and_b32_e32 v253, 0xffff0000, v40
	v_add_f32_e32 v80, v80, v252
	v_add_f32_e32 v81, v81, v253
	v_lshlrev_b32_e32 v252, 16, v41
	v_and_b32_e32 v253, 0xffff0000, v41
	v_add_f32_e32 v82, v82, v252
	v_add_f32_e32 v83, v83, v253
	v_lshlrev_b32_e32 v252, 16, v42
	v_and_b32_e32 v253, 0xffff0000, v42
	v_add_f32_e32 v84, v84, v252
	v_add_f32_e32 v85, v85, v253
	v_lshlrev_b32_e32 v252, 16, v43
	v_and_b32_e32 v253, 0xffff0000, v43
	v_add_f32_e32 v86, v86, v252
	v_add_f32_e32 v87, v87, v253
	v_lshlrev_b32_e32 v252, 16, v44
	v_and_b32_e32 v253, 0xffff0000, v44
	v_add_f32_e32 v244, v244, v252
	v_add_f32_e32 v245, v245, v253
	v_lshlrev_b32_e32 v252, 16, v45
	v_and_b32_e32 v253, 0xffff0000, v45
	v_add_f32_e32 v246, v246, v252
	v_add_f32_e32 v247, v247, v253
	v_lshlrev_b32_e32 v252, 16, v46
	v_and_b32_e32 v253, 0xffff0000, v46
	v_add_f32_e32 v248, v248, v252
	v_add_f32_e32 v249, v249, v253
	v_lshlrev_b32_e32 v252, 16, v47
	v_and_b32_e32 v253, 0xffff0000, v47
	v_add_f32_e32 v250, v250, v252
	v_add_f32_e32 v251, v251, v253
	v_and_b32_e32 v252, 0xffff0000, v0
	v_lshlrev_b32_e32 v0, 16, v0
	v_fmac_f32_e32 v64, 0x3fb504f3, v0
	v_fmac_f32_e32 v65, 0x3fb504f3, v252
	v_and_b32_e32 v252, 0xffff0000, v1
	v_lshlrev_b32_e32 v1, 16, v1
	v_fmac_f32_e32 v66, 0x3fb504f3, v1
	v_fmac_f32_e32 v67, 0x3fb504f3, v252
	v_add_f32_e32 v252, v64, v65
	v_add_f32_e32 v253, v66, v67
	v_add_f32_e32 v254, v252, v253
	v_and_b32_e32 v252, 0xffff0000, v2
	v_lshlrev_b32_e32 v2, 16, v2
	v_fmac_f32_e32 v68, 0x3fb504f3, v2
	v_fmac_f32_e32 v69, 0x3fb504f3, v252
	v_and_b32_e32 v252, 0xffff0000, v3
	v_lshlrev_b32_e32 v3, 16, v3
	v_fmac_f32_e32 v70, 0x3fb504f3, v3
	v_fmac_f32_e32 v71, 0x3fb504f3, v252
	v_add_f32_e32 v252, v68, v69
	v_add_f32_e32 v253, v70, v71
	v_add_f32_e32 v252, v252, v253
	v_add_f32_e32 v254, v254, v252
	v_and_b32_e32 v252, 0xffff0000, v4
	v_lshlrev_b32_e32 v4, 16, v4
	v_fmac_f32_e32 v72, 0x3fb504f3, v4
	v_fmac_f32_e32 v73, 0x3fb504f3, v252
	v_and_b32_e32 v252, 0xffff0000, v5
	v_lshlrev_b32_e32 v5, 16, v5
	v_fmac_f32_e32 v74, 0x3fb504f3, v5
	v_fmac_f32_e32 v75, 0x3fb504f3, v252
	v_add_f32_e32 v252, v72, v73
	v_add_f32_e32 v253, v74, v75
	v_add_f32_e32 v252, v252, v253
	v_add_f32_e32 v254, v254, v252
	v_and_b32_e32 v252, 0xffff0000, v6
	v_lshlrev_b32_e32 v6, 16, v6
	v_fmac_f32_e32 v76, 0x3fb504f3, v6
	v_fmac_f32_e32 v77, 0x3fb504f3, v252
	v_and_b32_e32 v252, 0xffff0000, v7
	v_lshlrev_b32_e32 v7, 16, v7
	v_fmac_f32_e32 v78, 0x3fb504f3, v7
	v_fmac_f32_e32 v79, 0x3fb504f3, v252
	v_add_f32_e32 v252, v76, v77
	v_add_f32_e32 v253, v78, v79
	v_add_f32_e32 v252, v252, v253
	v_add_f32_e32 v254, v254, v252
	v_and_b32_e32 v252, 0xffff0000, v8
	v_lshlrev_b32_e32 v8, 16, v8
	v_fmac_f32_e32 v80, 0x3fb504f3, v8
	v_fmac_f32_e32 v81, 0x3fb504f3, v252
	v_and_b32_e32 v252, 0xffff0000, v9
	v_lshlrev_b32_e32 v9, 16, v9
	v_fmac_f32_e32 v82, 0x3fb504f3, v9
	v_fmac_f32_e32 v83, 0x3fb504f3, v252
	v_add_f32_e32 v252, v80, v81
	v_add_f32_e32 v253, v82, v83
	v_add_f32_e32 v252, v252, v253
	v_add_f32_e32 v254, v254, v252
	v_and_b32_e32 v252, 0xffff0000, v10
	v_lshlrev_b32_e32 v10, 16, v10
	v_fmac_f32_e32 v84, 0x3fb504f3, v10
	v_fmac_f32_e32 v85, 0x3fb504f3, v252
	v_and_b32_e32 v252, 0xffff0000, v11
	v_lshlrev_b32_e32 v11, 16, v11
	v_fmac_f32_e32 v86, 0x3fb504f3, v11
	v_fmac_f32_e32 v87, 0x3fb504f3, v252
	v_add_f32_e32 v252, v84, v85
	v_add_f32_e32 v253, v86, v87
	v_add_f32_e32 v252, v252, v253
	v_add_f32_e32 v254, v254, v252
	v_and_b32_e32 v252, 0xffff0000, v12
	v_lshlrev_b32_e32 v12, 16, v12
	v_fmac_f32_e32 v244, 0x3fb504f3, v12
	v_fmac_f32_e32 v245, 0x3fb504f3, v252
	v_and_b32_e32 v252, 0xffff0000, v13
	v_lshlrev_b32_e32 v13, 16, v13
	v_fmac_f32_e32 v246, 0x3fb504f3, v13
	v_fmac_f32_e32 v247, 0x3fb504f3, v252
	v_add_f32_e32 v252, v244, v245
	v_add_f32_e32 v253, v246, v247
	v_add_f32_e32 v252, v252, v253
	v_add_f32_e32 v254, v254, v252
	v_and_b32_e32 v252, 0xffff0000, v14
	v_lshlrev_b32_e32 v14, 16, v14
	v_fmac_f32_e32 v248, 0x3fb504f3, v14
	v_fmac_f32_e32 v249, 0x3fb504f3, v252
	v_and_b32_e32 v252, 0xffff0000, v15
	v_lshlrev_b32_e32 v15, 16, v15
	v_fmac_f32_e32 v250, 0x3fb504f3, v15
	v_fmac_f32_e32 v251, 0x3fb504f3, v252
	v_add_f32_e32 v252, v248, v249
	v_add_f32_e32 v253, v250, v251
	v_add_f32_e32 v252, v252, v253
	v_add_f32_e32 v254, v254, v252
	s_nop 1
	v_add_f32_dpp v252, v254, v254 quad_perm:[1,0,3,2] row_mask:0xf bank_mask:0xf
	s_nop 1
	v_add_f32_dpp v252, v252, v252 quad_perm:[2,3,0,1] row_mask:0xf bank_mask:0xf
	s_nop 1
	v_add_f32_dpp v252, v252, v252 row_half_mirror row_mask:0xf bank_mask:0xf
	s_nop 1
	v_add_f32_dpp v252, v252, v252 row_mirror row_mask:0xf bank_mask:0xf
	s_nop 1
	v_readlane_b32 s86, v252, 0
	v_readlane_b32 s87, v252, 16
	v_readlane_b32 s88, v252, 32
	v_readlane_b32 s89, v252, 48
	s_nop 1
	v_mov_b32_e32 v253, s86
	v_add_f32_e32 v253, s87, v253
	v_add_f32_e32 v253, s88, v253
	v_add_f32_e32 v253, s89, v253
	v_mul_f32_e32 v253, 0x3a000000, v253
	s_nop 0
	v_readfirstlane_b32 s85, v253
	s_nop 1
	v_subrev_f32_e32 v64, s85, v64
	v_subrev_f32_e32 v65, s85, v65
	v_subrev_f32_e32 v66, s85, v66
	v_subrev_f32_e32 v67, s85, v67
	v_subrev_f32_e32 v68, s85, v68
	v_subrev_f32_e32 v69, s85, v69
	v_subrev_f32_e32 v70, s85, v70
	v_subrev_f32_e32 v71, s85, v71
	v_mul_f32_e32 v252, v64, v64
	v_fmac_f32_e32 v252, v65, v65
	v_mul_f32_e32 v253, v66, v66
	v_fmac_f32_e32 v253, v67, v67
	v_add_f32_e32 v254, v252, v253
	v_mul_f32_e32 v252, v68, v68
	v_fmac_f32_e32 v252, v69, v69
	v_mul_f32_e32 v253, v70, v70
	v_fmac_f32_e32 v253, v71, v71
	v_add_f32_e32 v252, v252, v253
	v_add_f32_e32 v254, v254, v252
	v_subrev_f32_e32 v72, s85, v72
	v_subrev_f32_e32 v73, s85, v73
	v_subrev_f32_e32 v74, s85, v74
	v_subrev_f32_e32 v75, s85, v75
	v_subrev_f32_e32 v76, s85, v76
	v_subrev_f32_e32 v77, s85, v77
	v_subrev_f32_e32 v78, s85, v78
	v_subrev_f32_e32 v79, s85, v79
	v_mul_f32_e32 v252, v72, v72
	v_fmac_f32_e32 v252, v73, v73
	v_mul_f32_e32 v253, v74, v74
	v_fmac_f32_e32 v253, v75, v75
	v_add_f32_e32 v252, v252, v253
	v_add_f32_e32 v254, v254, v252
	v_mul_f32_e32 v252, v76, v76
	v_fmac_f32_e32 v252, v77, v77
	v_mul_f32_e32 v253, v78, v78
	v_fmac_f32_e32 v253, v79, v79
	v_add_f32_e32 v252, v252, v253
	v_add_f32_e32 v254, v254, v252
	v_subrev_f32_e32 v80, s85, v80
	v_subrev_f32_e32 v81, s85, v81
	v_subrev_f32_e32 v82, s85, v82
	v_subrev_f32_e32 v83, s85, v83
	v_subrev_f32_e32 v84, s85, v84
	v_subrev_f32_e32 v85, s85, v85
	v_subrev_f32_e32 v86, s85, v86
	v_subrev_f32_e32 v87, s85, v87
	v_mul_f32_e32 v252, v80, v80
	v_fmac_f32_e32 v252, v81, v81
	v_mul_f32_e32 v253, v82, v82
	v_fmac_f32_e32 v253, v83, v83
	v_add_f32_e32 v252, v252, v253
	v_add_f32_e32 v254, v254, v252
	v_mul_f32_e32 v252, v84, v84
	v_fmac_f32_e32 v252, v85, v85
	v_mul_f32_e32 v253, v86, v86
	v_fmac_f32_e32 v253, v87, v87
	v_add_f32_e32 v252, v252, v253
	v_add_f32_e32 v254, v254, v252
	v_subrev_f32_e32 v244, s85, v244
	v_subrev_f32_e32 v245, s85, v245
	v_subrev_f32_e32 v246, s85, v246
	v_subrev_f32_e32 v247, s85, v247
	v_subrev_f32_e32 v248, s85, v248
	v_subrev_f32_e32 v249, s85, v249
	v_subrev_f32_e32 v250, s85, v250
	v_subrev_f32_e32 v251, s85, v251
	v_mul_f32_e32 v252, v244, v244
	v_fmac_f32_e32 v252, v245, v245
	v_mul_f32_e32 v253, v246, v246
	v_fmac_f32_e32 v253, v247, v247
	v_add_f32_e32 v252, v252, v253
	v_add_f32_e32 v254, v254, v252
	v_mul_f32_e32 v252, v248, v248
	v_fmac_f32_e32 v252, v249, v249
	v_mul_f32_e32 v253, v250, v250
	v_fmac_f32_e32 v253, v251, v251
	v_add_f32_e32 v252, v252, v253
	v_add_f32_e32 v254, v254, v252
	s_nop 1
	v_add_f32_dpp v252, v254, v254 quad_perm:[1,0,3,2] row_mask:0xf bank_mask:0xf
	s_nop 1
	v_add_f32_dpp v252, v252, v252 quad_perm:[2,3,0,1] row_mask:0xf bank_mask:0xf
	s_nop 1
	v_add_f32_dpp v252, v252, v252 row_half_mirror row_mask:0xf bank_mask:0xf
	s_nop 1
	v_add_f32_dpp v252, v252, v252 row_mirror row_mask:0xf bank_mask:0xf
	s_nop 1
	v_readlane_b32 s86, v252, 0
	v_readlane_b32 s87, v252, 16
	v_readlane_b32 s88, v252, 32
	v_readlane_b32 s89, v252, 48
	s_nop 1
	v_mov_b32_e32 v253, s86
	v_add_f32_e32 v253, s87, v253
	v_add_f32_e32 v253, s88, v253
	v_add_f32_e32 v253, s89, v253
	v_mov_b32_e32 v252, 0x3a000000
	v_fmaak_f32 v253, v253, v252, 0x3727c5ac
	v_rsq_f32_e32 v253, v253
	s_nop 1
	v_readfirstlane_b32 s85, v253
	s_add_u32 s12, s4, 0x2000000
	s_addc_u32 s13, s5, 0
	v_readlane_b32 s86, v241, 7
	v_readlane_b32 s87, v241, 8
	s_add_u32 s86, s86, 0x4000000
	s_addc_u32 s87, s87, 0
	s_add_u32 s88, s86, 0x1000
	s_addc_u32 s89, s87, 0
	ds_read_b64 v[252:253], v168
	ds_read_b64 v[254:255], v168 offset:8192
	ds_read_b64 v[88:89], v168 offset:512
	ds_read_b64 v[242:243], v168 offset:8704
	s_waitcnt lgkmcnt(2)
	v_mul_f32_e32 v64, s85, v64
	v_mul_f32_e32 v65, s85, v65
	v_fma_f32 v64, v64, v252, v254
	v_fma_f32 v65, v65, v253, v255
	ds_read_b64 v[252:253], v168 offset:1024
	ds_read_b64 v[254:255], v168 offset:9216
	s_waitcnt lgkmcnt(2)
	v_mul_f32_e32 v66, s85, v66
	v_mul_f32_e32 v67, s85, v67
	v_fma_f32 v66, v66, v88, v242
	v_fma_f32 v67, v67, v89, v243
	ds_read_b64 v[88:89], v168 offset:1536
	ds_read_b64 v[242:243], v168 offset:9728
	s_waitcnt lgkmcnt(2)
	v_mul_f32_e32 v68, s85, v68
	v_mul_f32_e32 v69, s85, v69
	v_fma_f32 v68, v68, v252, v254
	v_fma_f32 v69, v69, v253, v255
	ds_read_b64 v[252:253], v168 offset:2048
	ds_read_b64 v[254:255], v168 offset:10240
	s_waitcnt lgkmcnt(2)
	v_mul_f32_e32 v70, s85, v70
	v_mul_f32_e32 v71, s85, v71
	v_fma_f32 v70, v70, v88, v242
	v_fma_f32 v71, v71, v89, v243
	s_cmp_lg_u32 s90, 0
	s_cbranch_scc1 .Lln2_f32_26
	v_cvt_pk_bf16_f32 v64, v64, v65
	v_cvt_pk_bf16_f32 v65, v66, v67
	v_cvt_pk_bf16_f32 v66, v68, v69
	v_cvt_pk_bf16_f32 v67, v70, v71
	global_store_dwordx4 v90, v[64:67], s[12:13]
	s_branch .Lln2_st_27

.Lln2_hi_1:
	global_load_dwordx4 v[0:3], v90, s[4:5]
	global_load_dwordx4 v[4:7], v90, s[4:5] offset:1024
	global_load_dwordx4 v[8:11], v90, s[4:5] offset:2048
	global_load_dwordx4 v[12:15], v90, s[4:5] offset:3072
	global_load_dwordx4 v[16:19], v90, s[6:7]
	global_load_dwordx4 v[20:23], v90, s[6:7] offset:1024
	global_load_dwordx4 v[24:27], v90, s[6:7] offset:2048
	global_load_dwordx4 v[28:31], v90, s[6:7] offset:3072
	s_add_u32 s12, s4, 0x800000
	s_addc_u32 s13, s5, 0
	global_load_dwordx4 v[32:35], v90, s[12:13]
	global_load_dwordx4 v[36:39], v90, s[12:13] offset:1024
	global_load_dwordx4 v[40:43], v90, s[12:13] offset:2048
	global_load_dwordx4 v[44:47], v90, s[12:13] offset:3072
	s_add_u32 s12, s6, 0x800000
	s_addc_u32 s13, s7, 0
	global_load_dwordx4 v[48:51], v90, s[12:13]
	global_load_dwordx4 v[52:55], v90, s[12:13] offset:1024
	global_load_dwordx4 v[56:59], v90, s[12:13] offset:2048
	global_load_dwordx4 v[60:63], v90, s[12:13] offset:3072
	s_waitcnt vmcnt(8)
	v_lshlrev_b32_e32 v64, 16, v16
	v_and_b32_e32 v65, 0xffff0000, v16
	v_and_b32_e32 v252, 0xffff0000, v0
	v_lshlrev_b32_e32 v0, 16, v0
	v_fmac_f32_e32 v64, 0x3fb504f3, v0
	v_fmac_f32_e32 v65, 0x3fb504f3, v252
	v_lshlrev_b32_e32 v66, 16, v17
	v_and_b32_e32 v67, 0xffff0000, v17
	v_and_b32_e32 v252, 0xffff0000, v1
	v_lshlrev_b32_e32 v1, 16, v1
	v_fmac_f32_e32 v66, 0x3fb504f3, v1
	v_fmac_f32_e32 v67, 0x3fb504f3, v252
	v_add_f32_e32 v252, v64, v65
	v_add_f32_e32 v253, v66, v67
	v_add_f32_e32 v254, v252, v253
	v_lshlrev_b32_e32 v68, 16, v18
	v_and_b32_e32 v69, 0xffff0000, v18
	v_and_b32_e32 v252, 0xffff0000, v2
	v_lshlrev_b32_e32 v2, 16, v2
	v_fmac_f32_e32 v68, 0x3fb504f3, v2
	v_fmac_f32_e32 v69, 0x3fb504f3, v252
	v_lshlrev_b32_e32 v70, 16, v19
	v_and_b32_e32 v71, 0xffff0000, v19
	v_and_b32_e32 v252, 0xffff0000, v3
	v_lshlrev_b32_e32 v3, 16, v3
	v_fmac_f32_e32 v70, 0x3fb504f3, v3
	v_fmac_f32_e32 v71, 0x3fb504f3, v252
	v_add_f32_e32 v252, v68, v69
	v_add_f32_e32 v253, v70, v71
	v_add_f32_e32 v252, v252, v253
	v_add_f32_e32 v254, v254, v252
	v_lshlrev_b32_e32 v72, 16, v20
	v_and_b32_e32 v73, 0xffff0000, v20
	v_and_b32_e32 v252, 0xffff0000, v4
	v_lshlrev_b32_e32 v4, 16, v4
	v_fmac_f32_e32 v72, 0x3fb504f3, v4
	v_fmac_f32_e32 v73, 0x3fb504f3, v252
	v_lshlrev_b32_e32 v74, 16, v21
	v_and_b32_e32 v75, 0xffff0000, v21
	v_and_b32_e32 v252, 0xffff0000, v5
	v_lshlrev_b32_e32 v5, 16, v5
	v_fmac_f32_e32 v74, 0x3fb504f3, v5
	v_fmac_f32_e32 v75, 0x3fb504f3, v252
	v_add_f32_e32 v252, v72, v73
	v_add_f32_e32 v253, v74, v75
	v_add_f32_e32 v252, v252, v253
	v_add_f32_e32 v254, v254, v252
	v_lshlrev_b32_e32 v76, 16, v22
	v_and_b32_e32 v77, 0xffff0000, v22
	v_and_b32_e32 v252, 0xffff0000, v6
	v_lshlrev_b32_e32 v6, 16, v6
	v_fmac_f32_e32 v76, 0x3fb504f3, v6
	v_fmac_f32_e32 v77, 0x3fb504f3, v252
	v_lshlrev_b32_e32 v78, 16, v23
	v_and_b32_e32 v79, 0xffff0000, v23
	v_and_b32_e32 v252, 0xffff0000, v7
	v_lshlrev_b32_e32 v7, 16, v7
	v_fmac_f32_e32 v78, 0x3fb504f3, v7
	v_fmac_f32_e32 v79, 0x3fb504f3, v252
	v_add_f32_e32 v252, v76, v77
	v_add_f32_e32 v253, v78, v79
	v_add_f32_e32 v252, v252, v253
	v_add_f32_e32 v254, v254, v252
	v_lshlrev_b32_e32 v80, 16, v24
	v_and_b32_e32 v81, 0xffff0000, v24
	v_and_b32_e32 v252, 0xffff0000, v8
	v_lshlrev_b32_e32 v8, 16, v8
	v_fmac_f32_e32 v80, 0x3fb504f3, v8
	v_fmac_f32_e32 v81, 0x3fb504f3, v252
	v_lshlrev_b32_e32 v82, 16, v25
	v_and_b32_e32 v83, 0xffff0000, v25
	v_and_b32_e32 v252, 0xffff0000, v9
	v_lshlrev_b32_e32 v9, 16, v9
	v_fmac_f32_e32 v82, 0x3fb504f3, v9
	v_fmac_f32_e32 v83, 0x3fb504f3, v252
	v_add_f32_e32 v252, v80, v81
	v_add_f32_e32 v253, v82, v83
	v_add_f32_e32 v252, v252, v253
	v_add_f32_e32 v254, v254, v252
	v_lshlrev_b32_e32 v84, 16, v26
	v_and_b32_e32 v85, 0xffff0000, v26
	v_and_b32_e32 v252, 0xffff0000, v10
	v_lshlrev_b32_e32 v10, 16, v10
	v_fmac_f32_e32 v84, 0x3fb504f3, v10
	v_fmac_f32_e32 v85, 0x3fb504f3, v252
	v_lshlrev_b32_e32 v86, 16, v27
	v_and_b32_e32 v87, 0xffff0000, v27
	v_and_b32_e32 v252, 0xffff0000, v11
	v_lshlrev_b32_e32 v11, 16, v11
	v_fmac_f32_e32 v86, 0x3fb504f3, v11
	v_fmac_f32_e32 v87, 0x3fb504f3, v252
	v_add_f32_e32 v252, v84, v85
	v_add_f32_e32 v253, v86, v87
	v_add_f32_e32 v252, v252, v253
	v_add_f32_e32 v254, v254, v252
	v_lshlrev_b32_e32 v244, 16, v28
	v_and_b32_e32 v245, 0xffff0000, v28
	v_and_b32_e32 v252, 0xffff0000, v12
	v_lshlrev_b32_e32 v12, 16, v12
	v_fmac_f32_e32 v244, 0x3fb504f3, v12
	v_fmac_f32_e32 v245, 0x3fb504f3, v252
	v_lshlrev_b32_e32 v246, 16, v29
	v_and_b32_e32 v247, 0xffff0000, v29
	v_and_b32_e32 v252, 0xffff0000, v13
	v_lshlrev_b32_e32 v13, 16, v13
	v_fmac_f32_e32 v246, 0x3fb504f3, v13
	v_fmac_f32_e32 v247, 0x3fb504f3, v252
	v_add_f32_e32 v252, v244, v245
	v_add_f32_e32 v253, v246, v247
	v_add_f32_e32 v252, v252, v253
	v_add_f32_e32 v254, v254, v252
	v_lshlrev_b32_e32 v248, 16, v30
	v_and_b32_e32 v249, 0xffff0000, v30
	v_and_b32_e32 v252, 0xffff0000, v14
	v_lshlrev_b32_e32 v14, 16, v14
	v_fmac_f32_e32 v248, 0x3fb504f3, v14
	v_fmac_f32_e32 v249, 0x3fb504f3, v252
	v_lshlrev_b32_e32 v250, 16, v31
	v_and_b32_e32 v251, 0xffff0000, v31
	v_and_b32_e32 v252, 0xffff0000, v15
	v_lshlrev_b32_e32 v15, 16, v15
	v_fmac_f32_e32 v250, 0x3fb504f3, v15
	v_fmac_f32_e32 v251, 0x3fb504f3, v252
	v_add_f32_e32 v252, v248, v249
	v_add_f32_e32 v253, v250, v251
	v_add_f32_e32 v252, v252, v253
	v_add_f32_e32 v254, v254, v252
	s_add_u32 s12, s4, 0x1000000
	s_addc_u32 s13, s5, 0
	global_load_dwordx4 v[0:3], v90, s[12:13]
	global_load_dwordx4 v[4:7], v90, s[12:13] offset:1024
	global_load_dwordx4 v[8:11], v90, s[12:13] offset:2048
	global_load_dwordx4 v[12:15], v90, s[12:13] offset:3072
	s_add_u32 s12, s6, 0x1000000
	s_addc_u32 s13, s7, 0
	global_load_dwordx4 v[16:19], v90, s[12:13]
	global_load_dwordx4 v[20:23], v90, s[12:13] offset:1024
	global_load_dwordx4 v[24:27], v90, s[12:13] offset:2048
	global_load_dwordx4 v[28:31], v90, s[12:13] offset:3072
	s_nop 1
	v_add_f32_dpp v252, v254, v254 quad_perm:[1,0,3,2] row_mask:0xf bank_mask:0xf
	s_nop 1
	v_add_f32_dpp v252, v252, v252 quad_perm:[2,3,0,1] row_mask:0xf bank_mask:0xf
	s_nop 1
	v_add_f32_dpp v252, v252, v252 row_half_mirror row_mask:0xf bank_mask:0xf
	s_nop 1
	v_add_f32_dpp v252, v252, v252 row_mirror row_mask:0xf bank_mask:0xf
	s_nop 1
	v_readlane_b32 s86, v252, 0
	v_readlane_b32 s87, v252, 16
	v_readlane_b32 s88, v252, 32
	v_readlane_b32 s89, v252, 48
	s_nop 1
	v_mov_b32_e32 v253, s86
	v_add_f32_e32 v253, s87, v253
	v_add_f32_e32 v253, s88, v253
	v_add_f32_e32 v253, s89, v253
	v_mul_f32_e32 v253, 0x3a000000, v253
	s_nop 0
	v_readfirstlane_b32 s85, v253
	s_nop 1
	v_subrev_f32_e32 v64, s85, v64
	v_subrev_f32_e32 v65, s85, v65
	v_subrev_f32_e32 v66, s85, v66
	v_subrev_f32_e32 v67, s85, v67
	v_subrev_f32_e32 v68, s85, v68
	v_subrev_f32_e32 v69, s85, v69
	v_subrev_f32_e32 v70, s85, v70
	v_subrev_f32_e32 v71, s85, v71
	v_mul_f32_e32 v252, v64, v64
	v_fmac_f32_e32 v252, v65, v65
	v_mul_f32_e32 v253, v66, v66
	v_fmac_f32_e32 v253, v67, v67
	v_add_f32_e32 v254, v252, v253
	v_mul_f32_e32 v252, v68, v68
	v_fmac_f32_e32 v252, v69, v69
	v_mul_f32_e32 v253, v70, v70
	v_fmac_f32_e32 v253, v71, v71
	v_add_f32_e32 v252, v252, v253
	v_add_f32_e32 v254, v254, v252
	v_subrev_f32_e32 v72, s85, v72
	v_subrev_f32_e32 v73, s85, v73
	v_subrev_f32_e32 v74, s85, v74
	v_subrev_f32_e32 v75, s85, v75
	v_subrev_f32_e32 v76, s85, v76
	v_subrev_f32_e32 v77, s85, v77
	v_subrev_f32_e32 v78, s85, v78
	v_subrev_f32_e32 v79, s85, v79
	v_mul_f32_e32 v252, v72, v72
	v_fmac_f32_e32 v252, v73, v73
	v_mul_f32_e32 v253, v74, v74
	v_fmac_f32_e32 v253, v75, v75
	v_add_f32_e32 v252, v252, v253
	v_add_f32_e32 v254, v254, v252
	v_mul_f32_e32 v252, v76, v76
	v_fmac_f32_e32 v252, v77, v77
	v_mul_f32_e32 v253, v78, v78
	v_fmac_f32_e32 v253, v79, v79
	v_add_f32_e32 v252, v252, v253
	v_add_f32_e32 v254, v254, v252
	v_subrev_f32_e32 v80, s85, v80
	v_subrev_f32_e32 v81, s85, v81
	v_subrev_f32_e32 v82, s85, v82
	v_subrev_f32_e32 v83, s85, v83
	v_subrev_f32_e32 v84, s85, v84
	v_subrev_f32_e32 v85, s85, v85
	v_subrev_f32_e32 v86, s85, v86
	v_subrev_f32_e32 v87, s85, v87
	v_mul_f32_e32 v252, v80, v80
	v_fmac_f32_e32 v252, v81, v81
	v_mul_f32_e32 v253, v82, v82
	v_fmac_f32_e32 v253, v83, v83
	v_add_f32_e32 v252, v252, v253
	v_add_f32_e32 v254, v254, v252
	v_mul_f32_e32 v252, v84, v84
	v_fmac_f32_e32 v252, v85, v85
	v_mul_f32_e32 v253, v86, v86
	v_fmac_f32_e32 v253, v87, v87
	v_add_f32_e32 v252, v252, v253
	v_add_f32_e32 v254, v254, v252
	v_subrev_f32_e32 v244, s85, v244
	v_subrev_f32_e32 v245, s85, v245
	v_subrev_f32_e32 v246, s85, v246
	v_subrev_f32_e32 v247, s85, v247
	v_subrev_f32_e32 v248, s85, v248
	v_subrev_f32_e32 v249, s85, v249
	v_subrev_f32_e32 v250, s85, v250
	v_subrev_f32_e32 v251, s85, v251
	v_mul_f32_e32 v252, v244, v244
	v_fmac_f32_e32 v252, v245, v245
	v_mul_f32_e32 v253, v246, v246
	v_fmac_f32_e32 v253, v247, v247
	v_add_f32_e32 v252, v252, v253
	v_add_f32_e32 v254, v254, v252
	v_mul_f32_e32 v252, v248, v248
	v_fmac_f32_e32 v252, v249, v249
	v_mul_f32_e32 v253, v250, v250
	v_fmac_f32_e32 v253, v251, v251
	v_add_f32_e32 v252, v252, v253
	v_add_f32_e32 v254, v254, v252
	s_nop 1
	v_add_f32_dpp v252, v254, v254 quad_perm:[1,0,3,2] row_mask:0xf bank_mask:0xf
	s_nop 1
	v_add_f32_dpp v252, v252, v252 quad_perm:[2,3,0,1] row_mask:0xf bank_mask:0xf
	s_nop 1
	v_add_f32_dpp v252, v252, v252 row_half_mirror row_mask:0xf bank_mask:0xf
	s_nop 1
	v_add_f32_dpp v252, v252, v252 row_mirror row_mask:0xf bank_mask:0xf
	s_nop 1
	v_readlane_b32 s86, v252, 0
	v_readlane_b32 s87, v252, 16
	v_readlane_b32 s88, v252, 32
	v_readlane_b32 s89, v252, 48
	s_nop 1
	v_mov_b32_e32 v253, s86
	v_add_f32_e32 v253, s87, v253
	v_add_f32_e32 v253, s88, v253
	v_add_f32_e32 v253, s89, v253
	v_mov_b32_e32 v252, 0x3a000000
	v_fmaak_f32 v253, v253, v252, 0x3727c5ac
	v_rsq_f32_e32 v253, v253
	s_nop 1
	v_readfirstlane_b32 s85, v253
	s_mov_b32 s12, s4
	s_mov_b32 s13, s5
	v_readlane_b32 s86, v241, 7
	v_readlane_b32 s87, v241, 8
	s_add_u32 s86, s86, 0x0
	s_addc_u32 s87, s87, 0
	s_add_u32 s88, s86, 0x1000
	s_addc_u32 s89, s87, 0
	ds_read_b64 v[252:253], v168
	ds_read_b64 v[254:255], v168 offset:8192
	ds_read_b64 v[88:89], v168 offset:512
	ds_read_b64 v[242:243], v168 offset:8704
	s_waitcnt lgkmcnt(2)
	v_mul_f32_e32 v64, s85, v64
	v_mul_f32_e32 v65, s85, v65
	v_fma_f32 v64, v64, v252, v254
	v_fma_f32 v65, v65, v253, v255
	ds_read_b64 v[252:253], v168 offset:1024
	ds_read_b64 v[254:255], v168 offset:9216
	s_waitcnt lgkmcnt(2)
	v_mul_f32_e32 v66, s85, v66
	v_mul_f32_e32 v67, s85, v67
	v_fma_f32 v66, v66, v88, v242
	v_fma_f32 v67, v67, v89, v243
	ds_read_b64 v[88:89], v168 offset:1536
	ds_read_b64 v[242:243], v168 offset:9728
	s_waitcnt lgkmcnt(2)
	v_mul_f32_e32 v68, s85, v68
	v_mul_f32_e32 v69, s85, v69
	v_fma_f32 v68, v68, v252, v254
	v_fma_f32 v69, v69, v253, v255
	ds_read_b64 v[252:253], v168 offset:2048
	ds_read_b64 v[254:255], v168 offset:10240
	s_waitcnt lgkmcnt(2)
	v_mul_f32_e32 v70, s85, v70
	v_mul_f32_e32 v71, s85, v71
	v_fma_f32 v70, v70, v88, v242
	v_fma_f32 v71, v71, v89, v243
	s_cmp_lg_u32 s90, 0
	s_cbranch_scc1 .Lln2_f32_34
	v_cvt_pk_bf16_f32 v64, v64, v65
	v_cvt_pk_bf16_f32 v65, v66, v67
	v_cvt_pk_bf16_f32 v66, v68, v69
	v_cvt_pk_bf16_f32 v67, v70, v71
	global_store_dwordx4 v90, v[64:67], s[12:13]
	s_branch .Lln2_st_35

.Lln2_st_49:
	s_waitcnt vmcnt(16)
	v_lshlrev_b32_e32 v64, 16, v16
	v_and_b32_e32 v65, 0xffff0000, v16
	v_and_b32_e32 v252, 0xffff0000, v0
	v_lshlrev_b32_e32 v0, 16, v0
	v_fmac_f32_e32 v64, 0x3fb504f3, v0
	v_fmac_f32_e32 v65, 0x3fb504f3, v252
	v_lshlrev_b32_e32 v66, 16, v17
	v_and_b32_e32 v67, 0xffff0000, v17
	v_and_b32_e32 v252, 0xffff0000, v1
	v_lshlrev_b32_e32 v1, 16, v1
	v_fmac_f32_e32 v66, 0x3fb504f3, v1
	v_fmac_f32_e32 v67, 0x3fb504f3, v252
	v_add_f32_e32 v252, v64, v65
	v_add_f32_e32 v253, v66, v67
	v_add_f32_e32 v254, v252, v253
	v_lshlrev_b32_e32 v68, 16, v18
	v_and_b32_e32 v69, 0xffff0000, v18
	v_and_b32_e32 v252, 0xffff0000, v2
	v_lshlrev_b32_e32 v2, 16, v2
	v_fmac_f32_e32 v68, 0x3fb504f3, v2
	v_fmac_f32_e32 v69, 0x3fb504f3, v252
	v_lshlrev_b32_e32 v70, 16, v19
	v_and_b32_e32 v71, 0xffff0000, v19
	v_and_b32_e32 v252, 0xffff0000, v3
	v_lshlrev_b32_e32 v3, 16, v3
	v_fmac_f32_e32 v70, 0x3fb504f3, v3
	v_fmac_f32_e32 v71, 0x3fb504f3, v252
	v_add_f32_e32 v252, v68, v69
	v_add_f32_e32 v253, v70, v71
	v_add_f32_e32 v252, v252, v253
	v_add_f32_e32 v254, v254, v252
	v_lshlrev_b32_e32 v72, 16, v20
	v_and_b32_e32 v73, 0xffff0000, v20
	v_and_b32_e32 v252, 0xffff0000, v4
	v_lshlrev_b32_e32 v4, 16, v4
	v_fmac_f32_e32 v72, 0x3fb504f3, v4
	v_fmac_f32_e32 v73, 0x3fb504f3, v252
	v_lshlrev_b32_e32 v74, 16, v21
	v_and_b32_e32 v75, 0xffff0000, v21
	v_and_b32_e32 v252, 0xffff0000, v5
	v_lshlrev_b32_e32 v5, 16, v5
	v_fmac_f32_e32 v74, 0x3fb504f3, v5
	v_fmac_f32_e32 v75, 0x3fb504f3, v252
	v_add_f32_e32 v252, v72, v73
	v_add_f32_e32 v253, v74, v75
	v_add_f32_e32 v252, v252, v253
	v_add_f32_e32 v254, v254, v252
	v_lshlrev_b32_e32 v76, 16, v22
	v_and_b32_e32 v77, 0xffff0000, v22
	v_and_b32_e32 v252, 0xffff0000, v6
	v_lshlrev_b32_e32 v6, 16, v6
	v_fmac_f32_e32 v76, 0x3fb504f3, v6
	v_fmac_f32_e32 v77, 0x3fb504f3, v252
	v_lshlrev_b32_e32 v78, 16, v23
	v_and_b32_e32 v79, 0xffff0000, v23
	v_and_b32_e32 v252, 0xffff0000, v7
	v_lshlrev_b32_e32 v7, 16, v7
	v_fmac_f32_e32 v78, 0x3fb504f3, v7
	v_fmac_f32_e32 v79, 0x3fb504f3, v252
	v_add_f32_e32 v252, v76, v77
	v_add_f32_e32 v253, v78, v79
	v_add_f32_e32 v252, v252, v253
	v_add_f32_e32 v254, v254, v252
	v_lshlrev_b32_e32 v80, 16, v24
	v_and_b32_e32 v81, 0xffff0000, v24
	v_and_b32_e32 v252, 0xffff0000, v8
	v_lshlrev_b32_e32 v8, 16, v8
	v_fmac_f32_e32 v80, 0x3fb504f3, v8
	v_fmac_f32_e32 v81, 0x3fb504f3, v252
	v_lshlrev_b32_e32 v82, 16, v25
	v_and_b32_e32 v83, 0xffff0000, v25
	v_and_b32_e32 v252, 0xffff0000, v9
	v_lshlrev_b32_e32 v9, 16, v9
	v_fmac_f32_e32 v82, 0x3fb504f3, v9
	v_fmac_f32_e32 v83, 0x3fb504f3, v252
	v_add_f32_e32 v252, v80, v81
	v_add_f32_e32 v253, v82, v83
	v_add_f32_e32 v252, v252, v253
	v_add_f32_e32 v254, v254, v252
	v_lshlrev_b32_e32 v84, 16, v26
	v_and_b32_e32 v85, 0xffff0000, v26
	v_and_b32_e32 v252, 0xffff0000, v10
	v_lshlrev_b32_e32 v10, 16, v10
	v_fmac_f32_e32 v84, 0x3fb504f3, v10
	v_fmac_f32_e32 v85, 0x3fb504f3, v252
	v_lshlrev_b32_e32 v86, 16, v27
	v_and_b32_e32 v87, 0xffff0000, v27
	v_and_b32_e32 v252, 0xffff0000, v11
	v_lshlrev_b32_e32 v11, 16, v11
	v_fmac_f32_e32 v86, 0x3fb504f3, v11
	v_fmac_f32_e32 v87, 0x3fb504f3, v252
	v_add_f32_e32 v252, v84, v85
	v_add_f32_e32 v253, v86, v87
	v_add_f32_e32 v252, v252, v253
	v_add_f32_e32 v254, v254, v252
	v_lshlrev_b32_e32 v244, 16, v28
	v_and_b32_e32 v245, 0xffff0000, v28
	v_and_b32_e32 v252, 0xffff0000, v12
	v_lshlrev_b32_e32 v12, 16, v12
	v_fmac_f32_e32 v244, 0x3fb504f3, v12
	v_fmac_f32_e32 v245, 0x3fb504f3, v252
	v_lshlrev_b32_e32 v246, 16, v29
	v_and_b32_e32 v247, 0xffff0000, v29
	v_and_b32_e32 v252, 0xffff0000, v13
	v_lshlrev_b32_e32 v13, 16, v13
	v_fmac_f32_e32 v246, 0x3fb504f3, v13
	v_fmac_f32_e32 v247, 0x3fb504f3, v252
	v_add_f32_e32 v252, v244, v245
	v_add_f32_e32 v253, v246, v247
	v_add_f32_e32 v252, v252, v253
	v_add_f32_e32 v254, v254, v252
	v_lshlrev_b32_e32 v248, 16, v30
	v_and_b32_e32 v249, 0xffff0000, v30
	v_and_b32_e32 v252, 0xffff0000, v14
	v_lshlrev_b32_e32 v14, 16, v14
	v_fmac_f32_e32 v248, 0x3fb504f3, v14
	v_fmac_f32_e32 v249, 0x3fb504f3, v252
	v_lshlrev_b32_e32 v250, 16, v31
	v_and_b32_e32 v251, 0xffff0000, v31
	v_and_b32_e32 v252, 0xffff0000, v15
	v_lshlrev_b32_e32 v15, 16, v15
	v_fmac_f32_e32 v250, 0x3fb504f3, v15
	v_fmac_f32_e32 v251, 0x3fb504f3, v252
	v_add_f32_e32 v252, v248, v249
	v_add_f32_e32 v253, v250, v251
	v_add_f32_e32 v252, v252, v253
	v_add_f32_e32 v254, v254, v252
	s_add_u32 s12, s4, 0x17fc000
	s_addc_u32 s13, s5, 0
	global_load_dwordx4 v[0:3], v90, s[12:13]
	global_load_dwordx4 v[4:7], v90, s[12:13] offset:1024
	global_load_dwordx4 v[8:11], v90, s[12:13] offset:2048
	global_load_dwordx4 v[12:15], v90, s[12:13] offset:3072
	s_add_u32 s12, s6, 0x17fc000
	s_addc_u32 s13, s7, 0
	global_load_dwordx4 v[16:19], v90, s[12:13]
	global_load_dwordx4 v[20:23], v90, s[12:13] offset:1024
	global_load_dwordx4 v[24:27], v90, s[12:13] offset:2048
	global_load_dwordx4 v[28:31], v90, s[12:13] offset:3072
	s_nop 1
	v_add_f32_dpp v252, v254, v254 quad_perm:[1,0,3,2] row_mask:0xf bank_mask:0xf
	s_nop 1
	v_add_f32_dpp v252, v252, v252 quad_perm:[2,3,0,1] row_mask:0xf bank_mask:0xf
	s_nop 1
	v_add_f32_dpp v252, v252, v252 row_half_mirror row_mask:0xf bank_mask:0xf
	s_nop 1
	v_add_f32_dpp v252, v252, v252 row_mirror row_mask:0xf bank_mask:0xf
	s_nop 1
	v_readlane_b32 s86, v252, 0
	v_readlane_b32 s87, v252, 16
	v_readlane_b32 s88, v252, 32
	v_readlane_b32 s89, v252, 48
	s_nop 1
	v_mov_b32_e32 v253, s86
	v_add_f32_e32 v253, s87, v253
	v_add_f32_e32 v253, s88, v253
	v_add_f32_e32 v253, s89, v253
	v_mul_f32_e32 v253, 0x3a000000, v253
	s_nop 0
	v_readfirstlane_b32 s85, v253
	s_nop 1
	v_subrev_f32_e32 v64, s85, v64
	v_subrev_f32_e32 v65, s85, v65
	v_subrev_f32_e32 v66, s85, v66
	v_subrev_f32_e32 v67, s85, v67
	v_subrev_f32_e32 v68, s85, v68
	v_subrev_f32_e32 v69, s85, v69
	v_subrev_f32_e32 v70, s85, v70
	v_subrev_f32_e32 v71, s85, v71
	v_mul_f32_e32 v252, v64, v64
	v_fmac_f32_e32 v252, v65, v65
	v_mul_f32_e32 v253, v66, v66
	v_fmac_f32_e32 v253, v67, v67
	v_add_f32_e32 v254, v252, v253
	v_mul_f32_e32 v252, v68, v68
	v_fmac_f32_e32 v252, v69, v69
	v_mul_f32_e32 v253, v70, v70
	v_fmac_f32_e32 v253, v71, v71
	v_add_f32_e32 v252, v252, v253
	v_add_f32_e32 v254, v254, v252
	v_subrev_f32_e32 v72, s85, v72
	v_subrev_f32_e32 v73, s85, v73
	v_subrev_f32_e32 v74, s85, v74
	v_subrev_f32_e32 v75, s85, v75
	v_subrev_f32_e32 v76, s85, v76
	v_subrev_f32_e32 v77, s85, v77
	v_subrev_f32_e32 v78, s85, v78
	v_subrev_f32_e32 v79, s85, v79
	v_mul_f32_e32 v252, v72, v72
	v_fmac_f32_e32 v252, v73, v73
	v_mul_f32_e32 v253, v74, v74
	v_fmac_f32_e32 v253, v75, v75
	v_add_f32_e32 v252, v252, v253
	v_add_f32_e32 v254, v254, v252
	v_mul_f32_e32 v252, v76, v76
	v_fmac_f32_e32 v252, v77, v77
	v_mul_f32_e32 v253, v78, v78
	v_fmac_f32_e32 v253, v79, v79
	v_add_f32_e32 v252, v252, v253
	v_add_f32_e32 v254, v254, v252
	v_subrev_f32_e32 v80, s85, v80
	v_subrev_f32_e32 v81, s85, v81
	v_subrev_f32_e32 v82, s85, v82
	v_subrev_f32_e32 v83, s85, v83
	v_subrev_f32_e32 v84, s85, v84
	v_subrev_f32_e32 v85, s85, v85
	v_subrev_f32_e32 v86, s85, v86
	v_subrev_f32_e32 v87, s85, v87
	v_mul_f32_e32 v252, v80, v80
	v_fmac_f32_e32 v252, v81, v81
	v_mul_f32_e32 v253, v82, v82
	v_fmac_f32_e32 v253, v83, v83
	v_add_f32_e32 v252, v252, v253
	v_add_f32_e32 v254, v254, v252
	v_mul_f32_e32 v252, v84, v84
	v_fmac_f32_e32 v252, v85, v85
	v_mul_f32_e32 v253, v86, v86
	v_fmac_f32_e32 v253, v87, v87
	v_add_f32_e32 v252, v252, v253
	v_add_f32_e32 v254, v254, v252
	v_subrev_f32_e32 v244, s85, v244
	v_subrev_f32_e32 v245, s85, v245
	v_subrev_f32_e32 v246, s85, v246
	v_subrev_f32_e32 v247, s85, v247
	v_subrev_f32_e32 v248, s85, v248
	v_subrev_f32_e32 v249, s85, v249
	v_subrev_f32_e32 v250, s85, v250
	v_subrev_f32_e32 v251, s85, v251
	v_mul_f32_e32 v252, v244, v244
	v_fmac_f32_e32 v252, v245, v245
	v_mul_f32_e32 v253, v246, v246
	v_fmac_f32_e32 v253, v247, v247
	v_add_f32_e32 v252, v252, v253
	v_add_f32_e32 v254, v254, v252
	v_mul_f32_e32 v252, v248, v248
	v_fmac_f32_e32 v252, v249, v249
	v_mul_f32_e32 v253, v250, v250
	v_fmac_f32_e32 v253, v251, v251
	v_add_f32_e32 v252, v252, v253
	v_add_f32_e32 v254, v254, v252
	s_nop 1
	v_add_f32_dpp v252, v254, v254 quad_perm:[1,0,3,2] row_mask:0xf bank_mask:0xf
	s_nop 1
	v_add_f32_dpp v252, v252, v252 quad_perm:[2,3,0,1] row_mask:0xf bank_mask:0xf
	s_nop 1
	v_add_f32_dpp v252, v252, v252 row_half_mirror row_mask:0xf bank_mask:0xf
	s_nop 1
	v_add_f32_dpp v252, v252, v252 row_mirror row_mask:0xf bank_mask:0xf
	s_nop 1
	v_readlane_b32 s86, v252, 0
	v_readlane_b32 s87, v252, 16
	v_readlane_b32 s88, v252, 32
	v_readlane_b32 s89, v252, 48
	s_nop 1
	v_mov_b32_e32 v253, s86
	v_add_f32_e32 v253, s87, v253
	v_add_f32_e32 v253, s88, v253
	v_add_f32_e32 v253, s89, v253
	v_mov_b32_e32 v252, 0x3a000000
	v_fmaak_f32 v253, v253, v252, 0x3727c5ac
	v_rsq_f32_e32 v253, v253
	s_nop 1
	v_readfirstlane_b32 s85, v253
	s_add_u32 s12, s4, 0x1000000
	s_addc_u32 s13, s5, 0
	v_readlane_b32 s86, v241, 7
	v_readlane_b32 s87, v241, 8
	s_add_u32 s86, s86, 0x2000000
	s_addc_u32 s87, s87, 0
	s_add_u32 s88, s86, 0x1000
	s_addc_u32 s89, s87, 0
	ds_read_b64 v[252:253], v168
	ds_read_b64 v[254:255], v168 offset:8192
	ds_read_b64 v[88:89], v168 offset:512
	ds_read_b64 v[242:243], v168 offset:8704
	s_waitcnt lgkmcnt(2)
	v_mul_f32_e32 v64, s85, v64
	v_mul_f32_e32 v65, s85, v65
	v_fma_f32 v64, v64, v252, v254
	v_fma_f32 v65, v65, v253, v255
	ds_read_b64 v[252:253], v168 offset:1024
	ds_read_b64 v[254:255], v168 offset:9216
	s_waitcnt lgkmcnt(2)
	v_mul_f32_e32 v66, s85, v66
	v_mul_f32_e32 v67, s85, v67
	v_fma_f32 v66, v66, v88, v242
	v_fma_f32 v67, v67, v89, v243
	ds_read_b64 v[88:89], v168 offset:1536
	ds_read_b64 v[242:243], v168 offset:9728
	s_waitcnt lgkmcnt(2)
	v_mul_f32_e32 v68, s85, v68
	v_mul_f32_e32 v69, s85, v69
	v_fma_f32 v68, v68, v252, v254
	v_fma_f32 v69, v69, v253, v255
	ds_read_b64 v[252:253], v168 offset:2048
	ds_read_b64 v[254:255], v168 offset:10240
	s_waitcnt lgkmcnt(2)
	v_mul_f32_e32 v70, s85, v70
	v_mul_f32_e32 v71, s85, v71
	v_fma_f32 v70, v70, v88, v242
	v_fma_f32 v71, v71, v89, v243
	s_cmp_lg_u32 s90, 0
	s_cbranch_scc1 .Lln2_f32_50
	v_cvt_pk_bf16_f32 v64, v64, v65
	v_cvt_pk_bf16_f32 v65, v66, v67
	v_cvt_pk_bf16_f32 v66, v68, v69
	v_cvt_pk_bf16_f32 v67, v70, v71
	global_store_dwordx4 v90, v[64:67], s[12:13]
	s_branch .Lln2_st_51

.Lln2_st_57:
	s_waitcnt vmcnt(16)
	v_lshlrev_b32_e32 v64, 16, v48
	v_and_b32_e32 v65, 0xffff0000, v48
	v_and_b32_e32 v252, 0xffff0000, v32
	v_lshlrev_b32_e32 v32, 16, v32
	v_fmac_f32_e32 v64, 0x3fb504f3, v32
	v_fmac_f32_e32 v65, 0x3fb504f3, v252
	v_lshlrev_b32_e32 v66, 16, v49
	v_and_b32_e32 v67, 0xffff0000, v49
	v_and_b32_e32 v252, 0xffff0000, v33
	v_lshlrev_b32_e32 v33, 16, v33
	v_fmac_f32_e32 v66, 0x3fb504f3, v33
	v_fmac_f32_e32 v67, 0x3fb504f3, v252
	v_add_f32_e32 v252, v64, v65
	v_add_f32_e32 v253, v66, v67
	v_add_f32_e32 v254, v252, v253
	v_lshlrev_b32_e32 v68, 16, v50
	v_and_b32_e32 v69, 0xffff0000, v50
	v_and_b32_e32 v252, 0xffff0000, v34
	v_lshlrev_b32_e32 v34, 16, v34
	v_fmac_f32_e32 v68, 0x3fb504f3, v34
	v_fmac_f32_e32 v69, 0x3fb504f3, v252
	v_lshlrev_b32_e32 v70, 16, v51
	v_and_b32_e32 v71, 0xffff0000, v51
	v_and_b32_e32 v252, 0xffff0000, v35
	v_lshlrev_b32_e32 v35, 16, v35
	v_fmac_f32_e32 v70, 0x3fb504f3, v35
	v_fmac_f32_e32 v71, 0x3fb504f3, v252
	v_add_f32_e32 v252, v68, v69
	v_add_f32_e32 v253, v70, v71
	v_add_f32_e32 v252, v252, v253
	v_add_f32_e32 v254, v254, v252
	v_lshlrev_b32_e32 v72, 16, v52
	v_and_b32_e32 v73, 0xffff0000, v52
	v_and_b32_e32 v252, 0xffff0000, v36
	v_lshlrev_b32_e32 v36, 16, v36
	v_fmac_f32_e32 v72, 0x3fb504f3, v36
	v_fmac_f32_e32 v73, 0x3fb504f3, v252
	v_lshlrev_b32_e32 v74, 16, v53
	v_and_b32_e32 v75, 0xffff0000, v53
	v_and_b32_e32 v252, 0xffff0000, v37
	v_lshlrev_b32_e32 v37, 16, v37
	v_fmac_f32_e32 v74, 0x3fb504f3, v37
	v_fmac_f32_e32 v75, 0x3fb504f3, v252
	v_add_f32_e32 v252, v72, v73
	v_add_f32_e32 v253, v74, v75
	v_add_f32_e32 v252, v252, v253
	v_add_f32_e32 v254, v254, v252
	v_lshlrev_b32_e32 v76, 16, v54
	v_and_b32_e32 v77, 0xffff0000, v54
	v_and_b32_e32 v252, 0xffff0000, v38
	v_lshlrev_b32_e32 v38, 16, v38
	v_fmac_f32_e32 v76, 0x3fb504f3, v38
	v_fmac_f32_e32 v77, 0x3fb504f3, v252
	v_lshlrev_b32_e32 v78, 16, v55
	v_and_b32_e32 v79, 0xffff0000, v55
	v_and_b32_e32 v252, 0xffff0000, v39
	v_lshlrev_b32_e32 v39, 16, v39
	v_fmac_f32_e32 v78, 0x3fb504f3, v39
	v_fmac_f32_e32 v79, 0x3fb504f3, v252
	v_add_f32_e32 v252, v76, v77
	v_add_f32_e32 v253, v78, v79
	v_add_f32_e32 v252, v252, v253
	v_add_f32_e32 v254, v254, v252
	v_lshlrev_b32_e32 v80, 16, v56
	v_and_b32_e32 v81, 0xffff0000, v56
	v_and_b32_e32 v252, 0xffff0000, v40
	v_lshlrev_b32_e32 v40, 16, v40
	v_fmac_f32_e32 v80, 0x3fb504f3, v40
	v_fmac_f32_e32 v81, 0x3fb504f3, v252
	v_lshlrev_b32_e32 v82, 16, v57
	v_and_b32_e32 v83, 0xffff0000, v57
	v_and_b32_e32 v252, 0xffff0000, v41
	v_lshlrev_b32_e32 v41, 16, v41
	v_fmac_f32_e32 v82, 0x3fb504f3, v41
	v_fmac_f32_e32 v83, 0x3fb504f3, v252
	v_add_f32_e32 v252, v80, v81
	v_add_f32_e32 v253, v82, v83
	v_add_f32_e32 v252, v252, v253
	v_add_f32_e32 v254, v254, v252
	v_lshlrev_b32_e32 v84, 16, v58
	v_and_b32_e32 v85, 0xffff0000, v58
	v_and_b32_e32 v252, 0xffff0000, v42
	v_lshlrev_b32_e32 v42, 16, v42
	v_fmac_f32_e32 v84, 0x3fb504f3, v42
	v_fmac_f32_e32 v85, 0x3fb504f3, v252
	v_lshlrev_b32_e32 v86, 16, v59
	v_and_b32_e32 v87, 0xffff0000, v59
	v_and_b32_e32 v252, 0xffff0000, v43
	v_lshlrev_b32_e32 v43, 16, v43
	v_fmac_f32_e32 v86, 0x3fb504f3, v43
	v_fmac_f32_e32 v87, 0x3fb504f3, v252
	v_add_f32_e32 v252, v84, v85
	v_add_f32_e32 v253, v86, v87
	v_add_f32_e32 v252, v252, v253
	v_add_f32_e32 v254, v254, v252
	v_lshlrev_b32_e32 v244, 16, v60
	v_and_b32_e32 v245, 0xffff0000, v60
	v_and_b32_e32 v252, 0xffff0000, v44
	v_lshlrev_b32_e32 v44, 16, v44
	v_fmac_f32_e32 v244, 0x3fb504f3, v44
	v_fmac_f32_e32 v245, 0x3fb504f3, v252
	v_lshlrev_b32_e32 v246, 16, v61
	v_and_b32_e32 v247, 0xffff0000, v61
	v_and_b32_e32 v252, 0xffff0000, v45
	v_lshlrev_b32_e32 v45, 16, v45
	v_fmac_f32_e32 v246, 0x3fb504f3, v45
	v_fmac_f32_e32 v247, 0x3fb504f3, v252
	v_add_f32_e32 v252, v244, v245
	v_add_f32_e32 v253, v246, v247
	v_add_f32_e32 v252, v252, v253
	v_add_f32_e32 v254, v254, v252
	v_lshlrev_b32_e32 v248, 16, v62
	v_and_b32_e32 v249, 0xffff0000, v62
	v_and_b32_e32 v252, 0xffff0000, v46
	v_lshlrev_b32_e32 v46, 16, v46
	v_fmac_f32_e32 v248, 0x3fb504f3, v46
	v_fmac_f32_e32 v249, 0x3fb504f3, v252
	v_lshlrev_b32_e32 v250, 16, v63
	v_and_b32_e32 v251, 0xffff0000, v63
	v_and_b32_e32 v252, 0xffff0000, v47
	v_lshlrev_b32_e32 v47, 16, v47
	v_fmac_f32_e32 v250, 0x3fb504f3, v47
	v_fmac_f32_e32 v251, 0x3fb504f3, v252
	v_add_f32_e32 v252, v248, v249
	v_add_f32_e32 v253, v250, v251
	v_add_f32_e32 v252, v252, v253
	v_add_f32_e32 v254, v254, v252
	s_nop 1
	v_add_f32_dpp v252, v254, v254 quad_perm:[1,0,3,2] row_mask:0xf bank_mask:0xf
	s_nop 1
	v_add_f32_dpp v252, v252, v252 quad_perm:[2,3,0,1] row_mask:0xf bank_mask:0xf
	s_nop 1
	v_add_f32_dpp v252, v252, v252 row_half_mirror row_mask:0xf bank_mask:0xf
	s_nop 1
	v_add_f32_dpp v252, v252, v252 row_mirror row_mask:0xf bank_mask:0xf
	s_nop 1
	v_readlane_b32 s86, v252, 0
	v_readlane_b32 s87, v252, 16
	v_readlane_b32 s88, v252, 32
	v_readlane_b32 s89, v252, 48
	s_nop 1
	v_mov_b32_e32 v253, s86
	v_add_f32_e32 v253, s87, v253
	v_add_f32_e32 v253, s88, v253
	v_add_f32_e32 v253, s89, v253
	v_mul_f32_e32 v253, 0x3a000000, v253
	s_nop 0
	v_readfirstlane_b32 s85, v253
	s_nop 1
	v_subrev_f32_e32 v64, s85, v64
	v_subrev_f32_e32 v65, s85, v65
	v_subrev_f32_e32 v66, s85, v66
	v_subrev_f32_e32 v67, s85, v67
	v_subrev_f32_e32 v68, s85, v68
	v_subrev_f32_e32 v69, s85, v69
	v_subrev_f32_e32 v70, s85, v70
	v_subrev_f32_e32 v71, s85, v71
	v_mul_f32_e32 v252, v64, v64
	v_fmac_f32_e32 v252, v65, v65
	v_mul_f32_e32 v253, v66, v66
	v_fmac_f32_e32 v253, v67, v67
	v_add_f32_e32 v254, v252, v253
	v_mul_f32_e32 v252, v68, v68
	v_fmac_f32_e32 v252, v69, v69
	v_mul_f32_e32 v253, v70, v70
	v_fmac_f32_e32 v253, v71, v71
	v_add_f32_e32 v252, v252, v253
	v_add_f32_e32 v254, v254, v252
	v_subrev_f32_e32 v72, s85, v72
	v_subrev_f32_e32 v73, s85, v73
	v_subrev_f32_e32 v74, s85, v74
	v_subrev_f32_e32 v75, s85, v75
	v_subrev_f32_e32 v76, s85, v76
	v_subrev_f32_e32 v77, s85, v77
	v_subrev_f32_e32 v78, s85, v78
	v_subrev_f32_e32 v79, s85, v79
	v_mul_f32_e32 v252, v72, v72
	v_fmac_f32_e32 v252, v73, v73
	v_mul_f32_e32 v253, v74, v74
	v_fmac_f32_e32 v253, v75, v75
	v_add_f32_e32 v252, v252, v253
	v_add_f32_e32 v254, v254, v252
	v_mul_f32_e32 v252, v76, v76
	v_fmac_f32_e32 v252, v77, v77
	v_mul_f32_e32 v253, v78, v78
	v_fmac_f32_e32 v253, v79, v79
	v_add_f32_e32 v252, v252, v253
	v_add_f32_e32 v254, v254, v252
	v_subrev_f32_e32 v80, s85, v80
	v_subrev_f32_e32 v81, s85, v81
	v_subrev_f32_e32 v82, s85, v82
	v_subrev_f32_e32 v83, s85, v83
	v_subrev_f32_e32 v84, s85, v84
	v_subrev_f32_e32 v85, s85, v85
	v_subrev_f32_e32 v86, s85, v86
	v_subrev_f32_e32 v87, s85, v87
	v_mul_f32_e32 v252, v80, v80
	v_fmac_f32_e32 v252, v81, v81
	v_mul_f32_e32 v253, v82, v82
	v_fmac_f32_e32 v253, v83, v83
	v_add_f32_e32 v252, v252, v253
	v_add_f32_e32 v254, v254, v252
	v_mul_f32_e32 v252, v84, v84
	v_fmac_f32_e32 v252, v85, v85
	v_mul_f32_e32 v253, v86, v86
	v_fmac_f32_e32 v253, v87, v87
	v_add_f32_e32 v252, v252, v253
	v_add_f32_e32 v254, v254, v252
	v_subrev_f32_e32 v244, s85, v244
	v_subrev_f32_e32 v245, s85, v245
	v_subrev_f32_e32 v246, s85, v246
	v_subrev_f32_e32 v247, s85, v247
	v_subrev_f32_e32 v248, s85, v248
	v_subrev_f32_e32 v249, s85, v249
	v_subrev_f32_e32 v250, s85, v250
	v_subrev_f32_e32 v251, s85, v251
	v_mul_f32_e32 v252, v244, v244
	v_fmac_f32_e32 v252, v245, v245
	v_mul_f32_e32 v253, v246, v246
	v_fmac_f32_e32 v253, v247, v247
	v_add_f32_e32 v252, v252, v253
	v_add_f32_e32 v254, v254, v252
	v_mul_f32_e32 v252, v248, v248
	v_fmac_f32_e32 v252, v249, v249
	v_mul_f32_e32 v253, v250, v250
	v_fmac_f32_e32 v253, v251, v251
	v_add_f32_e32 v252, v252, v253
	v_add_f32_e32 v254, v254, v252
	s_nop 1
	v_add_f32_dpp v252, v254, v254 quad_perm:[1,0,3,2] row_mask:0xf bank_mask:0xf
	s_nop 1
	v_add_f32_dpp v252, v252, v252 quad_perm:[2,3,0,1] row_mask:0xf bank_mask:0xf
	s_nop 1
	v_add_f32_dpp v252, v252, v252 row_half_mirror row_mask:0xf bank_mask:0xf
	s_nop 1
	v_add_f32_dpp v252, v252, v252 row_mirror row_mask:0xf bank_mask:0xf
	s_nop 1
	v_readlane_b32 s86, v252, 0
	v_readlane_b32 s87, v252, 16
	v_readlane_b32 s88, v252, 32
	v_readlane_b32 s89, v252, 48
	s_nop 1
	v_mov_b32_e32 v253, s86
	v_add_f32_e32 v253, s87, v253
	v_add_f32_e32 v253, s88, v253
	v_add_f32_e32 v253, s89, v253
	v_mov_b32_e32 v252, 0x3a000000
	v_fmaak_f32 v253, v253, v252, 0x3727c5ac
	v_rsq_f32_e32 v253, v253
	s_nop 1
	v_readfirstlane_b32 s85, v253
	s_add_u32 s12, s4, 0x1800000
	s_addc_u32 s13, s5, 0
	v_readlane_b32 s86, v241, 7
	v_readlane_b32 s87, v241, 8
	s_add_u32 s86, s86, 0x3000000
	s_addc_u32 s87, s87, 0
	s_add_u32 s88, s86, 0x1000
	s_addc_u32 s89, s87, 0
	ds_read_b64 v[252:253], v168
	ds_read_b64 v[254:255], v168 offset:8192
	ds_read_b64 v[88:89], v168 offset:512
	ds_read_b64 v[242:243], v168 offset:8704
	s_waitcnt lgkmcnt(2)
	v_mul_f32_e32 v64, s85, v64
	v_mul_f32_e32 v65, s85, v65
	v_fma_f32 v64, v64, v252, v254
	v_fma_f32 v65, v65, v253, v255
	ds_read_b64 v[252:253], v168 offset:1024
	ds_read_b64 v[254:255], v168 offset:9216
	s_waitcnt lgkmcnt(2)
	v_mul_f32_e32 v66, s85, v66
	v_mul_f32_e32 v67, s85, v67
	v_fma_f32 v66, v66, v88, v242
	v_fma_f32 v67, v67, v89, v243
	ds_read_b64 v[88:89], v168 offset:1536
	ds_read_b64 v[242:243], v168 offset:9728
	s_waitcnt lgkmcnt(2)
	v_mul_f32_e32 v68, s85, v68
	v_mul_f32_e32 v69, s85, v69
	v_fma_f32 v68, v68, v252, v254
	v_fma_f32 v69, v69, v253, v255
	ds_read_b64 v[252:253], v168 offset:2048
	ds_read_b64 v[254:255], v168 offset:10240
	s_waitcnt lgkmcnt(2)
	v_mul_f32_e32 v70, s85, v70
	v_mul_f32_e32 v71, s85, v71
	v_fma_f32 v70, v70, v88, v242
	v_fma_f32 v71, v71, v89, v243
	s_cmp_lg_u32 s90, 0
	s_cbranch_scc1 .Lln2_f32_58
	v_cvt_pk_bf16_f32 v64, v64, v65
	v_cvt_pk_bf16_f32 v65, v66, v67
	v_cvt_pk_bf16_f32 v66, v68, v69
	v_cvt_pk_bf16_f32 v67, v70, v71
	global_store_dwordx4 v90, v[64:67], s[12:13]
	s_branch .Lln2_st_59

.Lln2_st_65:
	s_waitcnt vmcnt(8)
	v_lshlrev_b32_e32 v64, 16, v16
	v_and_b32_e32 v65, 0xffff0000, v16
	v_and_b32_e32 v252, 0xffff0000, v0
	v_lshlrev_b32_e32 v0, 16, v0
	v_fmac_f32_e32 v64, 0x3fb504f3, v0
	v_fmac_f32_e32 v65, 0x3fb504f3, v252
	v_lshlrev_b32_e32 v66, 16, v17
	v_and_b32_e32 v67, 0xffff0000, v17
	v_and_b32_e32 v252, 0xffff0000, v1
	v_lshlrev_b32_e32 v1, 16, v1
	v_fmac_f32_e32 v66, 0x3fb504f3, v1
	v_fmac_f32_e32 v67, 0x3fb504f3, v252
	v_add_f32_e32 v252, v64, v65
	v_add_f32_e32 v253, v66, v67
	v_add_f32_e32 v254, v252, v253
	v_lshlrev_b32_e32 v68, 16, v18
	v_and_b32_e32 v69, 0xffff0000, v18
	v_and_b32_e32 v252, 0xffff0000, v2
	v_lshlrev_b32_e32 v2, 16, v2
	v_fmac_f32_e32 v68, 0x3fb504f3, v2
	v_fmac_f32_e32 v69, 0x3fb504f3, v252
	v_lshlrev_b32_e32 v70, 16, v19
	v_and_b32_e32 v71, 0xffff0000, v19
	v_and_b32_e32 v252, 0xffff0000, v3
	v_lshlrev_b32_e32 v3, 16, v3
	v_fmac_f32_e32 v70, 0x3fb504f3, v3
	v_fmac_f32_e32 v71, 0x3fb504f3, v252
	v_add_f32_e32 v252, v68, v69
	v_add_f32_e32 v253, v70, v71
	v_add_f32_e32 v252, v252, v253
	v_add_f32_e32 v254, v254, v252
	v_lshlrev_b32_e32 v72, 16, v20
	v_and_b32_e32 v73, 0xffff0000, v20
	v_and_b32_e32 v252, 0xffff0000, v4
	v_lshlrev_b32_e32 v4, 16, v4
	v_fmac_f32_e32 v72, 0x3fb504f3, v4
	v_fmac_f32_e32 v73, 0x3fb504f3, v252
	v_lshlrev_b32_e32 v74, 16, v21
	v_and_b32_e32 v75, 0xffff0000, v21
	v_and_b32_e32 v252, 0xffff0000, v5
	v_lshlrev_b32_e32 v5, 16, v5
	v_fmac_f32_e32 v74, 0x3fb504f3, v5
	v_fmac_f32_e32 v75, 0x3fb504f3, v252
	v_add_f32_e32 v252, v72, v73
	v_add_f32_e32 v253, v74, v75
	v_add_f32_e32 v252, v252, v253
	v_add_f32_e32 v254, v254, v252
	v_lshlrev_b32_e32 v76, 16, v22
	v_and_b32_e32 v77, 0xffff0000, v22
	v_and_b32_e32 v252, 0xffff0000, v6
	v_lshlrev_b32_e32 v6, 16, v6
	v_fmac_f32_e32 v76, 0x3fb504f3, v6
	v_fmac_f32_e32 v77, 0x3fb504f3, v252
	v_lshlrev_b32_e32 v78, 16, v23
	v_and_b32_e32 v79, 0xffff0000, v23
	v_and_b32_e32 v252, 0xffff0000, v7
	v_lshlrev_b32_e32 v7, 16, v7
	v_fmac_f32_e32 v78, 0x3fb504f3, v7
	v_fmac_f32_e32 v79, 0x3fb504f3, v252
	v_add_f32_e32 v252, v76, v77
	v_add_f32_e32 v253, v78, v79
	v_add_f32_e32 v252, v252, v253
	v_add_f32_e32 v254, v254, v252
	v_lshlrev_b32_e32 v80, 16, v24
	v_and_b32_e32 v81, 0xffff0000, v24
	v_and_b32_e32 v252, 0xffff0000, v8
	v_lshlrev_b32_e32 v8, 16, v8
	v_fmac_f32_e32 v80, 0x3fb504f3, v8
	v_fmac_f32_e32 v81, 0x3fb504f3, v252
	v_lshlrev_b32_e32 v82, 16, v25
	v_and_b32_e32 v83, 0xffff0000, v25
	v_and_b32_e32 v252, 0xffff0000, v9
	v_lshlrev_b32_e32 v9, 16, v9
	v_fmac_f32_e32 v82, 0x3fb504f3, v9
	v_fmac_f32_e32 v83, 0x3fb504f3, v252
	v_add_f32_e32 v252, v80, v81
	v_add_f32_e32 v253, v82, v83
	v_add_f32_e32 v252, v252, v253
	v_add_f32_e32 v254, v254, v252
	v_lshlrev_b32_e32 v84, 16, v26
	v_and_b32_e32 v85, 0xffff0000, v26
	v_and_b32_e32 v252, 0xffff0000, v10
	v_lshlrev_b32_e32 v10, 16, v10
	v_fmac_f32_e32 v84, 0x3fb504f3, v10
	v_fmac_f32_e32 v85, 0x3fb504f3, v252
	v_lshlrev_b32_e32 v86, 16, v27
	v_and_b32_e32 v87, 0xffff0000, v27
	v_and_b32_e32 v252, 0xffff0000, v11
	v_lshlrev_b32_e32 v11, 16, v11
	v_fmac_f32_e32 v86, 0x3fb504f3, v11
	v_fmac_f32_e32 v87, 0x3fb504f3, v252
	v_add_f32_e32 v252, v84, v85
	v_add_f32_e32 v253, v86, v87
	v_add_f32_e32 v252, v252, v253
	v_add_f32_e32 v254, v254, v252
	v_lshlrev_b32_e32 v244, 16, v28
	v_and_b32_e32 v245, 0xffff0000, v28
	v_and_b32_e32 v252, 0xffff0000, v12
	v_lshlrev_b32_e32 v12, 16, v12
	v_fmac_f32_e32 v244, 0x3fb504f3, v12
	v_fmac_f32_e32 v245, 0x3fb504f3, v252
	v_lshlrev_b32_e32 v246, 16, v29
	v_and_b32_e32 v247, 0xffff0000, v29
	v_and_b32_e32 v252, 0xffff0000, v13
	v_lshlrev_b32_e32 v13, 16, v13
	v_fmac_f32_e32 v246, 0x3fb504f3, v13
	v_fmac_f32_e32 v247, 0x3fb504f3, v252
	v_add_f32_e32 v252, v244, v245
	v_add_f32_e32 v253, v246, v247
	v_add_f32_e32 v252, v252, v253
	v_add_f32_e32 v254, v254, v252
	v_lshlrev_b32_e32 v248, 16, v30
	v_and_b32_e32 v249, 0xffff0000, v30
	v_and_b32_e32 v252, 0xffff0000, v14
	v_lshlrev_b32_e32 v14, 16, v14
	v_fmac_f32_e32 v248, 0x3fb504f3, v14
	v_fmac_f32_e32 v249, 0x3fb504f3, v252
	v_lshlrev_b32_e32 v250, 16, v31
	v_and_b32_e32 v251, 0xffff0000, v31
	v_and_b32_e32 v252, 0xffff0000, v15
	v_lshlrev_b32_e32 v15, 16, v15
	v_fmac_f32_e32 v250, 0x3fb504f3, v15
	v_fmac_f32_e32 v251, 0x3fb504f3, v252
	v_add_f32_e32 v252, v248, v249
	v_add_f32_e32 v253, v250, v251
	v_add_f32_e32 v252, v252, v253
	v_add_f32_e32 v254, v254, v252
	s_nop 1
	v_add_f32_dpp v252, v254, v254 quad_perm:[1,0,3,2] row_mask:0xf bank_mask:0xf
	s_nop 1
	v_add_f32_dpp v252, v252, v252 quad_perm:[2,3,0,1] row_mask:0xf bank_mask:0xf
	s_nop 1
	v_add_f32_dpp v252, v252, v252 row_half_mirror row_mask:0xf bank_mask:0xf
	s_nop 1
	v_add_f32_dpp v252, v252, v252 row_mirror row_mask:0xf bank_mask:0xf
	s_nop 1
	v_readlane_b32 s86, v252, 0
	v_readlane_b32 s87, v252, 16
	v_readlane_b32 s88, v252, 32
	v_readlane_b32 s89, v252, 48
	s_nop 1
	v_mov_b32_e32 v253, s86
	v_add_f32_e32 v253, s87, v253
	v_add_f32_e32 v253, s88, v253
	v_add_f32_e32 v253, s89, v253
	v_mul_f32_e32 v253, 0x3a000000, v253
	s_nop 0
	v_readfirstlane_b32 s85, v253
	s_nop 1
	v_subrev_f32_e32 v64, s85, v64
	v_subrev_f32_e32 v65, s85, v65
	v_subrev_f32_e32 v66, s85, v66
	v_subrev_f32_e32 v67, s85, v67
	v_subrev_f32_e32 v68, s85, v68
	v_subrev_f32_e32 v69, s85, v69
	v_subrev_f32_e32 v70, s85, v70
	v_subrev_f32_e32 v71, s85, v71
	v_mul_f32_e32 v252, v64, v64
	v_fmac_f32_e32 v252, v65, v65
	v_mul_f32_e32 v253, v66, v66
	v_fmac_f32_e32 v253, v67, v67
	v_add_f32_e32 v254, v252, v253
	v_mul_f32_e32 v252, v68, v68
	v_fmac_f32_e32 v252, v69, v69
	v_mul_f32_e32 v253, v70, v70
	v_fmac_f32_e32 v253, v71, v71
	v_add_f32_e32 v252, v252, v253
	v_add_f32_e32 v254, v254, v252
	v_subrev_f32_e32 v72, s85, v72
	v_subrev_f32_e32 v73, s85, v73
	v_subrev_f32_e32 v74, s85, v74
	v_subrev_f32_e32 v75, s85, v75
	v_subrev_f32_e32 v76, s85, v76
	v_subrev_f32_e32 v77, s85, v77
	v_subrev_f32_e32 v78, s85, v78
	v_subrev_f32_e32 v79, s85, v79
	v_mul_f32_e32 v252, v72, v72
	v_fmac_f32_e32 v252, v73, v73
	v_mul_f32_e32 v253, v74, v74
	v_fmac_f32_e32 v253, v75, v75
	v_add_f32_e32 v252, v252, v253
	v_add_f32_e32 v254, v254, v252
	v_mul_f32_e32 v252, v76, v76
	v_fmac_f32_e32 v252, v77, v77
	v_mul_f32_e32 v253, v78, v78
	v_fmac_f32_e32 v253, v79, v79
	v_add_f32_e32 v252, v252, v253
	v_add_f32_e32 v254, v254, v252
	v_subrev_f32_e32 v80, s85, v80
	v_subrev_f32_e32 v81, s85, v81
	v_subrev_f32_e32 v82, s85, v82
	v_subrev_f32_e32 v83, s85, v83
	v_subrev_f32_e32 v84, s85, v84
	v_subrev_f32_e32 v85, s85, v85
	v_subrev_f32_e32 v86, s85, v86
	v_subrev_f32_e32 v87, s85, v87
	v_mul_f32_e32 v252, v80, v80
	v_fmac_f32_e32 v252, v81, v81
	v_mul_f32_e32 v253, v82, v82
	v_fmac_f32_e32 v253, v83, v83
	v_add_f32_e32 v252, v252, v253
	v_add_f32_e32 v254, v254, v252
	v_mul_f32_e32 v252, v84, v84
	v_fmac_f32_e32 v252, v85, v85
	v_mul_f32_e32 v253, v86, v86
	v_fmac_f32_e32 v253, v87, v87
	v_add_f32_e32 v252, v252, v253
	v_add_f32_e32 v254, v254, v252
	v_subrev_f32_e32 v244, s85, v244
	v_subrev_f32_e32 v245, s85, v245
	v_subrev_f32_e32 v246, s85, v246
	v_subrev_f32_e32 v247, s85, v247
	v_subrev_f32_e32 v248, s85, v248
	v_subrev_f32_e32 v249, s85, v249
	v_subrev_f32_e32 v250, s85, v250
	v_subrev_f32_e32 v251, s85, v251
	v_mul_f32_e32 v252, v244, v244
	v_fmac_f32_e32 v252, v245, v245
	v_mul_f32_e32 v253, v246, v246
	v_fmac_f32_e32 v253, v247, v247
	v_add_f32_e32 v252, v252, v253
	v_add_f32_e32 v254, v254, v252
	v_mul_f32_e32 v252, v248, v248
	v_fmac_f32_e32 v252, v249, v249
	v_mul_f32_e32 v253, v250, v250
	v_fmac_f32_e32 v253, v251, v251
	v_add_f32_e32 v252, v252, v253
	v_add_f32_e32 v254, v254, v252
	s_nop 1
	v_add_f32_dpp v252, v254, v254 quad_perm:[1,0,3,2] row_mask:0xf bank_mask:0xf
	s_nop 1
	v_add_f32_dpp v252, v252, v252 quad_perm:[2,3,0,1] row_mask:0xf bank_mask:0xf
	s_nop 1
	v_add_f32_dpp v252, v252, v252 row_half_mirror row_mask:0xf bank_mask:0xf
	s_nop 1
	v_add_f32_dpp v252, v252, v252 row_mirror row_mask:0xf bank_mask:0xf
	s_nop 1
	v_readlane_b32 s86, v252, 0
	v_readlane_b32 s87, v252, 16
	v_readlane_b32 s88, v252, 32
	v_readlane_b32 s89, v252, 48
	s_nop 1
	v_mov_b32_e32 v253, s86
	v_add_f32_e32 v253, s87, v253
	v_add_f32_e32 v253, s88, v253
	v_add_f32_e32 v253, s89, v253
	v_mov_b32_e32 v252, 0x3a000000
	v_fmaak_f32 v253, v253, v252, 0x3727c5ac
	v_rsq_f32_e32 v253, v253
	s_nop 1
	v_readfirstlane_b32 s85, v253
	s_add_u32 s12, s4, 0x17fc000
	s_addc_u32 s13, s5, 0
	v_readlane_b32 s86, v241, 7
	v_readlane_b32 s87, v241, 8
	s_add_u32 s86, s86, 0x2ff8000
	s_addc_u32 s87, s87, 0
	s_add_u32 s88, s86, 0x1000
	s_addc_u32 s89, s87, 0
	ds_read_b64 v[252:253], v168
	ds_read_b64 v[254:255], v168 offset:8192
	ds_read_b64 v[88:89], v168 offset:512
	ds_read_b64 v[242:243], v168 offset:8704
	s_waitcnt lgkmcnt(2)
	v_mul_f32_e32 v64, s85, v64
	v_mul_f32_e32 v65, s85, v65
	v_fma_f32 v64, v64, v252, v254
	v_fma_f32 v65, v65, v253, v255
	ds_read_b64 v[252:253], v168 offset:1024
	ds_read_b64 v[254:255], v168 offset:9216
	s_waitcnt lgkmcnt(2)
	v_mul_f32_e32 v66, s85, v66
	v_mul_f32_e32 v67, s85, v67
	v_fma_f32 v66, v66, v88, v242
	v_fma_f32 v67, v67, v89, v243
	ds_read_b64 v[88:89], v168 offset:1536
	ds_read_b64 v[242:243], v168 offset:9728
	s_waitcnt lgkmcnt(2)
	v_mul_f32_e32 v68, s85, v68
	v_mul_f32_e32 v69, s85, v69
	v_fma_f32 v68, v68, v252, v254
	v_fma_f32 v69, v69, v253, v255
	ds_read_b64 v[252:253], v168 offset:2048
	ds_read_b64 v[254:255], v168 offset:10240
	s_waitcnt lgkmcnt(2)
	v_mul_f32_e32 v70, s85, v70
	v_mul_f32_e32 v71, s85, v71
	v_fma_f32 v70, v70, v88, v242
	v_fma_f32 v71, v71, v89, v243
	s_cmp_lg_u32 s90, 0
	s_cbranch_scc1 .Lln2_f32_66
	v_cvt_pk_bf16_f32 v64, v64, v65
	v_cvt_pk_bf16_f32 v65, v66, v67
	v_cvt_pk_bf16_f32 v66, v68, v69
	v_cvt_pk_bf16_f32 v67, v70, v71
	global_store_dwordx4 v90, v[64:67], s[12:13]
	s_branch .Lln2_st_67
